# loop-edge edit: attention-A K-tile LDS base address computed before the barrier (out of the compute-segment head); loop-invariant Q base no longer recomputed
# speedup vs baseline: 1.0046x; 1.0046x over previous
; DI float bflo(unsigned u) { return __uint_as_float(u << 16); }
; DI float bfhi(unsigned u) { return __uint_as_float(u & 0xffff0000u); }
; DI int TID() { int t = threadIdx.x; asm volatile("" : "+v"(t)); return t; }
; __device__ __forceinline__ void attn_item_A(const Params& p, int layer, int head, int q0u, char* lds) {
;   const int tid = TID(), wid = tid >> 6, lane = tid & 63, r = lane & 31, h = lane >> 5;
;   u16* Ks = (u16*)lds;
;   u16* Vt = (u16*)(lds + LDS_K);
;   char* Qs = lds + LDS_Q + wid * 8192 + lane * 16;
;   const u16* P = (const u16*)(p.ws + OFF_P);
;   const bool ctxq = q0u < NCTX;
;   const int qcol = head * 128, kcol = 512 + head * 128, vcol = 1024 + head * 128, ocol = head * 128;
;   const float CS = 0.125f * LOG2E;
;   const int lo = 0, hi = ctxq ? 0 : SEQ;
;   const int ntiles = 8 + ((hi - lo) >> 5);
;   float bA, bB;
;   {
;     const u16* qg = P + (size_t)(q0u + wid * 32 + r) * LDP + qcol + 8 * h;
;     float nA = 0.f, nB = 0.f;
; #pragma unroll
;     for (int s = 0; s < 8; ++s) {
;       const u32x4 q = *(const u32x4*)(qg + 16 * s);
;       *(u32x4*)(Qs + s * 1024) = q;
;       float ss = 0.f;
; #pragma unroll
;       for (int j = 0; j < 4; ++j) { const float a = bflo(q[j]), b = bfhi(q[j]); ss += a * a + b * b; }
;       if (s < 4) nA += ss; else nB += ss;
;     }
;     nA += __shfl_xor(nA, 32); nB += __shfl_xor(nB, 32);
;     const float* km = (const float*)(p.ws + OFF_LAM) + 8 + layer * 24 + head * 2;
;     bA = sqrtf(nA) * km[0] * CS; bB = sqrtf(nB) * km[1] * CS;
;   }
.LBB0_1570:
	v_mov_b32_e32 v34, v211
	s_lshl_b32 s0, s36, 7
	v_ashrrev_i32_e32 v2, 6, v34
	v_and_b32_e32 v12, 31, v34
	v_lshl_add_u32 v191, v2, 5, s82
	v_add_u32_e32 v0, v191, v12
	v_mov_b64_e32 v[8:9], s[12:13]
	v_mad_i64_i32 v[0:1], s[4:5], v0, s63, v[8:9]
	s_ashr_i32 s1, s0, 31
	v_lshrrev_b32_e32 v3, 2, v34
	s_lshl_b64 s[4:5], s[0:1], 1
	v_and_b32_e32 v13, 8, v3
	v_lshl_add_u64 v[0:1], v[0:1], 0, s[4:5]
	v_lshlrev_b32_e32 v164, 1, v13
	v_lshl_add_u64 v[10:11], v[0:1], 0, v[164:165]
	global_load_dwordx4 v[14:17], v[10:11], off
	global_load_dwordx4 v[18:21], v[10:11], off offset:32
	global_load_dwordx4 v[22:25], v[10:11], off offset:64
	global_load_dwordx4 v[26:29], v[10:11], off offset:96
	v_lshlrev_b32_e32 v193, 13, v2
	global_load_dwordx4 v[30:33], v[10:11], off offset:128
	global_load_dwordx4 v[0:3], v[10:11], off offset:160
	global_load_dwordx4 v[4:7], v[10:11], off offset:192
	v_and_b32_e32 v167, 63, v34
	v_lshlrev_b32_e32 v194, 4, v167
	v_or_b32_e32 v36, v193, v194
	s_lshl_b32 s6, s36, 1
	s_ashr_i32 s7, s6, 31
	s_lshl_b64 s[6:7], s[6:7], 2
	s_add_u32 s6, s19, s6
	s_addc_u32 s7, s29, s7
	v_ashrrev_i32_e32 v195, 3, v34
	v_cmp_lt_i32_e32 vcc, v186, v188
	s_cmpk_lt_u32 s82, 0x100
	v_mad_u32_u24 v196, v12, s65, v164
	s_mov_b32 s8, 0
	s_waitcnt vmcnt(6)
	ds_write_b128 v36, v[14:17] offset:37888
	v_lshlrev_b32_e32 v35, 16, v14
	v_and_b32_e32 v14, 0xffff0000, v14
	v_lshlrev_b32_e32 v37, 16, v15
	v_and_b32_e32 v15, 0xffff0000, v15
	s_waitcnt vmcnt(5)
	ds_write_b128 v36, v[18:21] offset:38912
	v_lshlrev_b32_e32 v40, 16, v18
	v_and_b32_e32 v18, 0xffff0000, v18
	v_lshlrev_b32_e32 v41, 16, v19
	v_and_b32_e32 v19, 0xffff0000, v19
	v_lshlrev_b32_e32 v38, 16, v16
	v_and_b32_e32 v16, 0xffff0000, v16
	v_lshlrev_b32_e32 v42, 16, v20
	v_and_b32_e32 v20, 0xffff0000, v20
	v_mul_f32_e32 v14, v14, v14
	v_mul_f32_e32 v15, v15, v15
	v_mul_f32_e32 v18, v18, v18
	v_mul_f32_e32 v19, v19, v19
	v_lshlrev_b32_e32 v39, 16, v17
	v_and_b32_e32 v17, 0xffff0000, v17
	v_lshlrev_b32_e32 v43, 16, v21
	v_and_b32_e32 v21, 0xffff0000, v21
	s_waitcnt vmcnt(4)
	ds_write_b128 v36, v[22:25] offset:39936
	v_lshlrev_b32_e32 v44, 16, v22
	v_and_b32_e32 v22, 0xffff0000, v22
	v_lshlrev_b32_e32 v45, 16, v23
	v_and_b32_e32 v23, 0xffff0000, v23
	v_mul_f32_e32 v16, v16, v16
	v_mul_f32_e32 v20, v20, v20
	v_fmac_f32_e32 v14, v35, v35
	v_fmac_f32_e32 v15, v37, v37
	v_fmac_f32_e32 v18, v40, v40
	v_fmac_f32_e32 v19, v41, v41
	v_lshlrev_b32_e32 v46, 16, v24
	v_and_b32_e32 v24, 0xffff0000, v24
	v_mul_f32_e32 v17, v17, v17
	v_mul_f32_e32 v21, v21, v21
	v_mul_f32_e32 v22, v22, v22
	v_mul_f32_e32 v23, v23, v23
	v_fmac_f32_e32 v16, v38, v38
	v_fmac_f32_e32 v20, v42, v42
	v_add_f32_e32 v14, v14, v15
	v_add_f32_e32 v15, v18, v19
	v_lshlrev_b32_e32 v47, 16, v25
	v_and_b32_e32 v25, 0xffff0000, v25
	v_mul_f32_e32 v24, v24, v24
	v_fmac_f32_e32 v17, v39, v39
	v_fmac_f32_e32 v21, v43, v43
	v_fmac_f32_e32 v22, v44, v44
	v_fmac_f32_e32 v23, v45, v45
	v_add_f32_e32 v14, v16, v14
	v_add_f32_e32 v15, v20, v15
	v_mul_f32_e32 v25, v25, v25
	v_fmac_f32_e32 v24, v46, v46
	v_add_f32_e32 v18, v22, v23
	v_add_f32_e32 v14, v17, v14
	v_add_f32_e32 v15, v21, v15
	s_waitcnt vmcnt(3)
	ds_write_b128 v36, v[26:29] offset:40960
	v_lshlrev_b32_e32 v48, 16, v26
	v_and_b32_e32 v26, 0xffff0000, v26
	v_fmac_f32_e32 v25, v47, v47
	v_add_f32_e32 v16, v24, v18
	v_add_f32_e32 v14, v14, v15
	v_and_b32_e32 v15, 0xffff0000, v27
	v_lshlrev_b32_e32 v49, 16, v27
	v_mul_f32_e32 v26, v26, v26
	v_add_f32_e32 v16, v25, v16
	v_mul_f32_e32 v15, v15, v15
	v_and_b32_e32 v17, 0xffff0000, v28
	v_fmac_f32_e32 v26, v48, v48
	v_add_f32_e32 v14, v14, v16
	v_fmac_f32_e32 v15, v49, v49
	v_lshlrev_b32_e32 v16, 16, v28
	v_mul_f32_e32 v17, v17, v17
	v_add_f32_e32 v15, v26, v15
	v_fmac_f32_e32 v17, v16, v16
	v_add_f32_e32 v15, v17, v15
	v_and_b32_e32 v17, 0xffff0000, v29
	v_lshlrev_b32_e32 v16, 16, v29
	v_mul_f32_e32 v17, v17, v17
	v_fmac_f32_e32 v17, v16, v16
	v_add_f32_e32 v15, v17, v15
	v_add_f32_e32 v37, v14, v15
	s_waitcnt vmcnt(2)
	v_and_b32_e32 v15, 0xffff0000, v30
	v_lshlrev_b32_e32 v14, 16, v30
	v_mul_f32_e32 v18, v15, v15
	v_fmac_f32_e32 v18, v14, v14
	global_load_dwordx4 v[14:17], v[10:11], off offset:224
	v_and_b32_e32 v20, 0xffff0000, v31
	ds_write_b128 v36, v[30:33] offset:41984
	v_lshlrev_b32_e32 v19, 16, v31
	global_load_dwordx2 v[30:31], v165, s[6:7]
	v_mul_f32_e32 v10, v20, v20
	v_fmac_f32_e32 v10, v19, v19
	v_add_f32_e32 v10, v18, v10
	v_and_b32_e32 v18, 0xffff0000, v32
	v_lshlrev_b32_e32 v11, 16, v32
	v_mul_f32_e32 v18, v18, v18
	v_fmac_f32_e32 v18, v11, v11
	v_add_f32_e32 v10, v18, v10
	v_and_b32_e32 v18, 0xffff0000, v33
	v_lshlrev_b32_e32 v11, 16, v33
	v_mul_f32_e32 v18, v18, v18
	v_fmac_f32_e32 v18, v11, v11
	v_add_f32_e32 v10, v18, v10
	s_waitcnt vmcnt(3)
	v_and_b32_e32 v18, 0xffff0000, v0
	v_lshlrev_b32_e32 v11, 16, v0
	v_mul_f32_e32 v18, v18, v18
	v_and_b32_e32 v19, 0xffff0000, v1
	v_fmac_f32_e32 v18, v11, v11
	v_lshlrev_b32_e32 v11, 16, v1
	v_mul_f32_e32 v19, v19, v19
	v_fmac_f32_e32 v19, v11, v11
	v_add_f32_e32 v11, v18, v19
	v_and_b32_e32 v19, 0xffff0000, v2
	v_lshlrev_b32_e32 v18, 16, v2
	v_mul_f32_e32 v19, v19, v19
	v_fmac_f32_e32 v19, v18, v18
	v_add_f32_e32 v11, v19, v11
	v_and_b32_e32 v19, 0xffff0000, v3
	v_lshlrev_b32_e32 v18, 16, v3
	v_mul_f32_e32 v19, v19, v19
	v_fmac_f32_e32 v19, v18, v18
	v_add_f32_e32 v11, v19, v11
	v_add_f32_e32 v38, v10, v11
	s_waitcnt vmcnt(2)
; __device__ __forceinline__ void attn_item_A(const Params& p, int layer, int head, int q0u, char* lds) {
;     ...
;     nA += __shfl_xor(nA, 32); nB += __shfl_xor(nB, 32);
;     const float* km = (const float*)(p.ws + OFF_LAM) + 8 + layer * 24 + head * 2;
;     bA = sqrtf(nA) * km[0] * CS; bB = sqrtf(nB) * km[1] * CS;
;   }
;   const int srow = tid >> 3, sseg = (tid & 7) * 16;
;   const u16* VTg = (const u16*)(p.ws + OFF_VT) + (size_t)(head * 128 + (tid >> 1)) * LDVT + (tid & 1) * 16;
;   float lA = 0.f, lB = 0.f;
;   f32x16 o1[4], o2[4];
; #pragma unroll
;   for (int d = 0; d < 4; ++d)
; #pragma unroll
;     for (int e = 0; e < 16; ++e) { o1[d][e] = 0.f; o2[d][e] = 0.f; }
;   u32x4 rk0, rk1, rv0, rv1;
;   const u16* gnext;
;   ATT_LOADK(0); ATT_LOADV(0);
;   ATT_STOREK(0); ATT_STOREV(0);
;   __syncthreads();
	v_and_b32_e32 v11, 0xffff0000, v4
	v_lshlrev_b32_e32 v10, 16, v4
	v_mul_f32_e32 v11, v11, v11
	v_and_b32_e32 v18, 0xffff0000, v5
	v_fmac_f32_e32 v11, v10, v10
	v_lshlrev_b32_e32 v10, 16, v5
	v_mul_f32_e32 v18, v18, v18
	v_fmac_f32_e32 v18, v10, v10
	v_add_f32_e32 v10, v11, v18
	v_and_b32_e32 v18, 0xffff0000, v6
	v_lshlrev_b32_e32 v11, 16, v6
	v_mul_f32_e32 v18, v18, v18
	v_fmac_f32_e32 v18, v11, v11
	v_ashrrev_i32_e32 v42, 1, v34
	v_lshlrev_b32_e32 v24, 5, v34
	v_add_f32_e32 v39, v18, v10
	v_add_u32_e32 v18, s0, v42
	v_mov_b64_e32 v[10:11], s[14:15]
	v_mad_i64_i32 v[8:9], s[0:1], v195, s63, v[8:9]
	v_and_b32_e32 v32, 0xe0, v24
	v_mov_b32_e32 v33, v165
	v_mad_i64_i32 v[22:23], s[0:1], v18, s64, v[10:11]
	v_lshl_add_u64 v[8:9], v[8:9], 0, v[32:33]
	v_and_b32_e32 v34, 32, v24
	v_mov_b32_e32 v35, v165
	v_lshl_add_u64 v[18:19], v[8:9], 0, s[4:5]
	v_lshl_add_u64 v[170:171], v[22:23], 0, v[34:35]
	global_load_dwordx4 v[8:11], v[18:19], off offset:1040
	s_nop 0
	global_load_dwordx4 v[18:21], v[18:19], off offset:1024
	s_nop 0
	global_load_dwordx4 v[22:25], v[170:171], off offset:16
	global_load_dwordx4 v[26:29], v[170:171], off
	v_and_b32_e32 v41, 0xffff0000, v7
	v_lshlrev_b32_e32 v40, 16, v7
	v_mul_f32_e32 v35, v41, v41
	v_fmac_f32_e32 v35, v40, v40
	v_add_f32_e32 v35, v35, v39
	v_add_f32_e32 v35, v38, v35
	ds_write_b128 v36, v[0:3] offset:43008
	ds_write_b128 v36, v[4:7] offset:44032
	s_waitcnt vmcnt(5)
	ds_write_b128 v36, v[14:17] offset:45056
	s_mov_b32 s6, 32
	v_and_b32_e32 v39, 0xffff0000, v14
	v_lshlrev_b32_e32 v38, 16, v14
	v_mul_f32_e32 v39, v39, v39
	v_and_b32_e32 v40, 0xffff0000, v15
	v_fmac_f32_e32 v39, v38, v38
	v_lshlrev_b32_e32 v38, 16, v15
	v_mul_f32_e32 v40, v40, v40
	v_fmac_f32_e32 v40, v38, v38
	v_add_f32_e32 v38, v39, v40
	v_and_b32_e32 v40, 0xffff0000, v16
	v_lshlrev_b32_e32 v39, 16, v16
	v_mul_f32_e32 v40, v40, v40
	v_fmac_f32_e32 v40, v39, v39
	v_add_f32_e32 v38, v40, v38
	v_and_b32_e32 v40, 0xffff0000, v17
	v_lshlrev_b32_e32 v39, 16, v17
	v_mul_f32_e32 v40, v40, v40
	v_fmac_f32_e32 v40, v39, v39
	v_add_f32_e32 v38, v40, v38
	v_add_f32_e32 v35, v35, v38
	v_cndmask_b32_e32 v38, v214, v186, vcc
	v_lshlrev_b32_e32 v192, 2, v38
	ds_bpermute_b32 v38, v192, v35
	ds_bpermute_b32 v3, v192, v37
	s_waitcnt lgkmcnt(1)
	v_add_f32_e32 v0, v35, v38
	v_mul_f32_e32 v1, 0x4f800000, v0
	v_cmp_gt_f32_e32 vcc, s70, v0
	s_waitcnt lgkmcnt(0)
	v_add_f32_e32 v3, v37, v3
	v_cndmask_b32_e32 v1, v0, v1, vcc
	v_sqrt_f32_e32 v2, v1
	v_mov_b32_e32 v0, 0
	v_mov_b32_e32 v6, v0
	v_mov_b32_e32 v7, v0
	v_add_u32_e32 v4, -1, v2
	v_fma_f32 v5, -v4, v2, v1
	v_cmp_ge_f32_e64 s[0:1], 0, v5
	v_add_u32_e32 v5, 1, v2
	v_mov_b32_e32 v14, v0
	v_cndmask_b32_e64 v4, v2, v4, s[0:1]
	v_fma_f32 v2, -v5, v2, v1
	v_cmp_lt_f32_e64 s[0:1], 0, v2
	v_mov_b32_e32 v15, v0
	v_mov_b32_e32 v16, v0
	v_cndmask_b32_e64 v2, v4, v5, s[0:1]
	v_mul_f32_e32 v4, 0x37800000, v2
	v_cndmask_b32_e32 v2, v2, v4, vcc
	v_mul_f32_e32 v4, 0x4f800000, v3
	v_cmp_gt_f32_e32 vcc, s70, v3
	v_cmp_class_f32_e64 s[0:1], v1, v183
	v_mov_b32_e32 v17, v0
	v_cndmask_b32_e32 v3, v3, v4, vcc
	v_sqrt_f32_e32 v4, v3
	v_cndmask_b32_e64 v1, v2, v1, s[0:1]
	s_waitcnt vmcnt(4)
	v_mul_f32_e32 v1, v31, v1
	v_mul_f32_e32 v164, 0xbe38aa3b, v1
	v_add_u32_e32 v2, -1, v4
	v_fma_f32 v5, -v2, v4, v3
	v_cmp_ge_f32_e64 s[0:1], 0, v5
	v_add_u32_e32 v5, 1, v4
	v_mul_i32_i24_e32 v1, 0xffffff38, v12
	v_cndmask_b32_e64 v2, v4, v2, s[0:1]
	v_fma_f32 v4, -v5, v4, v3
	v_cmp_lt_f32_e64 s[0:1], 0, v4
	v_mov_b32_e32 v31, v0
	v_mov_b32_e32 v36, v0
	v_cndmask_b32_e64 v2, v2, v5, s[0:1]
	v_mul_f32_e32 v4, 0x37800000, v2
	v_cndmask_b32_e32 v2, v2, v4, vcc
	v_cmp_class_f32_e32 vcc, v3, v183
	v_mad_u64_u32 v[174:175], s[0:1], v42, s66, v[34:35]
	s_nop 0
	v_cndmask_b32_e32 v2, v2, v3, vcc
	v_mul_f32_e32 v4, v30, v2
	v_mad_u64_u32 v[172:173], s[0:1], v195, s65, v[32:33]
	v_add_u32_e32 v2, 0x4400, v174
	s_waitcnt vmcnt(2)
	ds_write_b128 v172, v[18:21]
	ds_write_b128 v172, v[8:11] offset:16
	s_waitcnt vmcnt(0)
	ds_write2_b64 v2, v[26:27], v[28:29] offset1:1
	v_add_u32_e32 v2, 0x4410, v174
	ds_write2_b64 v2, v[22:23], v[24:25] offset1:1
	v_lshl_add_u64 v[2:3], s[12:13], 0, v[32:33]
	v_lshl_add_u64 v[176:177], v[2:3], 0, s[4:5]
	v_mul_u32_u24_e32 v2, 0x110, v12
	v_mul_f32_e32 v173, 0xbe38aa3b, v4
	v_add3_u32 v175, v2, v1, v13
	s_cselect_b32 s0, 7, 0x207
	v_mov_b32_e32 v1, v0
	v_mov_b32_e32 v2, v0
	v_mov_b32_e32 v3, v0
	v_mov_b32_e32 v4, v0
	v_mov_b32_e32 v5, v0
	v_mov_b32_e32 v8, v0
	v_mov_b32_e32 v9, v0
	v_mov_b32_e32 v10, v0
	v_mov_b32_e32 v11, v0
	v_mov_b32_e32 v12, v0
	v_mov_b32_e32 v13, v0
	v_mov_b32_e32 v18, v0
	v_mov_b32_e32 v19, v0
	v_mov_b32_e32 v20, v0
	v_mov_b32_e32 v21, v0
	v_mov_b32_e32 v22, v0
	v_mov_b32_e32 v23, v0
	v_mov_b32_e32 v24, v0
	v_mov_b32_e32 v25, v0
	v_mov_b32_e32 v26, v0
	v_mov_b32_e32 v27, v0
	v_mov_b32_e32 v28, v0
	v_mov_b32_e32 v29, v0
	v_mov_b32_e32 v30, v0
	v_mov_b32_e32 v32, v0
	v_mov_b32_e32 v33, v0
	v_mov_b32_e32 v34, v0
	v_mov_b32_e32 v35, v0
	v_mov_b32_e32 v37, v0
	v_mov_b32_e32 v38, v0
	v_mov_b32_e32 v39, v0
	v_mov_b32_e32 v40, v0
	v_mov_b32_e32 v41, v0
	v_mov_b32_e32 v42, v0
	v_mov_b32_e32 v43, v0
	v_mov_b32_e32 v44, v0
	v_mov_b32_e32 v45, v0
	v_mov_b32_e32 v46, v0
	v_mov_b32_e32 v47, v0
	v_mov_b32_e32 v48, v0
	v_mov_b32_e32 v49, v0
	v_mov_b32_e32 v50, v0
	v_mov_b32_e32 v51, v0
	v_mov_b32_e32 v52, v0
	v_mov_b32_e32 v53, v0
	v_mov_b32_e32 v54, v0
	v_mov_b32_e32 v55, v0
	v_mov_b32_e32 v56, v0
	v_mov_b32_e32 v57, v0
	v_mov_b32_e32 v58, v0
	v_mov_b32_e32 v59, v0
	v_mov_b32_e32 v60, v0
	v_mov_b32_e32 v61, v0
	v_mov_b32_e32 v62, v0
	v_mov_b32_e32 v63, v0
	v_mov_b32_e32 v64, v0
	v_mov_b32_e32 v65, v0
	v_mov_b32_e32 v66, v0
; #define MFMA32(a, b, c) __builtin_amdgcn_mfma_f32_32x32x16_bf16((a), (b), (c), 0, 0, 0)
; __device__ __forceinline__ void attn_item_A(const Params& p, int layer, int head, int q0u, char* lds) {
;     ...
;   f32x16 o1[4], o2[4];
; #pragma unroll
;   for (int d = 0; d < 4; ++d)
; #pragma unroll
;     for (int e = 0; e < 16; ++e) { o1[d][e] = 0.f; o2[d][e] = 0.f; }
;   u32x4 rk0, rk1, rv0, rv1;
;   const u16* gnext;
;   ATT_LOADK(0); ATT_LOADV(0);
;   ATT_STOREK(0); ATT_STOREV(0);
;   __syncthreads();
;   for (int t = 0; t < ntiles; ++t) {
;     const int buf = t & 1;
;     const bool more = (t + 1 < ntiles);
;     if (more) { ATT_LOADK(t + 1); ATT_LOADV(t + 1); }
;     const u16* kt_ = Ks + buf * 32 * KLD + r * KLD + 8 * h;
;     bf16x8 a0, a1, b0, b1;
;     {
;       f32x16 sx, sy;
; #pragma unroll
;       for (int e = 0; e < 16; ++e) { sx[e] = 0.f; sy[e] = 0.f; }
; #pragma unroll
;       for (int s = 0; s < 4; ++s) {
;         const bf16x8 kf = *(const bf16x8*)(kt_ + 16 * s);
;         const bf16x8 qf = *(const bf16x8*)(Qs + s * 1024);
;         sx = MFMA32(kf, qf, sx);
;       }
; #pragma unroll
;       for (int s = 4; s < 8; ++s) {
;         const bf16x8 kf = *(const bf16x8*)(kt_ + 16 * s);
;         const bf16x8 qf = *(const bf16x8*)(Qs + s * 1024);
;         sy = MFMA32(kf, qf, sy);
;       }
	v_mov_b32_e32 v67, v0
	v_mov_b32_e32 v68, v0
	v_mov_b32_e32 v69, v0
	v_mov_b32_e32 v70, v0
	v_mov_b32_e32 v71, v0
	v_mov_b32_e32 v72, v0
	v_mov_b32_e32 v73, v0
	v_mov_b32_e32 v74, v0
	v_mov_b32_e32 v75, v0
	v_mov_b32_e32 v76, v0
	v_mov_b32_e32 v77, v0
	v_mov_b32_e32 v78, v0
	v_mov_b32_e32 v79, v0
	v_mov_b32_e32 v80, v0
	v_mov_b32_e32 v81, v0
	v_mov_b32_e32 v82, v0
	v_mov_b32_e32 v83, v0
	v_mov_b32_e32 v84, v0
	v_mov_b32_e32 v85, v0
	v_mov_b32_e32 v86, v0
	v_mov_b32_e32 v87, v0
	v_mov_b32_e32 v88, v0
	v_mov_b32_e32 v89, v0
	v_mov_b32_e32 v90, v0
	v_mov_b32_e32 v91, v0
	v_mov_b32_e32 v92, v0
	v_mov_b32_e32 v93, v0
	v_mov_b32_e32 v94, v0
	v_mov_b32_e32 v95, v0
	v_mov_b32_e32 v96, v0
	v_mov_b32_e32 v97, v0
	v_mov_b32_e32 v98, v0
	v_mov_b32_e32 v99, v0
	v_mov_b32_e32 v100, v0
	v_mov_b32_e32 v101, v0
	v_mov_b32_e32 v102, v0
	v_mov_b32_e32 v103, v0
	v_mov_b32_e32 v104, v0
	v_mov_b32_e32 v105, v0
	v_mov_b32_e32 v106, v0
	v_mov_b32_e32 v107, v0
	v_mov_b32_e32 v108, v0
	v_mov_b32_e32 v109, v0
	v_mov_b32_e32 v110, v0
	v_mov_b32_e32 v111, v0
	v_mov_b32_e32 v112, v0
	v_mov_b32_e32 v113, v0
	v_mov_b32_e32 v114, v0
	v_mov_b32_e32 v115, v0
	v_mov_b32_e32 v116, v0
	v_mov_b32_e32 v117, v0
	v_mov_b32_e32 v118, v0
	v_mov_b32_e32 v119, v0
	v_mov_b32_e32 v120, v0
	v_mov_b32_e32 v121, v0
	v_mov_b32_e32 v122, v0
	v_mov_b32_e32 v123, v0
	v_mov_b32_e32 v124, v0
	v_mov_b32_e32 v125, v0
	v_mov_b32_e32 v126, v0
	v_mov_b32_e32 v127, v0
	v_mov_b32_e32 v168, v0
	v_mov_b32_e32 v169, v0
	v_add_u32_e32 v197, v193, v194
	ds_read_b128 v[240:243], v197 offset:39936
	ds_read_b128 v[244:247], v197 offset:40960
	ds_read_b128 v[248:251], v197 offset:44032
	ds_read_b128 v[252:255], v197 offset:45056
	s_and_b32 s1, s8, 1
	s_mul_i32 s7, s1, 0x2200
	v_add_u32_e32 v210, s7, v196
	s_waitcnt lgkmcnt(0)
	s_barrier
.LBB0_1571:
	s_setprio 1
	s_and_b32 s1, s8, 1
	s_mul_i32 s7, s1, 0x2200
	ds_read_b128 v[128:131], v197 offset:37888
	ds_read_b128 v[160:163], v197 offset:38912
	ds_read_b128 v[144:147], v197 offset:41984
	ds_read_b128 v[178:181], v197 offset:43008
	ds_read_b128 v[132:135], v210
	ds_read_b128 v[198:201], v210 offset:32
	ds_read_b128 v[148:151], v210 offset:128
	ds_read_b128 v[202:205], v210 offset:160
	ds_read_b128 v[206:209], v210 offset:64
	ds_read_b128 v[216:219], v210 offset:96
	ds_read_b128 v[220:223], v210 offset:192
	ds_read_b128 v[224:227], v210 offset:224
	s_waitcnt lgkmcnt(7)
	v_mfma_f32_32x32x16_bf16 v[128:143], v[132:135], v[128:131], 0
	s_ashr_i32 s7, s6, 31
	s_add_i32 s8, s8, 1
	s_waitcnt lgkmcnt(5)
	v_mfma_f32_32x32x16_bf16 v[144:159], v[148:151], v[144:147], 0
	v_mfma_f32_32x32x16_bf16 v[128:143], v[198:201], v[160:163], v[128:143]
	s_waitcnt lgkmcnt(4)
	v_mfma_f32_32x32x16_bf16 v[144:159], v[202:205], v[178:181], v[144:159]
	s_waitcnt lgkmcnt(3)
	v_mfma_f32_32x32x16_bf16 v[128:143], v[206:209], v[240:243], v[128:143]
	v_lshl_add_u64 v[178:179], s[6:7], 1, v[170:171]
	s_mul_i32 s7, s1, 0x2400
	v_add_u32_e32 v210, s7, v175
	v_add_u32_e32 v212, 0x4000, v210
	v_add_u32_e32 v215, 0x4800, v210
	v_add_u32_e32 v238, 0x5000, v210
	s_waitcnt lgkmcnt(1)
	v_mfma_f32_32x32x16_bf16 v[144:159], v[220:223], v[248:251], v[144:159]
	v_add_u32_e32 v160, s6, v195
	v_mad_i64_i32 v[180:181], s[10:11], v160, s63, v[176:177]
	global_load_dwordx4 v[160:163], v[180:181], off offset:1040
	v_add_u32_e32 v210, 0x5800, v210
	s_xor_b32 s1, s1, 1
	s_add_i32 s6, s6, 32
	v_mfma_f32_32x32x16_bf16 v[128:143], v[216:219], v[244:247], v[128:143]
	ds_read2_b64 v[198:201], v212 offset0:128 offset1:130
	s_mul_i32 s7, s1, 0x2200
	s_mulk_i32 s1, 0x2400
	s_cmp_eq_u32 s0, s8
	s_waitcnt lgkmcnt(1)
	v_mfma_f32_32x32x16_bf16 v[144:159], v[224:227], v[252:255], v[144:159]
	s_setprio 0
	s_nop 5
	v_fmamk_f32 v128, v128, 0x3e38aa3b, v173
	v_fmamk_f32 v129, v129, 0x3e38aa3b, v173
	v_fmamk_f32 v130, v130, 0x3e38aa3b, v173
	v_fmamk_f32 v131, v131, 0x3e38aa3b, v173
	v_fmamk_f32 v132, v132, 0x3e38aa3b, v173
	v_fmamk_f32 v133, v133, 0x3e38aa3b, v173
	v_fmamk_f32 v202, v134, 0x3e38aa3b, v173
	v_fmamk_f32 v135, v135, 0x3e38aa3b, v173
	v_fmamk_f32 v203, v144, 0x3e38aa3b, v164
	v_fmamk_f32 v145, v145, 0x3e38aa3b, v164
	v_fmamk_f32 v204, v146, 0x3e38aa3b, v164
	v_fmamk_f32 v205, v147, 0x3e38aa3b, v164
	v_fmamk_f32 v206, v148, 0x3e38aa3b, v164
	v_fmamk_f32 v207, v149, 0x3e38aa3b, v164
	v_fmamk_f32 v208, v150, 0x3e38aa3b, v164
	v_fmamk_f32 v209, v151, 0x3e38aa3b, v164
	v_exp_f32_e32 v150, v128
	v_exp_f32_e32 v148, v129
	v_exp_f32_e32 v146, v130
	v_exp_f32_e32 v144, v131
	v_exp_f32_e32 v134, v132
	v_exp_f32_e32 v130, v133
	v_exp_f32_e32 v132, v202
	v_exp_f32_e32 v128, v135
	v_exp_f32_e32 v151, v203
	v_exp_f32_e32 v149, v145
	v_exp_f32_e32 v147, v204
	v_exp_f32_e32 v145, v205
	v_exp_f32_e32 v135, v206
	v_exp_f32_e32 v131, v207
	v_exp_f32_e32 v133, v208
	v_exp_f32_e32 v129, v209
	v_cvt_pk_bf16_f32 v202, v150, v148
	v_cvt_pk_bf16_f32 v203, v146, v144
	v_cvt_pk_bf16_f32 v204, v134, v130
	v_cvt_pk_bf16_f32 v205, v132, v128
	v_cvt_pk_bf16_f32 v206, v151, v149
	v_cvt_pk_bf16_f32 v207, v147, v145
	v_cvt_pk_bf16_f32 v208, v135, v131
	v_cvt_pk_bf16_f32 v209, v133, v129
	s_setprio 1
	s_waitcnt lgkmcnt(0)
	v_mfma_f32_32x32x16_bf16 v[64:79], v[202:205], v[198:201], v[64:79]
	v_fmamk_f32 v152, v152, 0x3e38aa3b, v164
	v_fmamk_f32 v153, v153, 0x3e38aa3b, v164
	v_fmamk_f32 v154, v154, 0x3e38aa3b, v164
	v_fmamk_f32 v155, v155, 0x3e38aa3b, v164
	v_fmamk_f32 v156, v156, 0x3e38aa3b, v164
	v_fmamk_f32 v157, v157, 0x3e38aa3b, v164
	v_fmamk_f32 v158, v158, 0x3e38aa3b, v164
	v_mfma_f32_32x32x16_bf16 v[48:63], v[206:209], v[198:201], v[48:63]
	ds_read2_b64 v[198:201], v215 offset0:160 offset1:162
	ds_read2_b64 v[216:219], v212 offset0:132 offset1:134
	ds_read2_b64 v[220:223], v238 offset0:192 offset1:194
	ds_read2_b64 v[224:227], v210 offset0:224 offset1:226
	v_fmamk_f32 v159, v159, 0x3e38aa3b, v164
	v_exp_f32_e32 v213, v152
	v_exp_f32_e32 v229, v153
	v_exp_f32_e32 v231, v154
	v_exp_f32_e32 v233, v157
	s_waitcnt lgkmcnt(1)
; __device__ __forceinline__ void attn_item_A(const Params& p, int layer, int head, int q0u, char* lds) {
;     ...
;         float w[16];
; #pragma unroll
;         for (int e = 0; e < 16; ++e) { w[e] = __builtin_amdgcn_exp2f(fmaf(sx[e], CS, -bA)); lA += w[e]; }
;         const u32x4 p0 = {pk2(w[0], w[1]), pk2(w[2], w[3]), pk2(w[4], w[5]), pk2(w[6], w[7])};
;         const u32x4 p1 = {pk2(w[8], w[9]), pk2(w[10], w[11]), pk2(w[12], w[13]), pk2(w[14], w[15])};
;         a0 = __builtin_bit_cast(bf16x8, p0); a1 = __builtin_bit_cast(bf16x8, p1);
;       }
;       {
;         float w[16];
; #pragma unroll
;         for (int e = 0; e < 16; ++e) { w[e] = __builtin_amdgcn_exp2f(fmaf(sy[e], CS, -bB)); lB += w[e]; }
;         const u32x4 p0 = {pk2(w[0], w[1]), pk2(w[2], w[3]), pk2(w[4], w[5]), pk2(w[6], w[7])};
;         const u32x4 p1 = {pk2(w[8], w[9]), pk2(w[10], w[11]), pk2(w[12], w[13]), pk2(w[14], w[15])};
;         b0 = __builtin_bit_cast(bf16x8, p0); b1 = __builtin_bit_cast(bf16x8, p1);
;       }
;     }
;     const u16* vt = Vt + buf * 128 * VLD + r * VLD + 4 * h;
; #pragma unroll
;     for (int d = 0; d < 4; d += 2) {
;       const s16x4 l0 = *(const s16x4*)(vt + d * 32 * VLD), h0 = *(const s16x4*)(vt + d * 32 * VLD + 8);
;       const s16x4 l1 = *(const s16x4*)(vt + d * 32 * VLD + 16), h1 = *(const s16x4*)(vt + d * 32 * VLD + 24);
;       const s16x4 m0 = *(const s16x4*)(vt + (d + 1) * 32 * VLD), n0 = *(const s16x4*)(vt + (d + 1) * 32 * VLD + 8);
;       const s16x4 m1 = *(const s16x4*)(vt + (d + 1) * 32 * VLD + 16), n1 = *(const s16x4*)(vt + (d + 1) * 32 * VLD + 24);
;       const bf16x8 v0 = {l0[0], l0[1], l0[2], l0[3], h0[0], h0[1], h0[2], h0[3]};
;       const bf16x8 v1 = {l1[0], l1[1], l1[2], l1[3], h1[0], h1[1], h1[2], h1[3]};
;       const bf16x8 u0 = {m0[0], m0[1], m0[2], m0[3], n0[0], n0[1], n0[2], n0[3]};
;       const bf16x8 u1 = {m1[0], m1[1], m1[2], m1[3], n1[0], n1[1], n1[2], n1[3]};
;       o1[d] = MFMA32(a0, v0, o1[d]);
;       o2[d] = MFMA32(b0, v0, o2[d]);
;       o1[d + 1] = MFMA32(a0, u0, o1[d + 1]);
;       o2[d + 1] = MFMA32(b0, u0, o2[d + 1]);
;       o1[d] = MFMA32(a1, v1, o1[d]);
;       o2[d] = MFMA32(b1, v1, o2[d]);
;       o1[d + 1] = MFMA32(a1, u1, o1[d + 1]);
;       o2[d + 1] = MFMA32(b1, u1, o2[d + 1]);
;     }
;     if (more) { ATT_STOREK(buf ^ 1); ATT_STOREV(buf ^ 1); }
;     __syncthreads();
	v_mfma_f32_32x32x16_bf16 v[96:111], v[202:205], v[220:223], v[96:111]
	v_exp_f32_e32 v235, v158
	v_exp_f32_e32 v237, v159
	v_fmamk_f32 v136, v136, 0x3e38aa3b, v173
	v_fmamk_f32 v137, v137, 0x3e38aa3b, v173
	v_fmamk_f32 v138, v138, 0x3e38aa3b, v173
	v_fmamk_f32 v139, v139, 0x3e38aa3b, v173
	v_fmamk_f32 v140, v140, 0x3e38aa3b, v173
	v_mfma_f32_32x32x16_bf16 v[16:31], v[206:209], v[220:223], v[16:31]
	v_exp_f32_e32 v221, v155
	v_exp_f32_e32 v223, v156
	global_load_dwordx4 v[152:155], v[180:181], off offset:1024
	global_load_dwordx4 v[156:159], v[178:179], off
	v_fmamk_f32 v141, v141, 0x3e38aa3b, v173
	global_load_dwordx4 v[178:181], v[178:179], off offset:16
	v_fmamk_f32 v142, v142, 0x3e38aa3b, v173
	v_fmamk_f32 v143, v143, 0x3e38aa3b, v173
	v_exp_f32_e32 v212, v136
	v_exp_f32_e32 v228, v137
	v_exp_f32_e32 v230, v138
	v_exp_f32_e32 v220, v139
	v_exp_f32_e32 v222, v140
	v_exp_f32_e32 v232, v141
	v_exp_f32_e32 v234, v142
	v_exp_f32_e32 v236, v143
	v_mfma_f32_32x32x16_bf16 v[80:95], v[202:205], v[198:201], v[80:95]
	v_cvt_pk_bf16_f32 v136, v212, v228
	v_cvt_pk_bf16_f32 v137, v230, v220
	v_cvt_pk_bf16_f32 v138, v222, v232
	v_cvt_pk_bf16_f32 v139, v234, v236
	v_cvt_pk_bf16_f32 v140, v213, v229
	v_cvt_pk_bf16_f32 v141, v231, v221
	v_cvt_pk_bf16_f32 v142, v223, v233
	v_mfma_f32_32x32x16_bf16 v[32:47], v[206:209], v[198:201], v[32:47]
	v_cvt_pk_bf16_f32 v143, v235, v237
	ds_read2_b64 v[198:201], v215 offset0:164 offset1:166
	v_add_f32_e64 v150, v168, v150
	v_add_f32_e64 v151, v169, v151
	v_add_f32_e64 v148, v148, v150
	v_add_f32_e64 v149, v149, v151
	v_pk_add_f32 v[146:147], v[146:147], v[148:149]
	s_waitcnt lgkmcnt(1)
	v_mfma_f32_32x32x16_bf16 v[112:127], v[202:205], v[224:227], v[112:127]
	ds_read2_b64 v[202:205], v210 offset0:228 offset1:230
	v_add_f32_e64 v144, v144, v146
	v_add_f32_e64 v145, v145, v147
	v_add_f32_e64 v134, v134, v144
	v_add_f32_e64 v135, v135, v145
	v_pk_add_f32 v[130:131], v[130:131], v[134:135]
	v_mfma_f32_32x32x16_bf16 v[0:15], v[206:209], v[224:227], v[0:15]
	v_add_f32_e64 v130, v132, v130
	v_add_f32_e64 v131, v133, v131
	v_add_u32_e32 v206, s7, v172
	v_add_f32_e64 v128, v128, v130
	v_add_f32_e64 v129, v129, v131
	v_add_u32_e32 v207, s1, v174
	v_pk_add_f32 v[128:129], v[212:213], v[128:129]
	v_add_u32_e32 v208, 0x4400, v207
	v_pk_add_f32 v[128:129], v[228:229], v[128:129]
	s_waitcnt lgkmcnt(1)
	v_mfma_f32_32x32x16_bf16 v[80:95], v[136:139], v[198:201], v[80:95]
	v_add_f32_e64 v128, v230, v128
	v_add_f32_e64 v129, v231, v129
	v_add_u32_e32 v207, 0x4410, v207
	v_add_f32_e64 v128, v220, v128
	v_add_f32_e64 v129, v221, v129
	v_pk_add_f32 v[128:129], v[222:223], v[128:129]
	s_nop 0
	v_pk_add_f32 v[128:129], v[232:233], v[128:129]
	v_mfma_f32_32x32x16_bf16 v[32:47], v[140:143], v[198:201], v[32:47]
	ds_read2_b64 v[198:201], v238 offset0:196 offset1:198
	v_add_f32_e64 v128, v234, v128
	v_add_f32_e64 v129, v235, v129
	s_setprio 0
	s_waitcnt vmcnt(2)
	ds_write_b128 v206, v[152:155]
	ds_write_b128 v206, v[160:163] offset:16
	s_waitcnt vmcnt(1)
	ds_write2_b64 v208, v[156:157], v[158:159] offset1:1
	s_waitcnt vmcnt(0)
	ds_write2_b64 v207, v[178:179], v[180:181] offset1:1
	v_mfma_f32_32x32x16_bf16 v[64:79], v[136:139], v[216:219], v[64:79]
	v_add_f32_e64 v168, v236, v128
	v_add_f32_e64 v169, v237, v129
	v_add_u32_e32 v210, s7, v196
	s_waitcnt lgkmcnt(0)
	s_barrier
	v_mfma_f32_32x32x16_bf16 v[48:63], v[140:143], v[216:219], v[48:63]
	v_mfma_f32_32x32x16_bf16 v[96:111], v[136:139], v[198:201], v[96:111]
	v_mfma_f32_32x32x16_bf16 v[16:31], v[140:143], v[198:201], v[16:31]
	v_mfma_f32_32x32x16_bf16 v[112:127], v[136:139], v[202:205], v[112:127]
	v_mfma_f32_32x32x16_bf16 v[0:15], v[140:143], v[202:205], v[0:15]
	s_cbranch_scc0 .LBB0_1571
	s_and_b32 s0, s0, 1
	s_mul_i32 s1, s0, 0x2200
	v_add_u32_e32 v170, s1, v196
	ds_read_b128 v[128:131], v170
	ds_read_b128 v[132:135], v197 offset:37888
	ds_read_b128 v[136:139], v197 offset:38912
	ds_read_b128 v[140:143], v170 offset:32
	s_mulk_i32 s0, 0x2400
	s_waitcnt lgkmcnt(2)
	v_mfma_f32_32x32x16_bf16 v[144:159], v[128:131], v[132:135], 0
	ds_read_b128 v[128:131], v170 offset:64
	ds_read_b128 v[132:135], v197 offset:39936
	ds_read_b128 v[160:163], v197 offset:40960
	ds_read_b128 v[176:179], v170 offset:96
	s_waitcnt lgkmcnt(4)
	v_mfma_f32_32x32x16_bf16 v[144:159], v[140:143], v[136:139], v[144:159]
	s_waitcnt lgkmcnt(2)
	v_mfma_f32_32x32x16_bf16 v[144:159], v[128:131], v[132:135], v[144:159]
	ds_read_b128 v[128:131], v170 offset:128
	ds_read_b128 v[132:135], v197 offset:41984
	ds_read_b128 v[198:201], v197 offset:43008
	ds_read_b128 v[202:205], v170 offset:160
	ds_read_b128 v[206:209], v197 offset:44032
	ds_read_b128 v[194:197], v197 offset:45056
	ds_read_b128 v[216:219], v170 offset:192
	ds_read_b128 v[220:223], v170 offset:224
	s_waitcnt lgkmcnt(6)
	v_mfma_f32_32x32x16_bf16 v[128:143], v[128:131], v[132:135], 0
	s_waitcnt lgkmcnt(4)
	v_mfma_f32_32x32x16_bf16 v[128:143], v[202:205], v[198:201], v[128:143]
	s_waitcnt lgkmcnt(1)
	v_mfma_f32_32x32x16_bf16 v[128:143], v[216:219], v[206:209], v[128:143]
	s_waitcnt lgkmcnt(0)
; #define MFMA32(a, b, c) __builtin_amdgcn_mfma_f32_32x32x16_bf16((a), (b), (c), 0, 0, 0)
; __device__ __forceinline__ void attn_item_A(const Params& p, int layer, int head, int q0u, char* lds) {
;     ...
;         float w[16];
; #pragma unroll
;         for (int e = 0; e < 16; ++e) { w[e] = __builtin_amdgcn_exp2f(fmaf(sx[e], CS, -bA)); lA += w[e]; }
;         const u32x4 p0 = {pk2(w[0], w[1]), pk2(w[2], w[3]), pk2(w[4], w[5]), pk2(w[6], w[7])};
;         const u32x4 p1 = {pk2(w[8], w[9]), pk2(w[10], w[11]), pk2(w[12], w[13]), pk2(w[14], w[15])};
;         a0 = __builtin_bit_cast(bf16x8, p0); a1 = __builtin_bit_cast(bf16x8, p1);
;       }
;       {
;         float w[16];
; #pragma unroll
;         for (int e = 0; e < 16; ++e) { w[e] = __builtin_amdgcn_exp2f(fmaf(sy[e], CS, -bB)); lB += w[e]; }
;         const u32x4 p0 = {pk2(w[0], w[1]), pk2(w[2], w[3]), pk2(w[4], w[5]), pk2(w[6], w[7])};
;         const u32x4 p1 = {pk2(w[8], w[9]), pk2(w[10], w[11]), pk2(w[12], w[13]), pk2(w[14], w[15])};
;         b0 = __builtin_bit_cast(bf16x8, p0); b1 = __builtin_bit_cast(bf16x8, p1);
;       }
;     }
;     const u16* vt = Vt + buf * 128 * VLD + r * VLD + 4 * h;
; #pragma unroll
;     for (int d = 0; d < 4; d += 2) {
;       const s16x4 l0 = *(const s16x4*)(vt + d * 32 * VLD), h0 = *(const s16x4*)(vt + d * 32 * VLD + 8);
;       const s16x4 l1 = *(const s16x4*)(vt + d * 32 * VLD + 16), h1 = *(const s16x4*)(vt + d * 32 * VLD + 24);
;       const s16x4 m0 = *(const s16x4*)(vt + (d + 1) * 32 * VLD), n0 = *(const s16x4*)(vt + (d + 1) * 32 * VLD + 8);
;       const s16x4 m1 = *(const s16x4*)(vt + (d + 1) * 32 * VLD + 16), n1 = *(const s16x4*)(vt + (d + 1) * 32 * VLD + 24);
;       const bf16x8 v0 = {l0[0], l0[1], l0[2], l0[3], h0[0], h0[1], h0[2], h0[3]};
;       const bf16x8 v1 = {l1[0], l1[1], l1[2], l1[3], h1[0], h1[1], h1[2], h1[3]};
;       const bf16x8 u0 = {m0[0], m0[1], m0[2], m0[3], n0[0], n0[1], n0[2], n0[3]};
;       const bf16x8 u1 = {m1[0], m1[1], m1[2], m1[3], n1[0], n1[1], n1[2], n1[3]};
;       o1[d] = MFMA32(a0, v0, o1[d]);
;       o2[d] = MFMA32(b0, v0, o2[d]);
;       o1[d + 1] = MFMA32(a0, u0, o1[d + 1]);
;       o2[d + 1] = MFMA32(b0, u0, o2[d + 1]);
;       o1[d] = MFMA32(a1, v1, o1[d]);
;       o2[d] = MFMA32(b1, v1, o2[d]);
;       o1[d + 1] = MFMA32(a1, u1, o1[d + 1]);
;       o2[d + 1] = MFMA32(b1, u1, o2[d + 1]);
;     }
	v_mfma_f32_32x32x16_bf16 v[128:143], v[220:223], v[194:197], v[128:143]
	v_mfma_f32_32x32x16_bf16 v[144:159], v[176:179], v[160:163], v[144:159]
	s_nop 10
	v_fmamk_f32 v128, v128, 0x3e38aa3b, v164
	v_exp_f32_e32 v194, v128
	v_fmamk_f32 v128, v129, 0x3e38aa3b, v164
	v_exp_f32_e32 v195, v128
	v_fmamk_f32 v128, v130, 0x3e38aa3b, v164
	v_exp_f32_e32 v196, v128
	v_fmamk_f32 v128, v131, 0x3e38aa3b, v164
	v_fmamk_f32 v144, v144, 0x3e38aa3b, v173
	v_exp_f32_e32 v160, v144
	v_fmamk_f32 v144, v155, 0x3e38aa3b, v173
	v_exp_f32_e32 v197, v128
	v_fmamk_f32 v128, v132, 0x3e38aa3b, v164
	v_fmamk_f32 v132, v134, 0x3e38aa3b, v164
	v_fmamk_f32 v145, v145, 0x3e38aa3b, v173
	v_fmamk_f32 v146, v146, 0x3e38aa3b, v173
	v_fmamk_f32 v147, v147, 0x3e38aa3b, v173
	v_fmamk_f32 v148, v148, 0x3e38aa3b, v173
	v_fmamk_f32 v149, v149, 0x3e38aa3b, v173
	v_fmamk_f32 v150, v150, 0x3e38aa3b, v173
	v_fmamk_f32 v151, v151, 0x3e38aa3b, v173
	v_exp_f32_e32 v179, v144
	v_fmamk_f32 v144, v156, 0x3e38aa3b, v173
	v_exp_f32_e32 v198, v128
	v_fmamk_f32 v128, v133, 0x3e38aa3b, v164
	v_add_u32_e32 v156, s0, v175
	v_exp_f32_e32 v175, v132
	v_fmamk_f32 v132, v135, 0x3e38aa3b, v164
	v_exp_f32_e32 v161, v145
	v_exp_f32_e32 v162, v146
	v_exp_f32_e32 v163, v147
	v_exp_f32_e32 v170, v148
	v_exp_f32_e32 v171, v149
	v_exp_f32_e32 v172, v150
	v_exp_f32_e32 v174, v151
	v_exp_f32_e32 v199, v128
	v_exp_f32_e32 v200, v132
	v_fmamk_f32 v152, v152, 0x3e38aa3b, v173
	v_exp_f32_e32 v180, v144
	v_fmamk_f32 v144, v157, 0x3e38aa3b, v173
	v_exp_f32_e32 v176, v152
	v_exp_f32_e32 v181, v144
	v_fmamk_f32 v144, v158, 0x3e38aa3b, v173
	v_add_u32_e32 v152, 0x4000, v156
	v_fmamk_f32 v136, v136, 0x3e38aa3b, v164
	v_exp_f32_e32 v193, v144
	v_cvt_pk_bf16_f32 v144, v160, v161
	v_cvt_pk_bf16_f32 v145, v162, v163
	v_cvt_pk_bf16_f32 v146, v170, v171
	v_cvt_pk_bf16_f32 v147, v172, v174
	ds_read2_b64 v[128:131], v152 offset0:128 offset1:130
	v_cvt_pk_bf16_f32 v132, v194, v195
	v_cvt_pk_bf16_f32 v133, v196, v197
	v_cvt_pk_bf16_f32 v134, v198, v199
	v_cvt_pk_bf16_f32 v135, v175, v200
	v_exp_f32_e32 v201, v136
	v_fmamk_f32 v136, v137, 0x3e38aa3b, v164
	v_exp_f32_e32 v202, v136
	v_fmamk_f32 v136, v138, 0x3e38aa3b, v164
	v_exp_f32_e32 v203, v136
	v_fmamk_f32 v136, v139, 0x3e38aa3b, v164
	v_fmamk_f32 v153, v153, 0x3e38aa3b, v173
	v_exp_f32_e32 v204, v136
	v_fmamk_f32 v136, v140, 0x3e38aa3b, v164
	v_exp_f32_e32 v177, v153
	v_add_u32_e32 v153, 0x4800, v156
	v_exp_f32_e32 v205, v136
	v_fmamk_f32 v136, v141, 0x3e38aa3b, v164
	v_fmamk_f32 v154, v154, 0x3e38aa3b, v173
	v_fmac_f32_e32 v173, 0x3e38aa3b, v159
	s_waitcnt lgkmcnt(0)
	v_mfma_f32_32x32x16_bf16 v[64:79], v[144:147], v[128:131], v[64:79]
	v_exp_f32_e32 v206, v136
	v_fmamk_f32 v136, v142, 0x3e38aa3b, v164
	v_fmac_f32_e32 v164, 0x3e38aa3b, v143
	v_exp_f32_e32 v178, v154
	v_exp_f32_e32 v173, v173
	v_exp_f32_e32 v207, v136
	v_exp_f32_e32 v164, v164
	v_mfma_f32_32x32x16_bf16 v[48:63], v[132:135], v[128:131], v[48:63]
	ds_read2_b64 v[128:131], v153 offset0:160 offset1:162
	v_cvt_pk_bf16_f32 v148, v176, v177
	v_cvt_pk_bf16_f32 v149, v178, v179
	v_cvt_pk_bf16_f32 v150, v180, v181
	v_cvt_pk_bf16_f32 v151, v193, v173
	v_cvt_pk_bf16_f32 v136, v201, v202
	v_cvt_pk_bf16_f32 v137, v203, v204
	s_waitcnt lgkmcnt(0)
	v_mfma_f32_32x32x16_bf16 v[80:95], v[144:147], v[128:131], v[80:95]
	v_cvt_pk_bf16_f32 v138, v205, v206
	v_cvt_pk_bf16_f32 v139, v207, v164
	v_add_f32_e32 v160, v168, v160
	v_add_f32_e32 v160, v161, v160
	v_mfma_f32_32x32x16_bf16 v[32:47], v[132:135], v[128:131], v[32:47]
	ds_read2_b64 v[128:131], v152 offset0:132 offset1:134
	v_add_u32_e32 v152, 0x5000, v156
	v_add_u32_e32 v156, 0x5800, v156
	s_waitcnt lgkmcnt(0)
	v_mfma_f32_32x32x16_bf16 v[64:79], v[148:151], v[128:131], v[64:79]
	v_mfma_f32_32x32x16_bf16 v[48:63], v[136:139], v[128:131], v[48:63]
	ds_read2_b64 v[128:131], v153 offset0:164 offset1:166
	ds_read2_b64 v[140:143], v152 offset0:192 offset1:194
	ds_read2_b64 v[152:155], v152 offset0:196 offset1:198
	s_waitcnt lgkmcnt(2)
	v_mfma_f32_32x32x16_bf16 v[80:95], v[148:151], v[128:131], v[80:95]
	v_mfma_f32_32x32x16_bf16 v[32:47], v[136:139], v[128:131], v[32:47]
	ds_read2_b64 v[128:131], v156 offset0:224 offset1:226
	ds_read2_b64 v[156:159], v156 offset0:228 offset1:230
	s_waitcnt lgkmcnt(0)
	s_barrier
; DI int crow(int i, int h) { return (i & 3) + 8 * (i >> 2) + 4 * h; }
; __device__ __forceinline__ void attn_item_A(const Params& p, int layer, int head, int q0u, char* lds) {
;     ...
;   int lane_e = lane; asm volatile("" : "+v"(lane_e));
;   const int r_e = lane_e & 31, h_e = lane_e >> 5;
;   lA += __shfl_xor(lA, 32); lB += __shfl_xor(lB, 32);
;   const float lam = ((const float*)(p.ws + OFF_LAM))[layer];
;   const float iA = 1.f / lA, iB = lam / lB;
;   u16* Mx = (u16*)(p.ws + OFF_M);
;   const int orow0 = q0u + wid * 32;
;   const float lam_init = 0.8f - 0.6f * expf(-0.3f * (float)layer);
;   float sw[4];
; #pragma unroll
;   for (int d = 0; d < 4; ++d) sw[d] = p.subln[layer * 128 + d * 32 + r_e] * (1.f - lam_init);
; #pragma unroll
;   for (int e = 0; e < 16; ++e) {
;     const int qq = crow(e, h_e);
;     const float ia = __shfl(iA, qq), ib = __shfl(iB, qq);
;     float ov[4];
;     float ss = 0.f;
; #pragma unroll
;     for (int d = 0; d < 4; ++d) { ov[d] = o1[d][e] * ia - o2[d][e] * ib; ss += ov[d] * ov[d]; }
; #pragma unroll
;     for (int x = 16; x >= 1; x >>= 1) ss += __shfl_xor(ss, x);
;     const float rs = rsqrtf(ss * (1.f / 128.f) + LN_EPS);
	global_load_dword v208, v165, s[16:17]
	v_and_b32_e32 v209, 31, v167
	v_mfma_f32_32x32x16_bf16 v[96:111], v[144:147], v[140:143], v[96:111]
	v_lshlrev_b32_e32 v210, 2, v209
	global_load_dword v212, v210, s[54:55]
	global_load_dword v213, v210, s[54:55] offset:128
	global_load_dword v215, v210, s[54:55] offset:256
	v_mfma_f32_32x32x16_bf16 v[16:31], v[132:135], v[140:143], v[16:31]
	v_add_f32_e32 v141, v169, v194
	v_add_f32_e32 v141, v195, v141
	v_add_f32_e32 v141, v196, v141
	v_add_f32_e32 v141, v197, v141
	v_add_f32_e32 v140, v162, v160
	v_add_f32_e32 v140, v163, v140
	v_add_f32_e32 v140, v170, v140
	v_mfma_f32_32x32x16_bf16 v[112:127], v[144:147], v[128:131], v[112:127]
	v_add_f32_e32 v140, v171, v140
	v_add_f32_e32 v140, v172, v140
	v_add_f32_e32 v140, v174, v140
	v_add_f32_e32 v140, v176, v140
	v_add_f32_e32 v140, v177, v140
	v_add_f32_e32 v140, v178, v140
	v_add_f32_e32 v140, v179, v140
	v_mfma_f32_32x32x16_bf16 v[0:15], v[132:135], v[128:131], v[0:15]
	v_add_f32_e32 v128, v198, v141
	v_add_f32_e32 v128, v199, v128
	v_add_f32_e32 v128, v175, v128
	v_add_f32_e32 v128, v200, v128
	v_add_f32_e32 v128, v201, v128
	v_add_f32_e32 v128, v202, v128
	v_add_f32_e32 v128, v203, v128
	v_add_f32_e32 v128, v204, v128
	v_add_f32_e32 v128, v205, v128
	v_add_f32_e32 v128, v206, v128
	v_add_f32_e32 v128, v207, v128
	v_add_f32_e32 v128, v164, v128
	ds_bpermute_b32 v129, v192, v128
	v_add_f32_e32 v130, v180, v140
	v_add_f32_e32 v130, v181, v130
	v_add_f32_e32 v130, v193, v130
	v_add_f32_e32 v130, v173, v130
	s_waitcnt lgkmcnt(0)
	v_add_f32_e32 v128, v128, v129
	ds_bpermute_b32 v133, v192, v130
	v_mfma_f32_32x32x16_bf16 v[0:15], v[136:139], v[156:159], v[0:15]
	v_mov_b32_e32 v143, v32
	v_mov_b32_e32 v140, v64
	v_mov_b32_e32 v142, v48
	s_waitcnt lgkmcnt(0)
	v_add_f32_e32 v133, v130, v133
	v_mov_b32_e32 v141, v80
	v_mov_b32_e32 v80, v65
	v_lshlrev_b32_e32 v164, 1, v209
	v_mfma_f32_32x32x16_bf16 v[16:31], v[136:139], v[152:155], v[16:31]
	s_nop 2
	v_mov_b32_e32 v146, v0
	v_xor_b32_e32 v0, 16, v214
	s_waitcnt vmcnt(3)
	v_div_scale_f32 v129, s[0:1], v128, v128, v208
	v_rcp_f32_e32 v131, v129
	v_mfma_f32_32x32x16_bf16 v[96:111], v[148:151], v[152:155], v[96:111]
	s_nop 2
	v_mov_b32_e32 v147, v16
	s_waitcnt vmcnt(1)
	v_mul_f32_e32 v130, 0x3f4ccccd, v213
	v_fma_f32 v132, -v129, v131, 1.0
	v_fmac_f32_e32 v131, v132, v131
	v_div_scale_f32 v132, vcc, v208, v128, v208
	v_mul_f32_e32 v134, v132, v131
	v_fma_f32 v135, -v129, v134, v132
	v_fmac_f32_e32 v134, v135, v131
	v_fma_f32 v129, -v129, v134, v132
	v_div_fmas_f32 v129, v129, v131, v134
	v_div_scale_f32 v134, s[0:1], v133, v133, 1.0
	v_rcp_f32_e32 v135, v134
	v_mfma_f32_32x32x16_bf16 v[112:127], v[148:151], v[156:159], v[112:127]
	v_div_fixup_f32 v132, v129, v128, v208
	v_mov_b32_e32 v145, v96
	v_fma_f32 v136, -v134, v135, 1.0
	v_fmac_f32_e32 v135, v136, v135
	v_div_scale_f32 v136, vcc, 1.0, v133, 1.0
	v_mul_f32_e32 v137, v136, v135
	v_fma_f32 v138, -v134, v137, v136
	v_fmac_f32_e32 v137, v138, v135
	v_fma_f32 v134, -v134, v137, v136
	v_div_fmas_f32 v134, v134, v135, v137
	v_ashrrev_i32_e32 v135, 3, v167
	v_div_fixup_f32 v133, v134, v133, 1.0
	v_and_b32_e32 v134, -4, v135
	v_cmp_lt_i32_e32 vcc, v0, v188
	v_or_b32_e32 v150, 1, v134
	v_and_or_b32 v136, v135, 60, v187
	v_cndmask_b32_e32 v16, v214, v0, vcc
	v_and_or_b32 v0, v150, 61, v187
	v_lshlrev_b32_e32 v137, 2, v136
	v_lshlrev_b32_e32 v32, 2, v0
	ds_bpermute_b32 v138, v137, v132
	ds_bpermute_b32 v0, v32, v132
	ds_bpermute_b32 v136, v137, v133
	ds_bpermute_b32 v64, v32, v133
	v_mov_b32_e32 v32, v49
	s_waitcnt lgkmcnt(3)
	v_pk_mul_f32 v[142:143], v[142:143], v[138:139] op_sel_hi:[1,0]
	v_mov_b32_e32 v144, v112
	v_pk_mul_f32 v[138:139], v[146:147], v[138:139] op_sel_hi:[1,0]
	v_lshlrev_b32_e32 v48, 2, v16
	s_waitcnt lgkmcnt(2)
	v_pk_mul_f32 v[32:33], v[32:33], v[0:1] op_sel_hi:[1,0]
	v_mov_b32_e32 v16, v1
	s_waitcnt lgkmcnt(1)
	v_pk_fma_f32 v[140:141], v[140:141], v[136:137], v[142:143] op_sel_hi:[1,0,1] neg_lo:[0,0,1] neg_hi:[0,0,1]
	v_pk_fma_f32 v[136:137], v[144:145], v[136:137], v[138:139] op_sel_hi:[1,0,1] neg_lo:[0,0,1] neg_hi:[0,0,1]
	s_waitcnt lgkmcnt(0)
	v_pk_fma_f32 v[144:145], v[80:81], v[64:65], v[32:33] op_sel_hi:[1,0,1] neg_lo:[0,0,1] neg_hi:[0,0,1]
	v_mov_b32_e32 v96, v113
	v_pk_mul_f32 v[0:1], v[16:17], v[0:1] op_sel_hi:[1,0]
	v_pk_mul_f32 v[142:143], v[140:141], v[140:141]
	v_pk_mul_f32 v[32:33], v[144:145], v[144:145]
	v_pk_fma_f32 v[96:97], v[96:97], v[64:65], v[0:1] op_sel_hi:[1,0,1] neg_lo:[0,0,1] neg_hi:[0,0,1]
	v_pk_mul_f32 v[138:139], v[136:137], v[136:137]
	v_pk_mul_f32 v[0:1], v[96:97], v[96:97]
	v_mov_b32_e32 v16, v32
	v_mov_b32_e32 v17, v142
	v_mov_b32_e32 v142, v33
	v_pk_add_f32 v[16:17], v[16:17], v[142:143]
	v_mov_b32_e32 v32, v1
	v_mov_b32_e32 v33, v139
	v_pk_add_f32 v[16:17], v[32:33], v[16:17]
	v_mov_b32_e32 v1, v138
	v_pk_add_f32 v[0:1], v[0:1], v[16:17]
	ds_bpermute_b32 v17, v48, v1
	ds_bpermute_b32 v16, v48, v0
	v_xor_b32_e32 v32, 8, v214
	v_cmp_lt_i32_e32 vcc, v32, v188
	s_add_u32 s0, s31, s4
	s_addc_u32 s1, s34, s5
	v_cndmask_b32_e32 v32, v214, v32, vcc
	v_lshlrev_b32_e32 v49, 2, v32
	s_waitcnt lgkmcnt(0)
	v_pk_add_f32 v[0:1], v[0:1], v[16:17]
	ds_bpermute_b32 v17, v49, v1
	ds_bpermute_b32 v16, v49, v0
	v_xor_b32_e32 v32, 4, v214
	v_cmp_lt_i32_e32 vcc, v32, v188
	v_mul_f32_e32 v131, 0x3f4ccccd, v212
	s_waitcnt vmcnt(0)
	v_mul_f32_e32 v129, 0x3f4ccccd, v215
	v_cndmask_b32_e32 v32, v214, v32, vcc
	v_lshlrev_b32_e32 v64, 2, v32
	s_waitcnt lgkmcnt(0)
	v_pk_add_f32 v[0:1], v[0:1], v[16:17]
	ds_bpermute_b32 v17, v64, v1
	ds_bpermute_b32 v16, v64, v0
	v_xor_b32_e32 v32, 2, v214
	v_cmp_lt_i32_e32 vcc, v32, v188
	v_or_b32_e32 v152, 2, v134
	v_or_b32_e32 v135, 3, v135
	v_cndmask_b32_e32 v32, v214, v32, vcc
	v_lshlrev_b32_e32 v65, 2, v32
	s_waitcnt lgkmcnt(0)
; DI u16 f2bf(float a) { return (u16)(pk2(a, 0.f) & 0xffffu); }
; DI int crow(int i, int h) { return (i & 3) + 8 * (i >> 2) + 4 * h; }
; __device__ __forceinline__ void attn_item_A(const Params& p, int layer, int head, int q0u, char* lds) {
;     ...
;   for (int e = 0; e < 16; ++e) {
;     const int qq = crow(e, h_e);
;     const float ia = __shfl(iA, qq), ib = __shfl(iB, qq);
;     float ov[4];
;     float ss = 0.f;
; #pragma unroll
;     for (int d = 0; d < 4; ++d) { ov[d] = o1[d][e] * ia - o2[d][e] * ib; ss += ov[d] * ov[d]; }
; #pragma unroll
;     for (int x = 16; x >= 1; x >>= 1) ss += __shfl_xor(ss, x);
;     const float rs = rsqrtf(ss * (1.f / 128.f) + LN_EPS);
;     const size_t rowoff = (size_t)(orow0 + qq) * LDX + ocol + r_e;
; #pragma unroll
;     for (int d = 0; d < 4; ++d) Mx[rowoff + d * 32] = f2bf(ov[d] * rs * sw[d]);
;   }
	v_pk_add_f32 v[0:1], v[0:1], v[16:17]
	ds_bpermute_b32 v17, v65, v1
	ds_bpermute_b32 v16, v65, v0
	v_xor_b32_e32 v32, 1, v214
	v_cmp_lt_i32_e32 vcc, v32, v188
	v_mov_b32_e32 v148, v2
	v_and_or_b32 v2, v135, 63, v187
	v_cndmask_b32_e32 v32, v214, v32, vcc
	v_lshlrev_b32_e32 v80, 2, v32
	s_waitcnt lgkmcnt(0)
	v_pk_add_f32 v[0:1], v[0:1], v[16:17]
	ds_bpermute_b32 v33, v80, v1
	ds_bpermute_b32 v32, v80, v0
	v_lshl_add_u64 v[16:17], s[0:1], 0, v[164:165]
	v_mov_b32_e32 v149, v18
	v_lshlrev_b32_e32 v18, 2, v2
	ds_bpermute_b32 v2, v18, v132
	s_waitcnt lgkmcnt(1)
	v_pk_add_f32 v[0:1], v[0:1], v[32:33]
	v_mov_b64_e32 v[32:33], s[30:31]
	v_pk_fma_f32 v[112:113], v[0:1], s[28:29], v[32:33] op_sel_hi:[1,0,0]
	v_mov_b32_e32 v142, v50
	v_mul_f32_e32 v0, 0x4b800000, v113
	v_cmp_gt_f32_e32 vcc, s80, v113
	ds_bpermute_b32 v50, v18, v133
	v_mov_b32_e32 v143, v34
	v_cndmask_b32_e32 v0, v113, v0, vcc
	v_rsq_f32_e32 v81, v0
	v_add_u32_e32 v0, v134, v191
	v_mad_i64_i32 v[0:1], s[0:1], v0, s77, v[16:17]
	v_mul_f32_e32 v113, 0x45800000, v81
	v_cndmask_b32_e32 v81, v81, v113, vcc
	v_mul_f32_e32 v113, v140, v81
	v_mul_f32_e32 v113, v131, v113
	v_cvt_pk_bf16_f32 v113, v113, s0
	global_store_short v[0:1], v113, off
	v_mul_f32_e32 v113, v141, v81
	v_mul_f32_e32 v113, v130, v113
	v_cvt_pk_bf16_f32 v113, v113, s0
	global_store_short v[0:1], v113, off offset:64
	v_mul_f32_e32 v113, v137, v81
	v_mul_f32_e32 v113, v129, v113
	v_cvt_pk_bf16_f32 v137, v113, s0
	v_mul_f32_e32 v113, 0x4b800000, v112
	v_cmp_gt_f32_e32 vcc, s80, v112
	v_mov_b32_e32 v34, v51
	v_mov_b32_e32 v140, v66
	v_cndmask_b32_e32 v112, v112, v113, vcc
	v_rsq_f32_e32 v151, v112
	v_and_or_b32 v112, v152, 62, v187
	v_lshlrev_b32_e32 v113, 2, v112
	ds_bpermute_b32 v138, v113, v132
	ds_bpermute_b32 v112, v113, v133
	v_mov_b32_e32 v141, v82
	v_mov_b32_e32 v82, v67
	s_waitcnt lgkmcnt(3)
	v_pk_mul_f32 v[34:35], v[34:35], v[2:3] op_sel_hi:[1,0]
	s_waitcnt lgkmcnt(1)
	v_pk_mul_f32 v[142:143], v[142:143], v[138:139] op_sel_hi:[1,0]
	v_mov_b32_e32 v18, v3
	s_waitcnt lgkmcnt(0)
	v_pk_fma_f32 v[140:141], v[140:141], v[112:113], v[142:143] op_sel_hi:[1,0,1] neg_lo:[0,0,1] neg_hi:[0,0,1]
	v_mov_b32_e32 v146, v114
	v_mov_b32_e32 v147, v98
	v_pk_mul_f32 v[138:139], v[148:149], v[138:139] op_sel_hi:[1,0]
	v_pk_fma_f32 v[66:67], v[82:83], v[50:51], v[34:35] op_sel_hi:[1,0,1] neg_lo:[0,0,1] neg_hi:[0,0,1]
	v_mov_b32_e32 v98, v115
	v_pk_mul_f32 v[2:3], v[18:19], v[2:3] op_sel_hi:[1,0]
	v_pk_mul_f32 v[142:143], v[140:141], v[140:141]
	v_pk_fma_f32 v[112:113], v[146:147], v[112:113], v[138:139] op_sel_hi:[1,0,1] neg_lo:[0,0,1] neg_hi:[0,0,1]
	v_pk_mul_f32 v[34:35], v[66:67], v[66:67]
	v_pk_fma_f32 v[50:51], v[98:99], v[50:51], v[2:3] op_sel_hi:[1,0,1] neg_lo:[0,0,1] neg_hi:[0,0,1]
	v_pk_mul_f32 v[138:139], v[112:113], v[112:113]
	v_pk_mul_f32 v[2:3], v[50:51], v[50:51]
	v_mov_b32_e32 v18, v34
	v_mov_b32_e32 v19, v142
	v_mov_b32_e32 v142, v35
	v_pk_add_f32 v[18:19], v[18:19], v[142:143]
	v_mov_b32_e32 v34, v3
	v_mov_b32_e32 v35, v139
	v_pk_add_f32 v[18:19], v[34:35], v[18:19]
	v_mov_b32_e32 v3, v138
	v_pk_add_f32 v[2:3], v[2:3], v[18:19]
	ds_bpermute_b32 v19, v48, v3
	ds_bpermute_b32 v18, v48, v2
	v_mul_f32_e32 v35, 0x45800000, v151
	v_cndmask_b32_e32 v35, v151, v35, vcc
	v_mul_f32_e32 v34, v136, v81
	v_mul_f32_e32 v81, v144, v35
	s_waitcnt lgkmcnt(0)
	v_pk_add_f32 v[18:19], v[2:3], v[18:19]
	ds_bpermute_b32 v83, v49, v19
	ds_bpermute_b32 v82, v49, v18
	v_add_u32_e32 v2, v150, v191
	v_mad_i64_i32 v[2:3], s[0:1], v2, s77, v[16:17]
	v_mul_f32_e32 v81, v131, v81
	s_waitcnt lgkmcnt(0)
	v_pk_add_f32 v[18:19], v[18:19], v[82:83]
	ds_bpermute_b32 v83, v64, v19
	ds_bpermute_b32 v82, v64, v18
	v_cvt_pk_bf16_f32 v81, v81, s0
	global_store_short v[2:3], v81, off
	v_mul_f32_e32 v81, v145, v35
	v_mul_f32_e32 v81, v130, v81
	s_waitcnt lgkmcnt(0)
	v_pk_add_f32 v[18:19], v[18:19], v[82:83]
	ds_bpermute_b32 v83, v65, v19
	ds_bpermute_b32 v82, v65, v18
	v_cvt_pk_bf16_f32 v81, v81, s0
	global_store_short v[2:3], v81, off offset:64
	v_mul_f32_e32 v81, v97, v35
	v_mul_f32_e32 v81, v129, v81
	s_waitcnt lgkmcnt(0)
	v_pk_add_f32 v[18:19], v[18:19], v[82:83]
	ds_bpermute_b32 v83, v80, v19
	ds_bpermute_b32 v82, v80, v18
	v_cvt_pk_bf16_f32 v81, v81, s0
	global_store_short v[2:3], v81, off offset:128
	v_mov_b32_e32 v136, v116
	v_add_u32_e32 v116, 9, v134
	s_waitcnt lgkmcnt(0)
	v_pk_add_f32 v[18:19], v[18:19], v[82:83]
	v_mov_b32_e32 v138, v4
	v_pk_fma_f32 v[82:83], v[18:19], s[28:29], v[32:33] op_sel_hi:[1,0,0]
	v_and_or_b32 v4, v116, 61, v187
	v_mul_f32_e32 v18, 0x4b800000, v83
	v_cmp_gt_f32_e32 vcc, s80, v83
	v_mov_b32_e32 v139, v20
	v_lshlrev_b32_e32 v20, 2, v4
	v_cndmask_b32_e32 v18, v83, v18, vcc
	v_rsq_f32_e32 v81, v18
	v_add_u32_e32 v18, v152, v191
	v_mad_i64_i32 v[18:19], s[0:1], v18, s77, v[16:17]
	v_mul_f32_e32 v83, 0x45800000, v81
	v_cndmask_b32_e32 v81, v81, v83, vcc
	v_mul_f32_e32 v83, v140, v81
	v_mul_f32_e32 v83, v131, v83
	v_cvt_pk_bf16_f32 v83, v83, s0
	global_store_short v[18:19], v83, off
	v_mul_f32_e32 v83, v141, v81
	v_mul_f32_e32 v83, v130, v83
	v_cvt_pk_bf16_f32 v83, v83, s0
	global_store_short v[18:19], v83, off offset:64
	v_mul_f32_e32 v83, v113, v81
	v_mul_f32_e32 v83, v129, v83
	v_cvt_pk_bf16_f32 v113, v83, s0
	v_mul_f32_e32 v83, 0x4b800000, v82
	v_cmp_gt_f32_e32 vcc, s80, v82
	v_add_u32_e32 v141, 8, v134
	v_mul_f32_e32 v35, v96, v35
	v_cndmask_b32_e32 v82, v82, v83, vcc
	v_rsq_f32_e32 v140, v82
	v_and_or_b32 v82, v141, 60, v187
	v_lshlrev_b32_e32 v83, 2, v82
	ds_bpermute_b32 v96, v83, v132
	ds_bpermute_b32 v4, v20, v132
	ds_bpermute_b32 v82, v83, v133
	v_mov_b32_e32 v114, v52
	ds_bpermute_b32 v52, v20, v133
	v_mov_b32_e32 v115, v36
	v_mov_b32_e32 v36, v53
	v_mov_b32_e32 v98, v68
	v_mov_b32_e32 v99, v84
	s_waitcnt lgkmcnt(3)
; DI u16 f2bf(float a) { return (u16)(pk2(a, 0.f) & 0xffffu); }
; DI int crow(int i, int h) { return (i & 3) + 8 * (i >> 2) + 4 * h; }
; __device__ __forceinline__ void attn_item_A(const Params& p, int layer, int head, int q0u, char* lds) {
;     ...
;   for (int e = 0; e < 16; ++e) {
;     const int qq = crow(e, h_e);
;     const float ia = __shfl(iA, qq), ib = __shfl(iB, qq);
;     float ov[4];
;     float ss = 0.f;
; #pragma unroll
;     for (int d = 0; d < 4; ++d) { ov[d] = o1[d][e] * ia - o2[d][e] * ib; ss += ov[d] * ov[d]; }
; #pragma unroll
;     for (int x = 16; x >= 1; x >>= 1) ss += __shfl_xor(ss, x);
;     const float rs = rsqrtf(ss * (1.f / 128.f) + LN_EPS);
;     const size_t rowoff = (size_t)(orow0 + qq) * LDX + ocol + r_e;
; #pragma unroll
;     for (int d = 0; d < 4; ++d) Mx[rowoff + d * 32] = f2bf(ov[d] * rs * sw[d]);
;   }
	v_pk_mul_f32 v[114:115], v[114:115], v[96:97] op_sel_hi:[1,0]
	v_mov_b32_e32 v84, v69
	s_waitcnt lgkmcnt(2)
	v_pk_mul_f32 v[36:37], v[36:37], v[4:5] op_sel_hi:[1,0]
	v_mov_b32_e32 v20, v5
	global_store_short v[0:1], v137, off offset:128
	s_waitcnt lgkmcnt(1)
	v_pk_fma_f32 v[98:99], v[98:99], v[82:83], v[114:115] op_sel_hi:[1,0,1] neg_lo:[0,0,1] neg_hi:[0,0,1]
	v_mov_b32_e32 v137, v100
	v_pk_mul_f32 v[96:97], v[138:139], v[96:97] op_sel_hi:[1,0]
	s_waitcnt lgkmcnt(0)
	v_pk_fma_f32 v[68:69], v[84:85], v[52:53], v[36:37] op_sel_hi:[1,0,1] neg_lo:[0,0,1] neg_hi:[0,0,1]
	v_mov_b32_e32 v100, v117
	v_pk_mul_f32 v[4:5], v[20:21], v[4:5] op_sel_hi:[1,0]
	v_pk_mul_f32 v[114:115], v[98:99], v[98:99]
	v_pk_fma_f32 v[82:83], v[136:137], v[82:83], v[96:97] op_sel_hi:[1,0,1] neg_lo:[0,0,1] neg_hi:[0,0,1]
	v_pk_mul_f32 v[36:37], v[68:69], v[68:69]
	v_pk_fma_f32 v[52:53], v[100:101], v[52:53], v[4:5] op_sel_hi:[1,0,1] neg_lo:[0,0,1] neg_hi:[0,0,1]
	v_pk_mul_f32 v[96:97], v[82:83], v[82:83]
	v_pk_mul_f32 v[4:5], v[52:53], v[52:53]
	v_mov_b32_e32 v20, v36
	v_mov_b32_e32 v21, v114
	v_mov_b32_e32 v114, v37
	v_pk_add_f32 v[20:21], v[20:21], v[114:115]
	v_mov_b32_e32 v36, v5
	v_mov_b32_e32 v37, v97
	v_pk_add_f32 v[20:21], v[36:37], v[20:21]
	v_mov_b32_e32 v5, v96
	v_pk_add_f32 v[4:5], v[4:5], v[20:21]
	ds_bpermute_b32 v21, v48, v5
	ds_bpermute_b32 v20, v48, v4
	v_mul_f32_e32 v37, 0x45800000, v140
	v_cndmask_b32_e32 v37, v140, v37, vcc
	v_mul_f32_e32 v66, v66, v37
	v_mul_f32_e32 v66, v131, v66
	s_waitcnt lgkmcnt(0)
	v_pk_add_f32 v[20:21], v[4:5], v[20:21]
	ds_bpermute_b32 v85, v49, v21
	ds_bpermute_b32 v84, v49, v20
	v_add_u32_e32 v4, v135, v191
	v_mad_i64_i32 v[4:5], s[0:1], v4, s77, v[16:17]
	v_mul_f32_e32 v36, v112, v81
	s_waitcnt lgkmcnt(0)
	v_pk_add_f32 v[20:21], v[20:21], v[84:85]
	ds_bpermute_b32 v85, v64, v21
	ds_bpermute_b32 v84, v64, v20
	v_cvt_pk_bf16_f32 v66, v66, s0
	global_store_short v[4:5], v66, off
	v_mul_f32_e32 v81, v67, v37
	v_mul_f32_e32 v51, v51, v37
	s_waitcnt lgkmcnt(0)
	v_pk_add_f32 v[20:21], v[20:21], v[84:85]
	ds_bpermute_b32 v67, v65, v21
	ds_bpermute_b32 v66, v65, v20
	v_mul_f32_e32 v51, v129, v51
	v_cvt_pk_bf16_f32 v51, v51, s0
	global_store_short v[4:5], v51, off offset:128
	v_mul_f32_e32 v37, v50, v37
	s_waitcnt lgkmcnt(0)
	v_pk_add_f32 v[20:21], v[20:21], v[66:67]
	ds_bpermute_b32 v67, v80, v21
	ds_bpermute_b32 v66, v80, v20
	v_mul_f32_e32 v81, v130, v81
	v_cvt_pk_bf16_f32 v81, v81, s0
	global_store_short v[4:5], v81, off offset:64
	global_store_short v[18:19], v113, off offset:128
	s_waitcnt lgkmcnt(0)
	v_pk_add_f32 v[20:21], v[20:21], v[66:67]
	v_add_u32_e32 v113, 10, v134
	v_pk_fma_f32 v[50:51], v[20:21], s[28:29], v[32:33] op_sel_hi:[1,0,0]
	v_mov_b32_e32 v96, v54
	v_mul_f32_e32 v20, 0x4b800000, v51
	v_cmp_gt_f32_e32 vcc, s80, v51
	v_mov_b32_e32 v97, v38
	v_mov_b32_e32 v100, v6
	v_cndmask_b32_e32 v20, v51, v20, vcc
	v_rsq_f32_e32 v51, v20
	v_add_u32_e32 v20, v141, v191
	v_mad_i64_i32 v[20:21], s[0:1], v20, s77, v[16:17]
	v_mul_f32_e32 v66, 0x45800000, v51
	v_cndmask_b32_e32 v81, v51, v66, vcc
	v_mul_f32_e32 v51, v98, v81
	v_mul_f32_e32 v51, v131, v51
	v_cvt_pk_bf16_f32 v51, v51, s0
	global_store_short v[20:21], v51, off
	v_mul_f32_e32 v51, v99, v81
	v_mul_f32_e32 v51, v130, v51
	v_cvt_pk_bf16_f32 v51, v51, s0
	global_store_short v[20:21], v51, off offset:64
	v_mul_f32_e32 v51, v83, v81
	v_mul_f32_e32 v51, v129, v51
	v_cvt_pk_bf16_f32 v83, v51, s0
	v_mul_f32_e32 v51, 0x4b800000, v50
	v_cmp_gt_f32_e32 vcc, s80, v50
	v_mov_b32_e32 v101, v22
	v_mov_b32_e32 v84, v70
	v_cndmask_b32_e32 v50, v50, v51, vcc
	v_rsq_f32_e32 v112, v50
	v_and_or_b32 v50, v113, 62, v187
	v_lshlrev_b32_e32 v51, 2, v50
	ds_bpermute_b32 v66, v51, v132
	ds_bpermute_b32 v50, v51, v133
	v_mov_b32_e32 v85, v86
	v_mov_b32_e32 v98, v118
	v_mov_b32_e32 v99, v102
	s_waitcnt lgkmcnt(1)
	v_pk_mul_f32 v[96:97], v[96:97], v[66:67] op_sel_hi:[1,0]
	v_pk_mul_f32 v[66:67], v[100:101], v[66:67] op_sel_hi:[1,0]
	s_waitcnt lgkmcnt(0)
	v_pk_fma_f32 v[84:85], v[84:85], v[50:51], v[96:97] op_sel_hi:[1,0,1] neg_lo:[0,0,1] neg_hi:[0,0,1]
	v_pk_fma_f32 v[50:51], v[98:99], v[50:51], v[66:67] op_sel_hi:[1,0,1] neg_lo:[0,0,1] neg_hi:[0,0,1]
	v_add_u32_e32 v98, 11, v134
	v_and_or_b32 v6, v98, 63, v187
	v_lshlrev_b32_e32 v22, 2, v6
	ds_bpermute_b32 v6, v22, v132
	ds_bpermute_b32 v54, v22, v133
	v_mov_b32_e32 v38, v55
	v_mov_b32_e32 v86, v71
	v_mov_b32_e32 v22, v7
	s_waitcnt lgkmcnt(1)
	v_pk_mul_f32 v[38:39], v[38:39], v[6:7] op_sel_hi:[1,0]
	v_mov_b32_e32 v102, v119
	s_waitcnt lgkmcnt(0)
	v_pk_fma_f32 v[70:71], v[86:87], v[54:55], v[38:39] op_sel_hi:[1,0,1] neg_lo:[0,0,1] neg_hi:[0,0,1]
	v_pk_mul_f32 v[6:7], v[22:23], v[6:7] op_sel_hi:[1,0]
	v_pk_mul_f32 v[96:97], v[84:85], v[84:85]
	v_pk_mul_f32 v[38:39], v[70:71], v[70:71]
	v_pk_fma_f32 v[54:55], v[102:103], v[54:55], v[6:7] op_sel_hi:[1,0,1] neg_lo:[0,0,1] neg_hi:[0,0,1]
	v_pk_mul_f32 v[66:67], v[50:51], v[50:51]
	v_pk_mul_f32 v[6:7], v[54:55], v[54:55]
	v_mov_b32_e32 v22, v38
	v_mov_b32_e32 v23, v96
	v_mov_b32_e32 v96, v39
	v_pk_add_f32 v[22:23], v[22:23], v[96:97]
	v_mov_b32_e32 v38, v7
	v_mov_b32_e32 v39, v67
	v_pk_add_f32 v[22:23], v[38:39], v[22:23]
	v_mov_b32_e32 v7, v66
	v_pk_add_f32 v[6:7], v[6:7], v[22:23]
	ds_bpermute_b32 v23, v48, v7
	ds_bpermute_b32 v22, v48, v6
	v_mul_f32_e32 v39, 0x45800000, v112
	v_cndmask_b32_e32 v39, v112, v39, vcc
	v_mul_f32_e32 v68, v68, v39
	v_mul_f32_e32 v53, v53, v39
	s_waitcnt lgkmcnt(0)
	v_pk_add_f32 v[22:23], v[6:7], v[22:23]
	ds_bpermute_b32 v67, v49, v23
	ds_bpermute_b32 v66, v49, v22
	v_add_u32_e32 v6, v116, v191
	v_mad_i64_i32 v[6:7], s[0:1], v6, s77, v[16:17]
	v_mul_f32_e32 v68, v131, v68
	s_waitcnt lgkmcnt(0)
; DI u16 f2bf(float a) { return (u16)(pk2(a, 0.f) & 0xffffu); }
; DI int crow(int i, int h) { return (i & 3) + 8 * (i >> 2) + 4 * h; }
; __device__ __forceinline__ void attn_item_A(const Params& p, int layer, int head, int q0u, char* lds) {
;     ...
;   for (int e = 0; e < 16; ++e) {
;     const int qq = crow(e, h_e);
;     const float ia = __shfl(iA, qq), ib = __shfl(iB, qq);
;     float ov[4];
;     float ss = 0.f;
; #pragma unroll
;     for (int d = 0; d < 4; ++d) { ov[d] = o1[d][e] * ia - o2[d][e] * ib; ss += ov[d] * ov[d]; }
; #pragma unroll
;     for (int x = 16; x >= 1; x >>= 1) ss += __shfl_xor(ss, x);
;     const float rs = rsqrtf(ss * (1.f / 128.f) + LN_EPS);
;     const size_t rowoff = (size_t)(orow0 + qq) * LDX + ocol + r_e;
; #pragma unroll
;     for (int d = 0; d < 4; ++d) Mx[rowoff + d * 32] = f2bf(ov[d] * rs * sw[d]);
;   }
	v_pk_add_f32 v[22:23], v[22:23], v[66:67]
	ds_bpermute_b32 v67, v64, v23
	ds_bpermute_b32 v66, v64, v22
	v_mul_f32_e32 v53, v129, v53
	v_cvt_pk_bf16_f32 v68, v68, s0
	v_cvt_pk_bf16_f32 v53, v53, s0
	global_store_short v[6:7], v68, off
	s_waitcnt lgkmcnt(0)
	v_pk_add_f32 v[22:23], v[22:23], v[66:67]
	ds_bpermute_b32 v67, v65, v23
	ds_bpermute_b32 v66, v65, v22
	v_mul_f32_e32 v68, v69, v39
	global_store_short v[6:7], v53, off offset:128
	v_mul_f32_e32 v39, v52, v39
	v_mul_f32_e32 v38, v82, v81
	s_waitcnt lgkmcnt(0)
	v_pk_add_f32 v[22:23], v[22:23], v[66:67]
	ds_bpermute_b32 v67, v80, v23
	ds_bpermute_b32 v66, v80, v22
	v_mul_f32_e32 v68, v130, v68
	v_cvt_pk_bf16_f32 v68, v68, s0
	v_add_u32_e32 v97, 16, v134
	global_store_short v[20:21], v83, off offset:128
	s_waitcnt lgkmcnt(0)
	v_pk_add_f32 v[22:23], v[22:23], v[66:67]
	v_mov_b32_e32 v82, v56
	v_pk_fma_f32 v[52:53], v[22:23], s[28:29], v[32:33] op_sel_hi:[1,0,0]
	v_mov_b32_e32 v83, v40
	v_mul_f32_e32 v22, 0x4b800000, v53
	v_cmp_gt_f32_e32 vcc, s80, v53
	v_mov_b32_e32 v86, v8
	v_mov_b32_e32 v87, v24
	v_cndmask_b32_e32 v22, v53, v22, vcc
	v_rsq_f32_e32 v53, v22
	v_add_u32_e32 v22, v113, v191
	v_mad_i64_i32 v[22:23], s[0:1], v22, s77, v[16:17]
	v_mul_f32_e32 v66, 0x45800000, v53
	v_cndmask_b32_e32 v81, v53, v66, vcc
	v_mul_f32_e32 v53, v84, v81
	v_mul_f32_e32 v53, v131, v53
	v_cvt_pk_bf16_f32 v53, v53, s0
	global_store_short v[22:23], v53, off
	v_mul_f32_e32 v53, v85, v81
	v_mul_f32_e32 v53, v130, v53
	v_cvt_pk_bf16_f32 v53, v53, s0
	global_store_short v[22:23], v53, off offset:64
	v_mul_f32_e32 v53, 0x4b800000, v52
	v_cmp_gt_f32_e32 vcc, s80, v52
	global_store_short v[6:7], v68, off offset:64
	v_mov_b32_e32 v68, v72
	v_cndmask_b32_e32 v52, v52, v53, vcc
	v_rsq_f32_e32 v96, v52
	v_and_or_b32 v52, v97, 60, v187
	v_lshlrev_b32_e32 v53, 2, v52
	ds_bpermute_b32 v66, v53, v132
	ds_bpermute_b32 v52, v53, v133
	v_mov_b32_e32 v69, v88
	v_mov_b32_e32 v84, v120
	v_mov_b32_e32 v85, v104
	s_waitcnt lgkmcnt(1)
	v_pk_mul_f32 v[82:83], v[82:83], v[66:67] op_sel_hi:[1,0]
	v_pk_mul_f32 v[66:67], v[86:87], v[66:67] op_sel_hi:[1,0]
	s_waitcnt lgkmcnt(0)
	v_pk_fma_f32 v[68:69], v[68:69], v[52:53], v[82:83] op_sel_hi:[1,0,1] neg_lo:[0,0,1] neg_hi:[0,0,1]
	v_pk_fma_f32 v[52:53], v[84:85], v[52:53], v[66:67] op_sel_hi:[1,0,1] neg_lo:[0,0,1] neg_hi:[0,0,1]
	v_add_u32_e32 v84, 17, v134
	v_and_or_b32 v8, v84, 61, v187
	v_lshlrev_b32_e32 v24, 2, v8
	ds_bpermute_b32 v8, v24, v132
	ds_bpermute_b32 v56, v24, v133
	v_mov_b32_e32 v40, v57
	v_mov_b32_e32 v88, v73
	v_mov_b32_e32 v24, v9
	s_waitcnt lgkmcnt(1)
	v_pk_mul_f32 v[40:41], v[40:41], v[8:9] op_sel_hi:[1,0]
	v_mov_b32_e32 v104, v121
	s_waitcnt lgkmcnt(0)
	v_pk_fma_f32 v[72:73], v[88:89], v[56:57], v[40:41] op_sel_hi:[1,0,1] neg_lo:[0,0,1] neg_hi:[0,0,1]
	v_pk_mul_f32 v[8:9], v[24:25], v[8:9] op_sel_hi:[1,0]
	v_pk_mul_f32 v[82:83], v[68:69], v[68:69]
	v_pk_mul_f32 v[40:41], v[72:73], v[72:73]
	v_pk_fma_f32 v[56:57], v[104:105], v[56:57], v[8:9] op_sel_hi:[1,0,1] neg_lo:[0,0,1] neg_hi:[0,0,1]
	v_pk_mul_f32 v[66:67], v[52:53], v[52:53]
	v_pk_mul_f32 v[8:9], v[56:57], v[56:57]
	v_mov_b32_e32 v24, v40
	v_mov_b32_e32 v25, v82
	v_mov_b32_e32 v82, v41
	v_pk_add_f32 v[24:25], v[24:25], v[82:83]
	v_mov_b32_e32 v40, v9
	v_mov_b32_e32 v41, v67
	v_pk_add_f32 v[24:25], v[40:41], v[24:25]
	v_mov_b32_e32 v9, v66
	v_pk_add_f32 v[8:9], v[8:9], v[24:25]
	ds_bpermute_b32 v25, v48, v9
	ds_bpermute_b32 v24, v48, v8
	v_mul_f32_e32 v51, v51, v81
	v_mul_f32_e32 v51, v129, v51
	v_cvt_pk_bf16_f32 v51, v51, s0
	global_store_short v[22:23], v51, off offset:128
	s_waitcnt lgkmcnt(0)
	v_pk_add_f32 v[24:25], v[8:9], v[24:25]
	v_mul_f32_e32 v40, v50, v81
	ds_bpermute_b32 v51, v49, v25
	ds_bpermute_b32 v50, v49, v24
	v_mul_f32_e32 v41, 0x45800000, v96
	v_cndmask_b32_e32 v41, v96, v41, vcc
	v_add_u32_e32 v8, v98, v191
	v_mul_f32_e32 v66, v70, v41
	s_waitcnt lgkmcnt(0)
	v_pk_add_f32 v[24:25], v[24:25], v[50:51]
	ds_bpermute_b32 v51, v64, v25
	ds_bpermute_b32 v50, v64, v24
	v_mad_i64_i32 v[8:9], s[0:1], v8, s77, v[16:17]
	v_mul_f32_e32 v66, v131, v66
	s_nop 0
	v_cvt_pk_bf16_f32 v66, v66, s0
	s_waitcnt lgkmcnt(0)
	v_pk_add_f32 v[24:25], v[24:25], v[50:51]
	ds_bpermute_b32 v51, v65, v25
	ds_bpermute_b32 v50, v65, v24
	global_store_short v[8:9], v66, off
	v_mul_f32_e32 v66, v71, v41
	v_mul_f32_e32 v55, v55, v41
	v_mul_f32_e32 v41, v54, v41
	s_waitcnt lgkmcnt(0)
	v_pk_add_f32 v[24:25], v[24:25], v[50:51]
	ds_bpermute_b32 v51, v80, v25
	ds_bpermute_b32 v50, v80, v24
	v_mul_f32_e32 v66, v130, v66
	v_mul_f32_e32 v55, v129, v55
	v_cvt_pk_bf16_f32 v66, v66, s0
	v_cvt_pk_bf16_f32 v55, v55, s0
	s_waitcnt lgkmcnt(0)
	v_pk_add_f32 v[24:25], v[24:25], v[50:51]
	v_add_u32_e32 v86, 18, v134
	v_pk_fma_f32 v[50:51], v[24:25], s[28:29], v[32:33] op_sel_hi:[1,0,0]
	global_store_short v[8:9], v66, off offset:64
	v_mul_f32_e32 v24, 0x4b800000, v51
	v_cmp_gt_f32_e32 vcc, s80, v51
	v_mov_b32_e32 v66, v74
	v_add_u32_e32 v74, 19, v134
	v_cndmask_b32_e32 v24, v51, v24, vcc
	v_rsq_f32_e32 v51, v24
	v_add_u32_e32 v24, v97, v191
	v_mad_i64_i32 v[24:25], s[0:1], v24, s77, v[16:17]
	v_mul_f32_e32 v54, 0x45800000, v51
	v_cndmask_b32_e32 v81, v51, v54, vcc
	v_mul_f32_e32 v51, v68, v81
	v_mul_f32_e32 v51, v131, v51
	v_cvt_pk_bf16_f32 v51, v51, s0
	global_store_short v[24:25], v51, off
	v_mul_f32_e32 v51, v69, v81
	v_mul_f32_e32 v51, v130, v51
	v_cvt_pk_bf16_f32 v51, v51, s0
	global_store_short v[24:25], v51, off offset:64
	v_mul_f32_e32 v51, v53, v81
	v_mul_f32_e32 v51, v129, v51
	v_cvt_pk_bf16_f32 v53, v51, s0
	v_mul_f32_e32 v51, 0x4b800000, v50
	v_cmp_gt_f32_e32 vcc, s80, v50
	v_mov_b32_e32 v82, v10
	v_and_or_b32 v10, v74, 63, v187
	v_cndmask_b32_e32 v50, v50, v51, vcc
	v_rsq_f32_e32 v85, v50
	v_and_or_b32 v50, v86, 62, v187
	v_lshlrev_b32_e32 v51, 2, v50
	ds_bpermute_b32 v54, v51, v132
	ds_bpermute_b32 v50, v51, v133
	v_mov_b32_e32 v68, v58
	v_mov_b32_e32 v69, v42
	v_mov_b32_e32 v83, v26
	v_lshlrev_b32_e32 v26, 2, v10
	global_store_short v[8:9], v55, off offset:128
	v_mov_b32_e32 v67, v90
	s_waitcnt lgkmcnt(1)
; DI u16 f2bf(float a) { return (u16)(pk2(a, 0.f) & 0xffffu); }
; DI int crow(int i, int h) { return (i & 3) + 8 * (i >> 2) + 4 * h; }
; __device__ __forceinline__ void attn_item_A(const Params& p, int layer, int head, int q0u, char* lds) {
;     ...
;   for (int e = 0; e < 16; ++e) {
;     const int qq = crow(e, h_e);
;     const float ia = __shfl(iA, qq), ib = __shfl(iB, qq);
;     float ov[4];
;     float ss = 0.f;
; #pragma unroll
;     for (int d = 0; d < 4; ++d) { ov[d] = o1[d][e] * ia - o2[d][e] * ib; ss += ov[d] * ov[d]; }
; #pragma unroll
;     for (int x = 16; x >= 1; x >>= 1) ss += __shfl_xor(ss, x);
;     const float rs = rsqrtf(ss * (1.f / 128.f) + LN_EPS);
;     const size_t rowoff = (size_t)(orow0 + qq) * LDX + ocol + r_e;
; #pragma unroll
;     for (int d = 0; d < 4; ++d) Mx[rowoff + d * 32] = f2bf(ov[d] * rs * sw[d]);
;   }
	v_pk_mul_f32 v[68:69], v[68:69], v[54:55] op_sel_hi:[1,0]
	v_mov_b32_e32 v70, v122
	v_mov_b32_e32 v71, v106
	v_pk_mul_f32 v[54:55], v[82:83], v[54:55] op_sel_hi:[1,0]
	ds_bpermute_b32 v10, v26, v132
	s_waitcnt lgkmcnt(1)
	v_pk_fma_f32 v[66:67], v[66:67], v[50:51], v[68:69] op_sel_hi:[1,0,1] neg_lo:[0,0,1] neg_hi:[0,0,1]
	v_pk_fma_f32 v[50:51], v[70:71], v[50:51], v[54:55] op_sel_hi:[1,0,1] neg_lo:[0,0,1] neg_hi:[0,0,1]
	ds_bpermute_b32 v54, v26, v133
	v_mov_b32_e32 v42, v59
	v_mov_b32_e32 v90, v75
	s_waitcnt lgkmcnt(1)
	v_pk_mul_f32 v[42:43], v[42:43], v[10:11] op_sel_hi:[1,0]
	v_mov_b32_e32 v26, v11
	s_waitcnt lgkmcnt(0)
	v_pk_fma_f32 v[42:43], v[90:91], v[54:55], v[42:43] op_sel_hi:[1,0,1] neg_lo:[0,0,1] neg_hi:[0,0,1]
	v_mov_b32_e32 v106, v123
	v_pk_mul_f32 v[10:11], v[26:27], v[10:11] op_sel_hi:[1,0]
	v_pk_mul_f32 v[68:69], v[66:67], v[66:67]
	v_pk_mul_f32 v[58:59], v[42:43], v[42:43]
	v_pk_fma_f32 v[54:55], v[106:107], v[54:55], v[10:11] op_sel_hi:[1,0,1] neg_lo:[0,0,1] neg_hi:[0,0,1]
	v_pk_mul_f32 v[70:71], v[50:51], v[50:51]
	v_pk_mul_f32 v[10:11], v[54:55], v[54:55]
	v_mov_b32_e32 v26, v58
	v_mov_b32_e32 v27, v68
	v_mov_b32_e32 v68, v59
	v_pk_add_f32 v[26:27], v[26:27], v[68:69]
	v_mov_b32_e32 v58, v11
	v_mov_b32_e32 v59, v71
	v_pk_add_f32 v[26:27], v[58:59], v[26:27]
	v_mov_b32_e32 v11, v70
	v_pk_add_f32 v[10:11], v[10:11], v[26:27]
	ds_bpermute_b32 v27, v48, v11
	ds_bpermute_b32 v26, v48, v10
	v_mul_f32_e32 v75, v52, v81
	v_mul_f32_e32 v52, 0x45800000, v85
	global_store_short v[24:25], v53, off offset:128
	v_cndmask_b32_e32 v58, v85, v52, vcc
	s_waitcnt lgkmcnt(0)
	v_pk_add_f32 v[26:27], v[10:11], v[26:27]
	ds_bpermute_b32 v53, v49, v27
	ds_bpermute_b32 v52, v49, v26
	v_add_u32_e32 v10, v84, v191
	v_mul_f32_e32 v59, v72, v58
	v_mad_i64_i32 v[10:11], s[0:1], v10, s77, v[16:17]
	s_waitcnt lgkmcnt(0)
	v_pk_add_f32 v[26:27], v[26:27], v[52:53]
	ds_bpermute_b32 v53, v64, v27
	ds_bpermute_b32 v52, v64, v26
	v_mul_f32_e32 v59, v131, v59
	v_cvt_pk_bf16_f32 v59, v59, s0
	v_mul_f32_e32 v72, v56, v58
	global_store_short v[10:11], v59, off
	s_waitcnt lgkmcnt(0)
	v_pk_add_f32 v[26:27], v[26:27], v[52:53]
	ds_bpermute_b32 v53, v65, v27
	ds_bpermute_b32 v52, v65, v26
	v_mul_f32_e32 v59, v73, v58
	v_mul_f32_e32 v57, v57, v58
	v_mul_f32_e32 v59, v130, v59
	v_mul_f32_e32 v57, v129, v57
	s_waitcnt lgkmcnt(0)
	v_pk_add_f32 v[26:27], v[26:27], v[52:53]
	ds_bpermute_b32 v53, v80, v27
	ds_bpermute_b32 v52, v80, v26
	v_cvt_pk_bf16_f32 v59, v59, s0
	v_cvt_pk_bf16_f32 v57, v57, s0
	v_add_u32_e32 v82, 24, v134
	v_mov_b32_e32 v70, v12
	s_waitcnt lgkmcnt(0)
	v_pk_add_f32 v[26:27], v[26:27], v[52:53]
	v_mov_b32_e32 v71, v28
	v_pk_fma_f32 v[52:53], v[26:27], s[28:29], v[32:33] op_sel_hi:[1,0,0]
	global_store_short v[10:11], v57, off offset:128
	v_mul_f32_e32 v26, 0x4b800000, v53
	v_cmp_gt_f32_e32 vcc, s80, v53
	global_store_short v[10:11], v59, off offset:64
	v_mov_b32_e32 v58, v76
	v_cndmask_b32_e32 v26, v53, v26, vcc
	v_rsq_f32_e32 v53, v26
	v_add_u32_e32 v26, v86, v191
	v_mad_i64_i32 v[26:27], s[0:1], v26, s77, v[16:17]
	v_mul_f32_e32 v56, 0x45800000, v53
	v_cndmask_b32_e32 v73, v53, v56, vcc
	v_mul_f32_e32 v53, v66, v73
	v_mul_f32_e32 v53, v131, v53
	v_cvt_pk_bf16_f32 v53, v53, s0
	global_store_short v[26:27], v53, off
	v_mul_f32_e32 v53, v67, v73
	v_mul_f32_e32 v53, v130, v53
	v_cvt_pk_bf16_f32 v53, v53, s0
	global_store_short v[26:27], v53, off offset:64
	v_mul_f32_e32 v53, 0x4b800000, v52
	v_cmp_gt_f32_e32 vcc, s80, v52
	v_mov_b32_e32 v66, v60
	v_mov_b32_e32 v67, v44
	v_cndmask_b32_e32 v52, v52, v53, vcc
	v_rsq_f32_e32 v81, v52
	v_and_or_b32 v52, v82, 60, v187
	v_lshlrev_b32_e32 v53, 2, v52
	ds_bpermute_b32 v56, v53, v132
	ds_bpermute_b32 v52, v53, v133
	v_mov_b32_e32 v59, v92
	v_mov_b32_e32 v68, v124
	v_mov_b32_e32 v69, v108
	s_waitcnt lgkmcnt(1)
	v_pk_mul_f32 v[66:67], v[66:67], v[56:57] op_sel_hi:[1,0]
	v_pk_mul_f32 v[56:57], v[70:71], v[56:57] op_sel_hi:[1,0]
	v_add_u32_e32 v70, 25, v134
	v_and_or_b32 v12, v70, 61, v187
	v_lshlrev_b32_e32 v28, 2, v12
	ds_bpermute_b32 v12, v28, v132
	s_waitcnt lgkmcnt(1)
	v_pk_fma_f32 v[58:59], v[58:59], v[52:53], v[66:67] op_sel_hi:[1,0,1] neg_lo:[0,0,1] neg_hi:[0,0,1]
	v_pk_fma_f32 v[52:53], v[68:69], v[52:53], v[56:57] op_sel_hi:[1,0,1] neg_lo:[0,0,1] neg_hi:[0,0,1]
	ds_bpermute_b32 v56, v28, v133
	v_mov_b32_e32 v44, v61
	v_mov_b32_e32 v92, v77
	s_waitcnt lgkmcnt(1)
	v_pk_mul_f32 v[44:45], v[44:45], v[12:13] op_sel_hi:[1,0]
	v_mov_b32_e32 v28, v13
	s_waitcnt lgkmcnt(0)
	v_pk_fma_f32 v[44:45], v[92:93], v[56:57], v[44:45] op_sel_hi:[1,0,1] neg_lo:[0,0,1] neg_hi:[0,0,1]
	v_mov_b32_e32 v108, v125
	v_pk_mul_f32 v[12:13], v[28:29], v[12:13] op_sel_hi:[1,0]
	v_pk_mul_f32 v[66:67], v[58:59], v[58:59]
	v_pk_mul_f32 v[60:61], v[44:45], v[44:45]
	v_pk_fma_f32 v[28:29], v[108:109], v[56:57], v[12:13] op_sel_hi:[1,0,1] neg_lo:[0,0,1] neg_hi:[0,0,1]
	v_pk_mul_f32 v[68:69], v[52:53], v[52:53]
	v_pk_mul_f32 v[12:13], v[28:29], v[28:29]
	v_mov_b32_e32 v56, v60
	v_mov_b32_e32 v57, v66
	v_mov_b32_e32 v66, v61
	v_pk_add_f32 v[56:57], v[56:57], v[66:67]
	v_mov_b32_e32 v60, v13
	v_mov_b32_e32 v61, v69
	v_pk_add_f32 v[56:57], v[60:61], v[56:57]
	v_mov_b32_e32 v13, v68
	v_pk_add_f32 v[12:13], v[12:13], v[56:57]
	ds_bpermute_b32 v57, v48, v13
	ds_bpermute_b32 v56, v48, v12
	v_mul_f32_e32 v51, v51, v73
	v_mul_f32_e32 v51, v129, v51
	v_cvt_pk_bf16_f32 v51, v51, s0
	v_mul_f32_e32 v68, v50, v73
	v_mul_f32_e32 v50, 0x45800000, v81
	global_store_short v[26:27], v51, off offset:128
	v_cndmask_b32_e32 v60, v81, v50, vcc
	s_waitcnt lgkmcnt(0)
; DI u16 f2bf(float a) { return (u16)(pk2(a, 0.f) & 0xffffu); }
; DI int crow(int i, int h) { return (i & 3) + 8 * (i >> 2) + 4 * h; }
; __device__ __forceinline__ void attn_item_A(const Params& p, int layer, int head, int q0u, char* lds) {
;     ...
;   for (int e = 0; e < 16; ++e) {
;     const int qq = crow(e, h_e);
;     const float ia = __shfl(iA, qq), ib = __shfl(iB, qq);
;     float ov[4];
;     float ss = 0.f;
; #pragma unroll
;     for (int d = 0; d < 4; ++d) { ov[d] = o1[d][e] * ia - o2[d][e] * ib; ss += ov[d] * ov[d]; }
; #pragma unroll
;     for (int x = 16; x >= 1; x >>= 1) ss += __shfl_xor(ss, x);
;     const float rs = rsqrtf(ss * (1.f / 128.f) + LN_EPS);
;     const size_t rowoff = (size_t)(orow0 + qq) * LDX + ocol + r_e;
; #pragma unroll
;     for (int d = 0; d < 4; ++d) Mx[rowoff + d * 32] = f2bf(ov[d] * rs * sw[d]);
;   }
	v_pk_add_f32 v[50:51], v[12:13], v[56:57]
	ds_bpermute_b32 v57, v49, v51
	ds_bpermute_b32 v56, v49, v50
	v_add_u32_e32 v12, v74, v191
	v_mul_f32_e32 v42, v42, v60
	v_mad_i64_i32 v[12:13], s[0:1], v12, s77, v[16:17]
	s_waitcnt lgkmcnt(0)
	v_pk_add_f32 v[50:51], v[50:51], v[56:57]
	ds_bpermute_b32 v57, v64, v51
	ds_bpermute_b32 v56, v64, v50
	v_mul_f32_e32 v42, v131, v42
	v_cvt_pk_bf16_f32 v42, v42, s0
	global_store_short v[12:13], v42, off
	v_mul_f32_e32 v61, v43, v60
	s_waitcnt lgkmcnt(0)
	v_pk_add_f32 v[42:43], v[50:51], v[56:57]
	ds_bpermute_b32 v51, v65, v43
	ds_bpermute_b32 v50, v65, v42
	v_mul_f32_e32 v69, v54, v60
	v_mul_f32_e32 v55, v55, v60
	v_mul_f32_e32 v56, v130, v61
	v_mul_f32_e32 v55, v129, v55
	s_waitcnt lgkmcnt(0)
	v_pk_add_f32 v[42:43], v[42:43], v[50:51]
	ds_bpermute_b32 v51, v80, v43
	ds_bpermute_b32 v50, v80, v42
	v_cvt_pk_bf16_f32 v56, v56, s0
	v_cvt_pk_bf16_f32 v55, v55, s0
	global_load_dword v128, v210, s[54:55] offset:384
	v_add_u32_e32 v74, 26, v134
	s_waitcnt lgkmcnt(0)
	v_pk_add_f32 v[42:43], v[42:43], v[50:51]
	v_add_u32_e32 v76, 27, v134
	v_pk_fma_f32 v[42:43], v[42:43], s[28:29], v[32:33] op_sel_hi:[1,0,0]
	v_mov_b32_e32 v66, v14
	v_mul_f32_e32 v50, 0x4b800000, v43
	v_cmp_gt_f32_e32 vcc, s80, v43
	v_mov_b32_e32 v67, v30
	v_and_or_b32 v14, v76, 63, v187
	v_cndmask_b32_e32 v43, v43, v50, vcc
	v_rsq_f32_e32 v43, v43
	v_add_u32_e32 v50, v82, v191
	v_mad_i64_i32 v[50:51], s[0:1], v50, s77, v[16:17]
	v_mul_f32_e32 v54, 0x45800000, v43
	v_cndmask_b32_e32 v71, v43, v54, vcc
	v_mul_f32_e32 v43, v58, v71
	v_mul_f32_e32 v43, v131, v43
	v_cvt_pk_bf16_f32 v43, v43, s0
	global_store_short v[50:51], v43, off
	v_mul_f32_e32 v43, v59, v71
	v_mul_f32_e32 v43, v130, v43
	v_cvt_pk_bf16_f32 v43, v43, s0
	global_store_short v[50:51], v43, off offset:64
	v_mul_f32_e32 v43, v53, v71
	v_mul_f32_e32 v43, v129, v43
	v_cvt_pk_bf16_f32 v53, v43, s0
	v_mul_f32_e32 v43, 0x4b800000, v42
	v_cmp_gt_f32_e32 vcc, s80, v42
	v_mov_b32_e32 v58, v62
	v_mov_b32_e32 v59, v46
	v_cndmask_b32_e32 v42, v42, v43, vcc
	v_rsq_f32_e32 v73, v42
	v_and_or_b32 v42, v74, 62, v187
	v_lshlrev_b32_e32 v43, 2, v42
	ds_bpermute_b32 v54, v43, v132
	ds_bpermute_b32 v42, v43, v133
	global_store_short v[12:13], v56, off offset:64
	global_store_short v[12:13], v55, off offset:128
	v_mov_b32_e32 v56, v78
	v_mov_b32_e32 v57, v94
	s_waitcnt lgkmcnt(1)
	v_pk_mul_f32 v[58:59], v[58:59], v[54:55] op_sel_hi:[1,0]
	v_mov_b32_e32 v60, v126
	v_mov_b32_e32 v61, v110
	v_pk_mul_f32 v[54:55], v[66:67], v[54:55] op_sel_hi:[1,0]
	v_lshlrev_b32_e32 v14, 2, v14
	s_waitcnt lgkmcnt(0)
	v_pk_fma_f32 v[56:57], v[56:57], v[42:43], v[58:59] op_sel_hi:[1,0,1] neg_lo:[0,0,1] neg_hi:[0,0,1]
	v_pk_fma_f32 v[42:43], v[60:61], v[42:43], v[54:55] op_sel_hi:[1,0,1] neg_lo:[0,0,1] neg_hi:[0,0,1]
	ds_bpermute_b32 v55, v14, v132
	ds_bpermute_b32 v54, v14, v133
	v_mov_b32_e32 v46, v63
	v_mov_b32_e32 v94, v79
	v_pk_mul_f32 v[58:59], v[56:57], v[56:57]
	s_waitcnt lgkmcnt(1)
	v_mov_b32_e32 v14, v55
	v_pk_mul_f32 v[46:47], v[46:47], v[14:15] op_sel_hi:[1,0]
	v_mov_b32_e32 v14, v127
	s_waitcnt lgkmcnt(0)
	v_pk_mul_f32 v[14:15], v[14:15], v[54:55]
	v_pk_fma_f32 v[46:47], v[94:95], v[54:55], v[46:47] op_sel_hi:[1,0,1] neg_lo:[0,0,1] neg_hi:[0,0,1]
	v_mul_f32_e32 v67, v111, v54
	v_mul_f32_e32 v31, v31, v55
	v_mov_b32_e32 v66, v14
	v_mov_b32_e32 v30, v15
	v_pk_mul_f32 v[62:63], v[46:47], v[46:47]
	v_pk_add_f32 v[14:15], v[66:67], v[30:31] neg_lo:[0,1] neg_hi:[0,1]
	v_pk_mul_f32 v[60:61], v[42:43], v[42:43]
	v_pk_mul_f32 v[30:31], v[14:15], v[14:15]
	v_mov_b32_e32 v54, v62
	v_mov_b32_e32 v55, v58
	v_mov_b32_e32 v58, v63
	v_pk_add_f32 v[54:55], v[54:55], v[58:59]
	v_mov_b32_e32 v58, v31
	v_mov_b32_e32 v59, v61
	v_pk_add_f32 v[54:55], v[58:59], v[54:55]
	v_mov_b32_e32 v31, v60
	v_pk_add_f32 v[30:31], v[30:31], v[54:55]
	ds_bpermute_b32 v55, v48, v31
	ds_bpermute_b32 v54, v48, v30
	global_store_short v[50:51], v53, off offset:128
	v_mul_f32_e32 v58, v52, v71
	v_mul_f32_e32 v48, 0x45800000, v73
	v_cndmask_b32_e32 v59, v73, v48, vcc
	s_waitcnt lgkmcnt(0)
	v_pk_add_f32 v[30:31], v[30:31], v[54:55]
	ds_bpermute_b32 v53, v49, v31
	ds_bpermute_b32 v52, v49, v30
	v_add_u32_e32 v48, v70, v191
	v_mul_f32_e32 v44, v44, v59
	v_mad_i64_i32 v[48:49], s[0:1], v48, s77, v[16:17]
	s_waitcnt lgkmcnt(0)
; DI u16 f2bf(float a) { return (u16)(pk2(a, 0.f) & 0xffffu); }
; DI int crow(int i, int h) { return (i & 3) + 8 * (i >> 2) + 4 * h; }
; __device__ __forceinline__ void attn_item_A(const Params& p, int layer, int head, int q0u, char* lds) {
;     ...
;   for (int e = 0; e < 16; ++e) {
;     const int qq = crow(e, h_e);
;     const float ia = __shfl(iA, qq), ib = __shfl(iB, qq);
;     float ov[4];
;     float ss = 0.f;
; #pragma unroll
;     for (int d = 0; d < 4; ++d) { ov[d] = o1[d][e] * ia - o2[d][e] * ib; ss += ov[d] * ov[d]; }
; #pragma unroll
;     for (int x = 16; x >= 1; x >>= 1) ss += __shfl_xor(ss, x);
;     const float rs = rsqrtf(ss * (1.f / 128.f) + LN_EPS);
;     const size_t rowoff = (size_t)(orow0 + qq) * LDX + ocol + r_e;
; #pragma unroll
;     for (int d = 0; d < 4; ++d) Mx[rowoff + d * 32] = f2bf(ov[d] * rs * sw[d]);
;   }
	v_pk_add_f32 v[30:31], v[30:31], v[52:53]
	ds_bpermute_b32 v53, v64, v31
	ds_bpermute_b32 v52, v64, v30
	v_mul_f32_e32 v44, v131, v44
	v_cvt_pk_bf16_f32 v44, v44, s0
	global_store_short v[48:49], v44, off
	v_mul_f32_e32 v54, v45, v59
	s_waitcnt lgkmcnt(0)
	v_pk_add_f32 v[30:31], v[30:31], v[52:53]
	ds_bpermute_b32 v45, v65, v31
	ds_bpermute_b32 v44, v65, v30
	v_mul_f32_e32 v29, v29, v59
	v_mul_f32_e32 v52, v130, v54
	v_mul_f32_e32 v29, v129, v29
	v_cvt_pk_bf16_f32 v52, v52, s0
	s_waitcnt lgkmcnt(0)
	v_pk_add_f32 v[30:31], v[30:31], v[44:45]
	ds_bpermute_b32 v45, v80, v31
	ds_bpermute_b32 v44, v80, v30
	v_cvt_pk_bf16_f32 v29, v29, s0
	global_store_short v[48:49], v52, off offset:64
	global_store_short v[48:49], v29, off offset:128
	v_mul_f32_e32 v52, v28, v59
	s_waitcnt lgkmcnt(0)
	v_pk_add_f32 v[28:29], v[30:31], v[44:45]
	s_nop 0
	v_pk_fma_f32 v[28:29], v[28:29], s[28:29], v[32:33] op_sel_hi:[1,0,0]
	s_nop 0
	v_mul_f32_e32 v30, 0x4b800000, v29
	v_cmp_gt_f32_e32 vcc, s80, v29
	v_mul_f32_e32 v33, 0x4b800000, v28
	s_nop 0
	v_cndmask_b32_e32 v29, v29, v30, vcc
	v_rsq_f32_e32 v29, v29
	v_add_u32_e32 v30, v74, v191
	v_mad_i64_i32 v[30:31], s[0:1], v30, s77, v[16:17]
	v_mul_f32_e32 v32, 0x45800000, v29
	v_cndmask_b32_e32 v29, v29, v32, vcc
	v_mul_f32_e32 v32, v56, v29
	v_mul_f32_e32 v32, v131, v32
	v_cvt_pk_bf16_f32 v32, v32, s0
	global_store_short v[30:31], v32, off
	v_mul_f32_e32 v32, v57, v29
	v_cmp_gt_f32_e32 vcc, s80, v28
	v_mul_f32_e32 v32, v130, v32
	v_cvt_pk_bf16_f32 v32, v32, s0
	v_cndmask_b32_e32 v28, v28, v33, vcc
	v_rsq_f32_e32 v28, v28
	global_store_short v[30:31], v32, off offset:64
	v_mul_f32_e32 v32, v43, v29
	v_mul_f32_e32 v32, v129, v32
	v_cvt_pk_bf16_f32 v32, v32, s0
	global_store_short v[30:31], v32, off offset:128
	v_mul_f32_e32 v32, 0x45800000, v28
	v_cndmask_b32_e32 v167, v28, v32, vcc
	v_add_u32_e32 v28, v76, v191
	v_mad_i64_i32 v[16:17], s[0:1], v28, s77, v[16:17]
	v_mul_f32_e32 v28, v46, v167
	v_mul_f32_e32 v28, v131, v28
	v_cvt_pk_bf16_f32 v28, v28, s0
	v_mul_f32_e32 v15, v15, v167
	global_store_short v[16:17], v28, off
	v_mul_f32_e32 v28, v47, v167
	v_mul_f32_e32 v15, v129, v15
	v_mul_f32_e32 v28, v130, v28
	v_cvt_pk_bf16_f32 v15, v15, s0
	v_mov_b32_e32 v129, v14
	v_cvt_pk_bf16_f32 v28, v28, s0
	global_store_short v[16:17], v15, off offset:128
	s_waitcnt vmcnt(13)
	v_pk_mul_f32 v[14:15], v[128:129], v[166:167]
	global_store_short v[16:17], v28, off offset:64
	v_mul_f32_e32 v28, v14, v34
	v_cvt_pk_bf16_f32 v28, v28, s0
	global_store_short v[0:1], v28, off offset:192
	v_mul_f32_e32 v0, v14, v35
	v_cvt_pk_bf16_f32 v0, v0, s0
	global_store_short v[2:3], v0, off offset:192
	v_mul_f32_e32 v0, v14, v36
	v_cvt_pk_bf16_f32 v0, v0, s0
	global_store_short v[18:19], v0, off offset:192
	v_mul_f32_e32 v0, v14, v37
	v_cvt_pk_bf16_f32 v0, v0, s0
	global_store_short v[4:5], v0, off offset:192
	v_mul_f32_e32 v0, v14, v38
	v_cvt_pk_bf16_f32 v0, v0, s0
	global_store_short v[20:21], v0, off offset:192
	v_mul_f32_e32 v0, v14, v39
	v_cvt_pk_bf16_f32 v0, v0, s0
	global_store_short v[6:7], v0, off offset:192
	v_mul_f32_e32 v0, v14, v40
	v_cvt_pk_bf16_f32 v0, v0, s0
	global_store_short v[22:23], v0, off offset:192
	v_mul_f32_e32 v0, v14, v41
	v_cvt_pk_bf16_f32 v0, v0, s0
	global_store_short v[8:9], v0, off offset:192
	v_mul_f32_e32 v0, v14, v75
	v_cvt_pk_bf16_f32 v0, v0, s0
	global_store_short v[24:25], v0, off offset:192
	v_mul_f32_e32 v0, v14, v72
	v_cvt_pk_bf16_f32 v0, v0, s0
	global_store_short v[10:11], v0, off offset:192
	v_mul_f32_e32 v0, v14, v68
	v_cvt_pk_bf16_f32 v0, v0, s0
	global_store_short v[26:27], v0, off offset:192
	v_mul_f32_e32 v0, v14, v69
	v_cvt_pk_bf16_f32 v0, v0, s0
	global_store_short v[12:13], v0, off offset:192
	v_mul_f32_e32 v0, v14, v58
	v_cvt_pk_bf16_f32 v0, v0, s0
	global_store_short v[50:51], v0, off offset:192
	v_mul_f32_e32 v0, v14, v52
	v_mul_f32_e32 v29, v42, v29
	v_cvt_pk_bf16_f32 v0, v0, s0
	global_store_short v[48:49], v0, off offset:192
	v_mul_f32_e32 v0, v14, v29
	v_cvt_pk_bf16_f32 v0, v0, s0
	global_store_short v[30:31], v0, off offset:192
	v_mul_f32_e32 v0, v14, v15
	s_branch .LBB0_1476

; DI float bflo(unsigned u) { return __uint_as_float(u << 16); }
; DI float bfhi(unsigned u) { return __uint_as_float(u & 0xffff0000u); }
; DI int TID() { int t = threadIdx.x; asm volatile("" : "+v"(t)); return t; }
; __device__ __forceinline__ void attn_item_A(const Params& p, int layer, int head, int q0u, char* lds) {
;   const int tid = TID(), wid = tid >> 6, lane = tid & 63, r = lane & 31, h = lane >> 5;
;   u16* Ks = (u16*)lds;
;   u16* Vt = (u16*)(lds + LDS_K);
;   char* Qs = lds + LDS_Q + wid * 8192 + lane * 16;
;   const u16* P = (const u16*)(p.ws + OFF_P);
;   const bool ctxq = q0u < NCTX;
;   const int qcol = head * 128, kcol = 512 + head * 128, vcol = 1024 + head * 128, ocol = head * 128;
;   const float CS = 0.125f * LOG2E;
;   const int lo = 0, hi = ctxq ? 0 : SEQ;
;   const int ntiles = 8 + ((hi - lo) >> 5);
;   float bA, bB;
;   {
;     const u16* qg = P + (size_t)(q0u + wid * 32 + r) * LDP + qcol + 8 * h;
;     float nA = 0.f, nB = 0.f;
; #pragma unroll
;     for (int s = 0; s < 8; ++s) {
;       const u32x4 q = *(const u32x4*)(qg + 16 * s);
;       *(u32x4*)(Qs + s * 1024) = q;
;       float ss = 0.f;
; #pragma unroll
;       for (int j = 0; j < 4; ++j) { const float a = bflo(q[j]), b = bfhi(q[j]); ss += a * a + b * b; }
;       if (s < 4) nA += ss; else nB += ss;
;     }
;     nA += __shfl_xor(nA, 32); nB += __shfl_xor(nB, 32);
;     const float* km = (const float*)(p.ws + OFF_LAM) + 8 + layer * 24 + head * 2;
;     bA = sqrtf(nA) * km[0] * CS; bB = sqrtf(nB) * km[1] * CS;
;   }
.LBB0_2326:
	v_mov_b32_e32 v36, v211
	s_lshl_b32 s0, s48, 7
	v_ashrrev_i32_e32 v2, 6, v36
	v_and_b32_e32 v16, 31, v36
	v_lshl_add_u32 v190, v2, 5, s82
	v_or_b32_e32 v0, v190, v16
	v_mov_b64_e32 v[12:13], s[14:15]
	v_mad_i64_i32 v[0:1], s[4:5], v0, s68, v[12:13]
	s_ashr_i32 s1, s0, 31
	v_lshrrev_b32_e32 v3, 2, v36
	s_lshl_b64 s[4:5], s[0:1], 1
	v_and_b32_e32 v17, 8, v3
	v_lshl_add_u64 v[0:1], v[0:1], 0, s[4:5]
	v_lshlrev_b32_e32 v164, 1, v17
	v_lshl_add_u64 v[14:15], v[0:1], 0, v[164:165]
	global_load_dwordx4 v[18:21], v[14:15], off
	global_load_dwordx4 v[22:25], v[14:15], off offset:32
	global_load_dwordx4 v[26:29], v[14:15], off offset:64
	global_load_dwordx4 v[30:33], v[14:15], off offset:96
	v_lshlrev_b32_e32 v192, 13, v2
	global_load_dwordx4 v[0:3], v[14:15], off offset:128
	global_load_dwordx4 v[4:7], v[14:15], off offset:160
	global_load_dwordx4 v[8:11], v[14:15], off offset:192
	v_and_b32_e32 v167, 63, v36
	v_lshlrev_b32_e32 v193, 4, v167
	v_or_b32_e32 v40, v192, v193
	s_lshl_b32 s6, s48, 1
	s_ashr_i32 s7, s6, 31
	s_lshl_b64 s[6:7], s[6:7], 2
	s_add_u32 s6, s21, s6
	s_addc_u32 s7, s31, s7
	v_ashrrev_i32_e32 v194, 3, v36
	v_cmp_lt_i32_e32 vcc, v185, v187
	s_mov_b32 s8, 0
	v_mad_u32_u24 v195, v16, s71, v164
	s_waitcnt vmcnt(6)
	ds_write_b128 v40, v[18:21] offset:37888
	v_lshlrev_b32_e32 v34, 16, v18
	v_and_b32_e32 v18, 0xffff0000, v18
	v_lshlrev_b32_e32 v35, 16, v19
	v_and_b32_e32 v19, 0xffff0000, v19
	s_waitcnt vmcnt(5)
	ds_write_b128 v40, v[22:25] offset:38912
	v_lshlrev_b32_e32 v39, 16, v22
	v_and_b32_e32 v22, 0xffff0000, v22
	v_lshlrev_b32_e32 v41, 16, v23
	v_and_b32_e32 v23, 0xffff0000, v23
	v_lshlrev_b32_e32 v37, 16, v20
	v_and_b32_e32 v20, 0xffff0000, v20
	v_lshlrev_b32_e32 v42, 16, v24
	v_and_b32_e32 v24, 0xffff0000, v24
	v_mul_f32_e32 v18, v18, v18
	v_mul_f32_e32 v19, v19, v19
	v_mul_f32_e32 v22, v22, v22
	v_mul_f32_e32 v23, v23, v23
	v_lshlrev_b32_e32 v38, 16, v21
	v_and_b32_e32 v21, 0xffff0000, v21
	v_lshlrev_b32_e32 v43, 16, v25
	v_and_b32_e32 v25, 0xffff0000, v25
	s_waitcnt vmcnt(4)
	ds_write_b128 v40, v[26:29] offset:39936
	v_lshlrev_b32_e32 v44, 16, v26
	v_and_b32_e32 v26, 0xffff0000, v26
	v_lshlrev_b32_e32 v45, 16, v27
	v_and_b32_e32 v27, 0xffff0000, v27
	v_mul_f32_e32 v20, v20, v20
	v_mul_f32_e32 v24, v24, v24
	v_fmac_f32_e32 v18, v34, v34
	v_fmac_f32_e32 v19, v35, v35
	v_fmac_f32_e32 v22, v39, v39
	v_fmac_f32_e32 v23, v41, v41
	v_lshlrev_b32_e32 v46, 16, v28
	v_and_b32_e32 v28, 0xffff0000, v28
	v_mul_f32_e32 v21, v21, v21
	v_mul_f32_e32 v25, v25, v25
	v_mul_f32_e32 v26, v26, v26
	v_mul_f32_e32 v27, v27, v27
	v_fmac_f32_e32 v20, v37, v37
	v_fmac_f32_e32 v24, v42, v42
	v_add_f32_e32 v18, v18, v19
	v_add_f32_e32 v19, v22, v23
	v_lshlrev_b32_e32 v47, 16, v29
	v_and_b32_e32 v29, 0xffff0000, v29
	v_mul_f32_e32 v28, v28, v28
	v_fmac_f32_e32 v21, v38, v38
	v_fmac_f32_e32 v25, v43, v43
	v_fmac_f32_e32 v26, v44, v44
	v_fmac_f32_e32 v27, v45, v45
	v_add_f32_e32 v18, v20, v18
	v_add_f32_e32 v19, v24, v19
	v_mul_f32_e32 v29, v29, v29
	v_fmac_f32_e32 v28, v46, v46
	v_add_f32_e32 v22, v26, v27
	v_add_f32_e32 v18, v21, v18
	v_add_f32_e32 v19, v25, v19
	s_waitcnt vmcnt(3)
	ds_write_b128 v40, v[30:33] offset:40960
	v_lshlrev_b32_e32 v48, 16, v30
	v_and_b32_e32 v30, 0xffff0000, v30
	v_fmac_f32_e32 v29, v47, v47
	v_add_f32_e32 v20, v28, v22
	v_add_f32_e32 v18, v18, v19
	v_and_b32_e32 v19, 0xffff0000, v31
	v_lshlrev_b32_e32 v49, 16, v31
	v_mul_f32_e32 v30, v30, v30
	v_add_f32_e32 v20, v29, v20
	v_mul_f32_e32 v19, v19, v19
	v_and_b32_e32 v21, 0xffff0000, v32
	v_fmac_f32_e32 v30, v48, v48
	v_add_f32_e32 v18, v18, v20
	v_fmac_f32_e32 v19, v49, v49
	v_lshlrev_b32_e32 v20, 16, v32
	v_mul_f32_e32 v21, v21, v21
	v_add_f32_e32 v19, v30, v19
	v_fmac_f32_e32 v21, v20, v20
	v_add_f32_e32 v19, v21, v19
	v_and_b32_e32 v21, 0xffff0000, v33
	v_lshlrev_b32_e32 v20, 16, v33
	v_mul_f32_e32 v21, v21, v21
	v_fmac_f32_e32 v21, v20, v20
	v_add_f32_e32 v19, v21, v19
	v_add_f32_e32 v41, v18, v19
	s_waitcnt vmcnt(2)
	v_and_b32_e32 v19, 0xffff0000, v0
	v_lshlrev_b32_e32 v18, 16, v0
	v_mul_f32_e32 v22, v19, v19
	v_fmac_f32_e32 v22, v18, v18
	global_load_dwordx4 v[18:21], v[14:15], off offset:224
	global_load_dwordx2 v[34:35], v165, s[6:7]
	v_and_b32_e32 v24, 0xffff0000, v1
	v_lshlrev_b32_e32 v23, 16, v1
	v_mul_f32_e32 v14, v24, v24
	v_fmac_f32_e32 v14, v23, v23
	v_add_f32_e32 v14, v22, v14
	v_and_b32_e32 v22, 0xffff0000, v2
	v_lshlrev_b32_e32 v15, 16, v2
	v_mul_f32_e32 v22, v22, v22
	v_fmac_f32_e32 v22, v15, v15
	v_add_f32_e32 v14, v22, v14
	v_and_b32_e32 v22, 0xffff0000, v3
	v_lshlrev_b32_e32 v15, 16, v3
	v_mul_f32_e32 v22, v22, v22
	v_fmac_f32_e32 v22, v15, v15
	v_add_f32_e32 v14, v22, v14
	s_waitcnt vmcnt(3)
	v_and_b32_e32 v22, 0xffff0000, v4
	v_lshlrev_b32_e32 v15, 16, v4
	v_mul_f32_e32 v22, v22, v22
	v_and_b32_e32 v23, 0xffff0000, v5
	v_fmac_f32_e32 v22, v15, v15
	v_lshlrev_b32_e32 v15, 16, v5
	v_mul_f32_e32 v23, v23, v23
	v_fmac_f32_e32 v23, v15, v15
	v_add_f32_e32 v15, v22, v23
	v_and_b32_e32 v23, 0xffff0000, v6
	v_lshlrev_b32_e32 v22, 16, v6
	v_mul_f32_e32 v23, v23, v23
	v_fmac_f32_e32 v23, v22, v22
	v_add_f32_e32 v15, v23, v15
	v_and_b32_e32 v23, 0xffff0000, v7
	v_lshlrev_b32_e32 v22, 16, v7
	v_mul_f32_e32 v23, v23, v23
	v_fmac_f32_e32 v23, v22, v22
	v_add_f32_e32 v15, v23, v15
	v_add_f32_e32 v42, v14, v15
	s_waitcnt vmcnt(2)
; __device__ __forceinline__ void attn_item_A(const Params& p, int layer, int head, int q0u, char* lds) {
;     ...
;     nA += __shfl_xor(nA, 32); nB += __shfl_xor(nB, 32);
;     const float* km = (const float*)(p.ws + OFF_LAM) + 8 + layer * 24 + head * 2;
;     bA = sqrtf(nA) * km[0] * CS; bB = sqrtf(nB) * km[1] * CS;
;   }
;   const int srow = tid >> 3, sseg = (tid & 7) * 16;
;   const u16* VTg = (const u16*)(p.ws + OFF_VT) + (size_t)(head * 128 + (tid >> 1)) * LDVT + (tid & 1) * 16;
;   float lA = 0.f, lB = 0.f;
;   f32x16 o1[4], o2[4];
; #pragma unroll
;   for (int d = 0; d < 4; ++d)
; #pragma unroll
;     for (int e = 0; e < 16; ++e) { o1[d][e] = 0.f; o2[d][e] = 0.f; }
;   u32x4 rk0, rk1, rv0, rv1;
;   const u16* gnext;
;   ATT_LOADK(0); ATT_LOADV(0);
;   ATT_STOREK(0); ATT_STOREV(0);
;   __syncthreads();
	v_and_b32_e32 v15, 0xffff0000, v8
	v_lshlrev_b32_e32 v14, 16, v8
	v_mul_f32_e32 v15, v15, v15
	v_and_b32_e32 v22, 0xffff0000, v9
	v_fmac_f32_e32 v15, v14, v14
	v_lshlrev_b32_e32 v14, 16, v9
	v_mul_f32_e32 v22, v22, v22
	v_fmac_f32_e32 v22, v14, v14
	v_add_f32_e32 v14, v15, v22
	v_and_b32_e32 v22, 0xffff0000, v10
	v_lshlrev_b32_e32 v15, 16, v10
	v_mul_f32_e32 v22, v22, v22
	v_fmac_f32_e32 v22, v15, v15
	v_ashrrev_i32_e32 v46, 1, v36
	v_lshlrev_b32_e32 v28, 5, v36
	v_add_f32_e32 v43, v22, v14
	v_add_u32_e32 v22, s0, v46
	v_mov_b64_e32 v[14:15], s[16:17]
	v_mad_i64_i32 v[12:13], s[0:1], v194, s68, v[12:13]
	v_and_b32_e32 v36, 0xe0, v28
	v_mov_b32_e32 v37, v165
	v_mad_i64_i32 v[26:27], s[0:1], v22, s70, v[14:15]
	v_lshl_add_u64 v[12:13], v[12:13], 0, v[36:37]
	v_and_b32_e32 v38, 32, v28
	v_mov_b32_e32 v39, v165
	v_lshl_add_u64 v[22:23], v[12:13], 0, s[4:5]
	v_lshl_add_u64 v[170:171], v[26:27], 0, v[38:39]
	global_load_dwordx4 v[12:15], v[22:23], off offset:1040
	s_nop 0
	global_load_dwordx4 v[22:25], v[22:23], off offset:1024
	s_nop 0
	global_load_dwordx4 v[26:29], v[170:171], off offset:16
	global_load_dwordx4 v[30:33], v[170:171], off
	v_and_b32_e32 v45, 0xffff0000, v11
	v_lshlrev_b32_e32 v44, 16, v11
	v_mul_f32_e32 v39, v45, v45
	v_fmac_f32_e32 v39, v44, v44
	v_add_f32_e32 v39, v39, v43
	v_add_f32_e32 v39, v42, v39
	ds_write_b128 v40, v[0:3] offset:41984
	ds_write_b128 v40, v[4:7] offset:43008
	ds_write_b128 v40, v[8:11] offset:44032
	s_waitcnt vmcnt(5)
	ds_write_b128 v40, v[18:21] offset:45056
	s_mov_b32 s6, 32
	v_and_b32_e32 v43, 0xffff0000, v18
	v_lshlrev_b32_e32 v42, 16, v18
	v_mul_f32_e32 v43, v43, v43
	v_and_b32_e32 v44, 0xffff0000, v19
	v_fmac_f32_e32 v43, v42, v42
	v_lshlrev_b32_e32 v42, 16, v19
	v_mul_f32_e32 v44, v44, v44
	v_fmac_f32_e32 v44, v42, v42
	v_add_f32_e32 v42, v43, v44
	v_and_b32_e32 v44, 0xffff0000, v20
	v_lshlrev_b32_e32 v43, 16, v20
	v_mul_f32_e32 v44, v44, v44
	v_fmac_f32_e32 v44, v43, v43
	v_add_f32_e32 v42, v44, v42
	v_and_b32_e32 v44, 0xffff0000, v21
	v_lshlrev_b32_e32 v43, 16, v21
	v_mul_f32_e32 v44, v44, v44
	v_fmac_f32_e32 v44, v43, v43
	v_add_f32_e32 v42, v44, v42
	v_add_f32_e32 v39, v39, v42
	v_cndmask_b32_e32 v42, v214, v185, vcc
	v_lshlrev_b32_e32 v191, 2, v42
	ds_bpermute_b32 v42, v191, v39
	ds_bpermute_b32 v3, v191, v41
	s_waitcnt lgkmcnt(1)
	v_add_f32_e32 v0, v39, v42
	v_mul_f32_e32 v1, 0x4f800000, v0
	v_cmp_gt_f32_e32 vcc, s69, v0
	s_waitcnt lgkmcnt(0)
	v_add_f32_e32 v3, v41, v3
	v_cndmask_b32_e32 v1, v0, v1, vcc
	v_sqrt_f32_e32 v2, v1
	v_mov_b32_e32 v0, 0
	v_mov_b32_e32 v6, v0
	v_mov_b32_e32 v7, v0
	v_add_u32_e32 v4, -1, v2
	v_fma_f32 v5, -v4, v2, v1
	v_cmp_ge_f32_e64 s[0:1], 0, v5
	v_add_u32_e32 v5, 1, v2
	v_mov_b32_e32 v8, v0
	v_cndmask_b32_e64 v4, v2, v4, s[0:1]
	v_fma_f32 v2, -v5, v2, v1
	v_cmp_lt_f32_e64 s[0:1], 0, v2
	v_mov_b32_e32 v9, v0
	v_mov_b32_e32 v10, v0
	v_cndmask_b32_e64 v2, v4, v5, s[0:1]
	v_mul_f32_e32 v4, 0x37800000, v2
	v_cndmask_b32_e32 v2, v2, v4, vcc
	v_mul_f32_e32 v4, 0x4f800000, v3
	v_cmp_gt_f32_e32 vcc, s69, v3
	v_cmp_class_f32_e64 s[0:1], v1, v182
	v_mov_b32_e32 v11, v0
	v_cndmask_b32_e32 v3, v3, v4, vcc
	v_sqrt_f32_e32 v4, v3
	v_cndmask_b32_e64 v1, v2, v1, s[0:1]
	s_waitcnt vmcnt(4)
	v_mul_f32_e32 v1, v35, v1
	v_mov_b32_e32 v18, v0
	v_add_u32_e32 v2, -1, v4
	v_fma_f32 v5, -v2, v4, v3
	v_cmp_ge_f32_e64 s[0:1], 0, v5
	v_add_u32_e32 v5, 1, v4
	v_mov_b32_e32 v19, v0
	v_cndmask_b32_e64 v2, v4, v2, s[0:1]
	v_fma_f32 v4, -v5, v4, v3
	v_cmp_lt_f32_e64 s[0:1], 0, v4
	v_mov_b32_e32 v20, v0
	v_mov_b32_e32 v21, v0
	v_cndmask_b32_e64 v2, v2, v5, s[0:1]
	v_mul_f32_e32 v4, 0x37800000, v2
	v_cndmask_b32_e32 v2, v2, v4, vcc
	v_cmp_class_f32_e32 vcc, v3, v182
	v_mad_u64_u32 v[174:175], s[0:1], v46, s72, v[38:39]
	s_nop 0
	v_cndmask_b32_e32 v2, v2, v3, vcc
	v_mul_f32_e32 v4, v34, v2
	v_mad_u64_u32 v[172:173], s[0:1], v194, s71, v[36:37]
	v_add_u32_e32 v2, 0x4400, v174
	s_waitcnt vmcnt(2)
	ds_write_b128 v172, v[22:25]
	ds_write_b128 v172, v[12:15] offset:16
	s_waitcnt vmcnt(0)
	ds_write2_b64 v2, v[30:31], v[32:33] offset1:1
	v_add_u32_e32 v2, 0x4410, v174
	ds_write2_b64 v2, v[26:27], v[28:29] offset1:1
	v_lshl_add_u64 v[2:3], s[14:15], 0, v[36:37]
	v_lshl_add_u64 v[176:177], v[2:3], 0, s[4:5]
	v_mul_u32_u24_e32 v2, 0x110, v16
	v_mul_f32_e32 v173, 0xbe38aa3b, v1
	v_mul_i32_i24_e32 v1, 0xffffff38, v16
	v_mul_f32_e32 v175, 0xbe38aa3b, v4
	v_add3_u32 v164, v2, v1, v17
	v_mov_b32_e32 v1, v0
	v_mov_b32_e32 v2, v0
	v_mov_b32_e32 v3, v0
	v_mov_b32_e32 v4, v0
	v_mov_b32_e32 v5, v0
	v_mov_b32_e32 v12, v0
	v_mov_b32_e32 v13, v0
	v_mov_b32_e32 v14, v0
	v_mov_b32_e32 v15, v0
	v_mov_b32_e32 v16, v0
	v_mov_b32_e32 v17, v0
	v_mov_b32_e32 v22, v0
	v_mov_b32_e32 v23, v0
	v_mov_b32_e32 v24, v0
	v_mov_b32_e32 v25, v0
	v_mov_b32_e32 v26, v0
	v_mov_b32_e32 v27, v0
	v_mov_b32_e32 v28, v0
	v_mov_b32_e32 v29, v0
	v_mov_b32_e32 v30, v0
	v_mov_b32_e32 v31, v0
	v_mov_b32_e32 v32, v0
	v_mov_b32_e32 v33, v0
	v_mov_b32_e32 v34, v0
	v_mov_b32_e32 v35, v0
	v_mov_b32_e32 v36, v0
	v_mov_b32_e32 v37, v0
	v_mov_b32_e32 v38, v0
	v_mov_b32_e32 v39, v0
	v_mov_b32_e32 v40, v0
	v_mov_b32_e32 v41, v0
	v_mov_b32_e32 v42, v0
	v_mov_b32_e32 v43, v0
	v_mov_b32_e32 v44, v0
	v_mov_b32_e32 v45, v0
	v_mov_b32_e32 v46, v0
	v_mov_b32_e32 v47, v0
	v_mov_b32_e32 v48, v0
	v_mov_b32_e32 v49, v0
	v_mov_b32_e32 v50, v0
	v_mov_b32_e32 v51, v0
	v_mov_b32_e32 v52, v0
	v_mov_b32_e32 v53, v0
	v_mov_b32_e32 v54, v0
	v_mov_b32_e32 v55, v0
	v_mov_b32_e32 v56, v0
	v_mov_b32_e32 v57, v0
	v_mov_b32_e32 v58, v0
	v_mov_b32_e32 v59, v0
	v_mov_b32_e32 v60, v0
	v_mov_b32_e32 v61, v0
	v_mov_b32_e32 v62, v0
	v_mov_b32_e32 v63, v0
	v_mov_b32_e32 v64, v0
; #define MFMA32(a, b, c) __builtin_amdgcn_mfma_f32_32x32x16_bf16((a), (b), (c), 0, 0, 0)
; __device__ __forceinline__ void attn_item_A(const Params& p, int layer, int head, int q0u, char* lds) {
;     ...
;   f32x16 o1[4], o2[4];
; #pragma unroll
;   for (int d = 0; d < 4; ++d)
; #pragma unroll
;     for (int e = 0; e < 16; ++e) { o1[d][e] = 0.f; o2[d][e] = 0.f; }
;   u32x4 rk0, rk1, rv0, rv1;
;   const u16* gnext;
;   ATT_LOADK(0); ATT_LOADV(0);
;   ATT_STOREK(0); ATT_STOREV(0);
;   __syncthreads();
;   for (int t = 0; t < ntiles; ++t) {
;     const int buf = t & 1;
;     const bool more = (t + 1 < ntiles);
;     if (more) { ATT_LOADK(t + 1); ATT_LOADV(t + 1); }
;     const u16* kt_ = Ks + buf * 32 * KLD + r * KLD + 8 * h;
;     bf16x8 a0, a1, b0, b1;
;     {
;       f32x16 sx, sy;
; #pragma unroll
;       for (int e = 0; e < 16; ++e) { sx[e] = 0.f; sy[e] = 0.f; }
; #pragma unroll
;       for (int s = 0; s < 4; ++s) {
;         const bf16x8 kf = *(const bf16x8*)(kt_ + 16 * s);
;         const bf16x8 qf = *(const bf16x8*)(Qs + s * 1024);
;         sx = MFMA32(kf, qf, sx);
;       }
; #pragma unroll
;       for (int s = 4; s < 8; ++s) {
;         const bf16x8 kf = *(const bf16x8*)(kt_ + 16 * s);
;         const bf16x8 qf = *(const bf16x8*)(Qs + s * 1024);
;         sy = MFMA32(kf, qf, sy);
;       }
	v_mov_b32_e32 v65, v0
	v_mov_b32_e32 v66, v0
	v_mov_b32_e32 v67, v0
	v_mov_b32_e32 v68, v0
	v_mov_b32_e32 v69, v0
	v_mov_b32_e32 v70, v0
	v_mov_b32_e32 v71, v0
	v_mov_b32_e32 v72, v0
	v_mov_b32_e32 v73, v0
	v_mov_b32_e32 v74, v0
	v_mov_b32_e32 v75, v0
	v_mov_b32_e32 v76, v0
	v_mov_b32_e32 v77, v0
	v_mov_b32_e32 v78, v0
	v_mov_b32_e32 v79, v0
	v_mov_b32_e32 v80, v0
	v_mov_b32_e32 v81, v0
	v_mov_b32_e32 v82, v0
	v_mov_b32_e32 v83, v0
	v_mov_b32_e32 v84, v0
	v_mov_b32_e32 v85, v0
	v_mov_b32_e32 v86, v0
	v_mov_b32_e32 v87, v0
	v_mov_b32_e32 v88, v0
	v_mov_b32_e32 v89, v0
	v_mov_b32_e32 v90, v0
	v_mov_b32_e32 v91, v0
	v_mov_b32_e32 v92, v0
	v_mov_b32_e32 v93, v0
	v_mov_b32_e32 v94, v0
	v_mov_b32_e32 v95, v0
	v_mov_b32_e32 v96, v0
	v_mov_b32_e32 v97, v0
	v_mov_b32_e32 v98, v0
	v_mov_b32_e32 v99, v0
	v_mov_b32_e32 v100, v0
	v_mov_b32_e32 v101, v0
	v_mov_b32_e32 v102, v0
	v_mov_b32_e32 v103, v0
	v_mov_b32_e32 v104, v0
	v_mov_b32_e32 v105, v0
	v_mov_b32_e32 v106, v0
	v_mov_b32_e32 v107, v0
	v_mov_b32_e32 v108, v0
	v_mov_b32_e32 v109, v0
	v_mov_b32_e32 v110, v0
	v_mov_b32_e32 v111, v0
	v_mov_b32_e32 v112, v0
	v_mov_b32_e32 v113, v0
	v_mov_b32_e32 v114, v0
	v_mov_b32_e32 v115, v0
	v_mov_b32_e32 v116, v0
	v_mov_b32_e32 v117, v0
	v_mov_b32_e32 v118, v0
	v_mov_b32_e32 v119, v0
	v_mov_b32_e32 v120, v0
	v_mov_b32_e32 v121, v0
	v_mov_b32_e32 v122, v0
	v_mov_b32_e32 v123, v0
	v_mov_b32_e32 v124, v0
	v_mov_b32_e32 v125, v0
	v_mov_b32_e32 v126, v0
	v_mov_b32_e32 v127, v0
	v_mov_b32_e32 v168, v0
	v_mov_b32_e32 v169, v0
	v_add_u32_e32 v196, v192, v193
	ds_read_b128 v[240:243], v196 offset:39936
	ds_read_b128 v[244:247], v196 offset:40960
	ds_read_b128 v[248:251], v196 offset:44032
	ds_read_b128 v[252:255], v196 offset:45056
	s_and_b32 s0, s8, 1
	s_mul_i32 s1, s0, 0x2200
	v_add_u32_e32 v197, s1, v195
	s_waitcnt lgkmcnt(0)
	s_barrier
.LBB0_2327:
	s_setprio 1
	s_and_b32 s0, s8, 1
	s_mul_i32 s1, s0, 0x2200
	ds_read_b128 v[128:131], v196 offset:37888
	ds_read_b128 v[160:163], v196 offset:38912
	ds_read_b128 v[144:147], v196 offset:41984
	ds_read_b128 v[178:181], v196 offset:43008
	ds_read_b128 v[132:135], v197
	ds_read_b128 v[198:201], v197 offset:32
	ds_read_b128 v[148:151], v197 offset:128
	ds_read_b128 v[202:205], v197 offset:160
	ds_read_b128 v[206:209], v197 offset:64
	ds_read_b128 v[216:219], v197 offset:96
	ds_read_b128 v[220:223], v197 offset:192
	ds_read_b128 v[224:227], v197 offset:224
	s_waitcnt lgkmcnt(7)
	v_mfma_f32_32x32x16_bf16 v[128:143], v[132:135], v[128:131], 0
	s_mul_i32 s1, s0, 0x2400
	s_ashr_i32 s7, s6, 31
	s_xor_b32 s0, s0, 1
	s_add_i32 s8, s8, 1
	s_waitcnt lgkmcnt(5)
	v_mfma_f32_32x32x16_bf16 v[144:159], v[148:151], v[144:147], 0
	v_mfma_f32_32x32x16_bf16 v[128:143], v[198:201], v[160:163], v[128:143]
	s_waitcnt lgkmcnt(4)
	v_mfma_f32_32x32x16_bf16 v[144:159], v[202:205], v[178:181], v[144:159]
	s_waitcnt lgkmcnt(3)
	v_mfma_f32_32x32x16_bf16 v[128:143], v[206:209], v[240:243], v[128:143]
	v_add_u32_e32 v197, s1, v164
	v_add_u32_e32 v210, 0x4000, v197
	v_add_u32_e32 v215, 0x4800, v197
	v_add_u32_e32 v238, 0x5000, v197
	v_add_u32_e32 v197, 0x5800, v197
	v_lshl_add_u64 v[178:179], s[6:7], 1, v[170:171]
	s_waitcnt lgkmcnt(1)
	v_mfma_f32_32x32x16_bf16 v[144:159], v[220:223], v[248:251], v[144:159]
	v_add_u32_e32 v160, s6, v194
	v_mad_i64_i32 v[180:181], s[10:11], v160, s68, v[176:177]
	global_load_dwordx4 v[160:163], v[180:181], off offset:1040
	s_add_i32 s6, s6, 32
	s_mul_i32 s1, s0, 0x2200
	s_mulk_i32 s0, 0x2400
	v_mfma_f32_32x32x16_bf16 v[128:143], v[216:219], v[244:247], v[128:143]
	ds_read2_b64 v[198:201], v210 offset0:128 offset1:130
	s_cmpk_eq_i32 s6, 0x4100
	s_waitcnt lgkmcnt(1)
	v_mfma_f32_32x32x16_bf16 v[144:159], v[224:227], v[252:255], v[144:159]
	s_setprio 0
	s_nop 7
	v_fmamk_f32 v128, v128, 0x3e38aa3b, v175
	v_fmamk_f32 v129, v129, 0x3e38aa3b, v175
	v_fmamk_f32 v130, v130, 0x3e38aa3b, v175
	v_fmamk_f32 v131, v131, 0x3e38aa3b, v175
	v_fmamk_f32 v132, v132, 0x3e38aa3b, v175
	v_fmamk_f32 v133, v133, 0x3e38aa3b, v175
	v_fmamk_f32 v202, v134, 0x3e38aa3b, v175
	v_fmamk_f32 v135, v135, 0x3e38aa3b, v175
	v_fmamk_f32 v203, v144, 0x3e38aa3b, v173
	v_fmamk_f32 v145, v145, 0x3e38aa3b, v173
	v_fmamk_f32 v204, v146, 0x3e38aa3b, v173
	v_fmamk_f32 v205, v147, 0x3e38aa3b, v173
	v_fmamk_f32 v206, v148, 0x3e38aa3b, v173
	v_fmamk_f32 v207, v149, 0x3e38aa3b, v173
	v_fmamk_f32 v208, v150, 0x3e38aa3b, v173
	v_fmamk_f32 v209, v151, 0x3e38aa3b, v173
	v_exp_f32_e32 v150, v128
	v_exp_f32_e32 v148, v129
	v_exp_f32_e32 v146, v130
	v_exp_f32_e32 v144, v131
	v_exp_f32_e32 v134, v132
	v_exp_f32_e32 v130, v133
	v_exp_f32_e32 v132, v202
	v_exp_f32_e32 v128, v135
	v_exp_f32_e32 v151, v203
	v_exp_f32_e32 v149, v145
	v_exp_f32_e32 v147, v204
	v_exp_f32_e32 v145, v205
	v_exp_f32_e32 v135, v206
	v_exp_f32_e32 v131, v207
	v_exp_f32_e32 v133, v208
	v_exp_f32_e32 v129, v209
	v_cvt_pk_bf16_f32 v202, v150, v148
	v_cvt_pk_bf16_f32 v203, v146, v144
	v_cvt_pk_bf16_f32 v204, v134, v130
	v_cvt_pk_bf16_f32 v205, v132, v128
	v_cvt_pk_bf16_f32 v206, v151, v149
	v_cvt_pk_bf16_f32 v207, v147, v145
	v_cvt_pk_bf16_f32 v208, v135, v131
	v_cvt_pk_bf16_f32 v209, v133, v129
	s_setprio 1
	s_waitcnt lgkmcnt(0)
	v_mfma_f32_32x32x16_bf16 v[64:79], v[202:205], v[198:201], v[64:79]
	v_fmamk_f32 v152, v152, 0x3e38aa3b, v173
	v_fmamk_f32 v153, v153, 0x3e38aa3b, v173
	v_fmamk_f32 v154, v154, 0x3e38aa3b, v173
	v_fmamk_f32 v155, v155, 0x3e38aa3b, v173
	v_fmamk_f32 v156, v156, 0x3e38aa3b, v173
	v_fmamk_f32 v157, v157, 0x3e38aa3b, v173
	v_fmamk_f32 v158, v158, 0x3e38aa3b, v173
	v_mfma_f32_32x32x16_bf16 v[48:63], v[206:209], v[198:201], v[48:63]
	ds_read2_b64 v[198:201], v215 offset0:160 offset1:162
	ds_read2_b64 v[216:219], v210 offset0:132 offset1:134
	ds_read2_b64 v[220:223], v238 offset0:192 offset1:194
	ds_read2_b64 v[224:227], v197 offset0:224 offset1:226
	v_fmamk_f32 v159, v159, 0x3e38aa3b, v173
	v_exp_f32_e32 v213, v152
	v_exp_f32_e32 v229, v153
	v_exp_f32_e32 v231, v154
	v_exp_f32_e32 v233, v157
	s_waitcnt lgkmcnt(1)
; __device__ __forceinline__ void attn_item_A(const Params& p, int layer, int head, int q0u, char* lds) {
;     ...
;         float w[16];
; #pragma unroll
;         for (int e = 0; e < 16; ++e) { w[e] = __builtin_amdgcn_exp2f(fmaf(sx[e], CS, -bA)); lA += w[e]; }
;         const u32x4 p0 = {pk2(w[0], w[1]), pk2(w[2], w[3]), pk2(w[4], w[5]), pk2(w[6], w[7])};
;         const u32x4 p1 = {pk2(w[8], w[9]), pk2(w[10], w[11]), pk2(w[12], w[13]), pk2(w[14], w[15])};
;         a0 = __builtin_bit_cast(bf16x8, p0); a1 = __builtin_bit_cast(bf16x8, p1);
;       }
;       {
;         float w[16];
; #pragma unroll
;         for (int e = 0; e < 16; ++e) { w[e] = __builtin_amdgcn_exp2f(fmaf(sy[e], CS, -bB)); lB += w[e]; }
;         const u32x4 p0 = {pk2(w[0], w[1]), pk2(w[2], w[3]), pk2(w[4], w[5]), pk2(w[6], w[7])};
;         const u32x4 p1 = {pk2(w[8], w[9]), pk2(w[10], w[11]), pk2(w[12], w[13]), pk2(w[14], w[15])};
;         b0 = __builtin_bit_cast(bf16x8, p0); b1 = __builtin_bit_cast(bf16x8, p1);
;       }
;     }
;     const u16* vt = Vt + buf * 128 * VLD + r * VLD + 4 * h;
; #pragma unroll
;     for (int d = 0; d < 4; d += 2) {
;       const s16x4 l0 = *(const s16x4*)(vt + d * 32 * VLD), h0 = *(const s16x4*)(vt + d * 32 * VLD + 8);
;       const s16x4 l1 = *(const s16x4*)(vt + d * 32 * VLD + 16), h1 = *(const s16x4*)(vt + d * 32 * VLD + 24);
;       const s16x4 m0 = *(const s16x4*)(vt + (d + 1) * 32 * VLD), n0 = *(const s16x4*)(vt + (d + 1) * 32 * VLD + 8);
;       const s16x4 m1 = *(const s16x4*)(vt + (d + 1) * 32 * VLD + 16), n1 = *(const s16x4*)(vt + (d + 1) * 32 * VLD + 24);
;       const bf16x8 v0 = {l0[0], l0[1], l0[2], l0[3], h0[0], h0[1], h0[2], h0[3]};
;       const bf16x8 v1 = {l1[0], l1[1], l1[2], l1[3], h1[0], h1[1], h1[2], h1[3]};
;       const bf16x8 u0 = {m0[0], m0[1], m0[2], m0[3], n0[0], n0[1], n0[2], n0[3]};
;       const bf16x8 u1 = {m1[0], m1[1], m1[2], m1[3], n1[0], n1[1], n1[2], n1[3]};
;       o1[d] = MFMA32(a0, v0, o1[d]);
;       o2[d] = MFMA32(b0, v0, o2[d]);
;       o1[d + 1] = MFMA32(a0, u0, o1[d + 1]);
;       o2[d + 1] = MFMA32(b0, u0, o2[d + 1]);
;       o1[d] = MFMA32(a1, v1, o1[d]);
;       o2[d] = MFMA32(b1, v1, o2[d]);
;       o1[d + 1] = MFMA32(a1, u1, o1[d + 1]);
;       o2[d + 1] = MFMA32(b1, u1, o2[d + 1]);
;     }
;     if (more) { ATT_STOREK(buf ^ 1); ATT_STOREV(buf ^ 1); }
;     __syncthreads();
	v_mfma_f32_32x32x16_bf16 v[96:111], v[202:205], v[220:223], v[96:111]
	v_exp_f32_e32 v235, v158
	v_exp_f32_e32 v237, v159
	v_fmamk_f32 v136, v136, 0x3e38aa3b, v175
	v_fmamk_f32 v137, v137, 0x3e38aa3b, v175
	v_fmamk_f32 v138, v138, 0x3e38aa3b, v175
	v_fmamk_f32 v139, v139, 0x3e38aa3b, v175
	v_fmamk_f32 v140, v140, 0x3e38aa3b, v175
	v_mfma_f32_32x32x16_bf16 v[16:31], v[206:209], v[220:223], v[16:31]
	v_exp_f32_e32 v221, v155
	v_exp_f32_e32 v223, v156
	global_load_dwordx4 v[152:155], v[180:181], off offset:1024
	global_load_dwordx4 v[156:159], v[178:179], off
	v_fmamk_f32 v141, v141, 0x3e38aa3b, v175
	global_load_dwordx4 v[178:181], v[178:179], off offset:16
	v_fmamk_f32 v142, v142, 0x3e38aa3b, v175
	v_fmamk_f32 v143, v143, 0x3e38aa3b, v175
	v_exp_f32_e32 v212, v136
	v_exp_f32_e32 v228, v137
	v_exp_f32_e32 v230, v138
	v_exp_f32_e32 v220, v139
	v_exp_f32_e32 v222, v140
	v_exp_f32_e32 v232, v141
	v_exp_f32_e32 v234, v142
	v_exp_f32_e32 v236, v143
	v_mfma_f32_32x32x16_bf16 v[80:95], v[202:205], v[198:201], v[80:95]
	v_cvt_pk_bf16_f32 v136, v212, v228
	v_cvt_pk_bf16_f32 v137, v230, v220
	v_cvt_pk_bf16_f32 v138, v222, v232
	v_cvt_pk_bf16_f32 v139, v234, v236
	v_cvt_pk_bf16_f32 v140, v213, v229
	v_cvt_pk_bf16_f32 v141, v231, v221
	v_cvt_pk_bf16_f32 v142, v223, v233
	v_mfma_f32_32x32x16_bf16 v[32:47], v[206:209], v[198:201], v[32:47]
	v_cvt_pk_bf16_f32 v143, v235, v237
	ds_read2_b64 v[198:201], v215 offset0:164 offset1:166
	v_add_f32_e64 v150, v168, v150
	v_add_f32_e64 v151, v169, v151
	v_add_f32_e64 v148, v148, v150
	v_add_f32_e64 v149, v149, v151
	v_pk_add_f32 v[146:147], v[146:147], v[148:149]
	s_waitcnt lgkmcnt(1)
	v_mfma_f32_32x32x16_bf16 v[112:127], v[202:205], v[224:227], v[112:127]
	ds_read2_b64 v[202:205], v197 offset0:228 offset1:230
	v_add_f32_e64 v144, v144, v146
	v_add_f32_e64 v145, v145, v147
	v_add_f32_e64 v134, v134, v144
	v_add_f32_e64 v135, v135, v145
	v_pk_add_f32 v[130:131], v[130:131], v[134:135]
	v_mfma_f32_32x32x16_bf16 v[0:15], v[206:209], v[224:227], v[0:15]
	v_add_f32_e64 v130, v132, v130
	v_add_f32_e64 v131, v133, v131
	v_add_u32_e32 v206, s1, v172
	v_add_f32_e64 v128, v128, v130
	v_add_f32_e64 v129, v129, v131
	v_add_u32_e32 v207, s0, v174
	v_pk_add_f32 v[128:129], v[212:213], v[128:129]
	v_add_u32_e32 v197, 0x4400, v207
	v_pk_add_f32 v[128:129], v[228:229], v[128:129]
	s_waitcnt lgkmcnt(1)
	v_mfma_f32_32x32x16_bf16 v[80:95], v[136:139], v[198:201], v[80:95]
	v_add_f32_e64 v128, v230, v128
	v_add_f32_e64 v129, v231, v129
	v_add_u32_e32 v207, 0x4410, v207
	v_add_f32_e64 v128, v220, v128
	v_add_f32_e64 v129, v221, v129
	v_pk_add_f32 v[128:129], v[222:223], v[128:129]
	s_nop 0
	v_pk_add_f32 v[128:129], v[232:233], v[128:129]
	v_mfma_f32_32x32x16_bf16 v[32:47], v[140:143], v[198:201], v[32:47]
	ds_read2_b64 v[198:201], v238 offset0:196 offset1:198
	v_add_f32_e64 v128, v234, v128
	v_add_f32_e64 v129, v235, v129
	s_setprio 0
	s_waitcnt vmcnt(2)
	ds_write_b128 v206, v[152:155]
	ds_write_b128 v206, v[160:163] offset:16
	s_waitcnt vmcnt(1)
	ds_write2_b64 v197, v[156:157], v[158:159] offset1:1
	s_waitcnt vmcnt(0)
	ds_write2_b64 v207, v[178:179], v[180:181] offset1:1
	v_mfma_f32_32x32x16_bf16 v[64:79], v[136:139], v[216:219], v[64:79]
	v_add_f32_e64 v168, v236, v128
	v_add_f32_e64 v169, v237, v129
	v_add_u32_e32 v197, s1, v195
	s_waitcnt lgkmcnt(0)
	s_barrier
	v_mfma_f32_32x32x16_bf16 v[48:63], v[140:143], v[216:219], v[48:63]
	v_mfma_f32_32x32x16_bf16 v[96:111], v[136:139], v[198:201], v[96:111]
	v_mfma_f32_32x32x16_bf16 v[16:31], v[140:143], v[198:201], v[16:31]
	v_mfma_f32_32x32x16_bf16 v[112:127], v[136:139], v[202:205], v[112:127]
	v_mfma_f32_32x32x16_bf16 v[0:15], v[140:143], v[202:205], v[0:15]
	s_cbranch_scc0 .LBB0_2327
	ds_read_b128 v[128:131], v195 offset:8704
	ds_read_b128 v[132:135], v196 offset:37888
	ds_read_b128 v[136:139], v195 offset:8736
	ds_read_b128 v[140:143], v196 offset:38912
	s_waitcnt lgkmcnt(2)
	v_mfma_f32_32x32x16_bf16 v[144:159], v[128:131], v[132:135], 0
	ds_read_b128 v[128:131], v195 offset:8768
	ds_read_b128 v[132:135], v196 offset:39936
	ds_read_b128 v[160:163], v195 offset:8800
	ds_read_b128 v[176:179], v196 offset:40960
	s_waitcnt lgkmcnt(4)
	v_mfma_f32_32x32x16_bf16 v[144:159], v[136:139], v[140:143], v[144:159]
	s_waitcnt lgkmcnt(2)
	v_mfma_f32_32x32x16_bf16 v[144:159], v[128:131], v[132:135], v[144:159]
	ds_read_b128 v[128:131], v195 offset:8832
	ds_read_b128 v[132:135], v196 offset:41984
	ds_read_b128 v[198:201], v195 offset:8864
	ds_read_b128 v[202:205], v196 offset:43008
	ds_read_b128 v[206:209], v195 offset:8896
	ds_read_b128 v[192:195], v195 offset:8928
	ds_read_b128 v[216:219], v196 offset:44032
	ds_read_b128 v[220:223], v196 offset:45056
	s_waitcnt lgkmcnt(6)
	v_mfma_f32_32x32x16_bf16 v[128:143], v[128:131], v[132:135], 0
	s_waitcnt lgkmcnt(4)
	v_mfma_f32_32x32x16_bf16 v[128:143], v[198:201], v[202:205], v[128:143]
	s_waitcnt lgkmcnt(1)
	v_mfma_f32_32x32x16_bf16 v[128:143], v[206:209], v[216:219], v[128:143]
	s_waitcnt lgkmcnt(0)
; __device__ __forceinline__ void attn_item_A(const Params& p, int layer, int head, int q0u, char* lds) {
;     ...
;         float w[16];
; #pragma unroll
;         for (int e = 0; e < 16; ++e) { w[e] = __builtin_amdgcn_exp2f(fmaf(sx[e], CS, -bA)); lA += w[e]; }
;         const u32x4 p0 = {pk2(w[0], w[1]), pk2(w[2], w[3]), pk2(w[4], w[5]), pk2(w[6], w[7])};
;         const u32x4 p1 = {pk2(w[8], w[9]), pk2(w[10], w[11]), pk2(w[12], w[13]), pk2(w[14], w[15])};
;         a0 = __builtin_bit_cast(bf16x8, p0); a1 = __builtin_bit_cast(bf16x8, p1);
;       }
;       {
;         float w[16];
; #pragma unroll
;         for (int e = 0; e < 16; ++e) { w[e] = __builtin_amdgcn_exp2f(fmaf(sy[e], CS, -bB)); lB += w[e]; }
;         const u32x4 p0 = {pk2(w[0], w[1]), pk2(w[2], w[3]), pk2(w[4], w[5]), pk2(w[6], w[7])};
;         const u32x4 p1 = {pk2(w[8], w[9]), pk2(w[10], w[11]), pk2(w[12], w[13]), pk2(w[14], w[15])};
;         b0 = __builtin_bit_cast(bf16x8, p0); b1 = __builtin_bit_cast(bf16x8, p1);
;       }
;     }
;     const u16* vt = Vt + buf * 128 * VLD + r * VLD + 4 * h;
; #pragma unroll
;     for (int d = 0; d < 4; d += 2) {
;       const s16x4 l0 = *(const s16x4*)(vt + d * 32 * VLD), h0 = *(const s16x4*)(vt + d * 32 * VLD + 8);
;       const s16x4 l1 = *(const s16x4*)(vt + d * 32 * VLD + 16), h1 = *(const s16x4*)(vt + d * 32 * VLD + 24);
;       const s16x4 m0 = *(const s16x4*)(vt + (d + 1) * 32 * VLD), n0 = *(const s16x4*)(vt + (d + 1) * 32 * VLD + 8);
;       const s16x4 m1 = *(const s16x4*)(vt + (d + 1) * 32 * VLD + 16), n1 = *(const s16x4*)(vt + (d + 1) * 32 * VLD + 24);
;       const bf16x8 v0 = {l0[0], l0[1], l0[2], l0[3], h0[0], h0[1], h0[2], h0[3]};
;       const bf16x8 v1 = {l1[0], l1[1], l1[2], l1[3], h1[0], h1[1], h1[2], h1[3]};
;       const bf16x8 u0 = {m0[0], m0[1], m0[2], m0[3], n0[0], n0[1], n0[2], n0[3]};
;       const bf16x8 u1 = {m1[0], m1[1], m1[2], m1[3], n1[0], n1[1], n1[2], n1[3]};
;       o1[d] = MFMA32(a0, v0, o1[d]);
;       o2[d] = MFMA32(b0, v0, o2[d]);
;       o1[d + 1] = MFMA32(a0, u0, o1[d + 1]);
;       o2[d + 1] = MFMA32(b0, u0, o2[d + 1]);
;       o1[d] = MFMA32(a1, v1, o1[d]);
;       o2[d] = MFMA32(b1, v1, o2[d]);
;       o1[d + 1] = MFMA32(a1, u1, o1[d + 1]);
;       o2[d + 1] = MFMA32(b1, u1, o2[d + 1]);
;     }
;     if (more) { ATT_STOREK(buf ^ 1); ATT_STOREV(buf ^ 1); }
;     __syncthreads();
;   }
	v_mfma_f32_32x32x16_bf16 v[128:143], v[192:195], v[220:223], v[128:143]
	v_mfma_f32_32x32x16_bf16 v[144:159], v[160:163], v[176:179], v[144:159]
	s_nop 10
	v_fmamk_f32 v128, v128, 0x3e38aa3b, v173
	v_exp_f32_e32 v192, v128
	v_fmamk_f32 v128, v129, 0x3e38aa3b, v173
	v_exp_f32_e32 v193, v128
	v_fmamk_f32 v128, v130, 0x3e38aa3b, v173
	v_exp_f32_e32 v194, v128
	v_fmamk_f32 v128, v131, 0x3e38aa3b, v173
	v_exp_f32_e32 v195, v128
	v_fmamk_f32 v128, v132, 0x3e38aa3b, v173
	v_fmamk_f32 v132, v134, 0x3e38aa3b, v173
	v_fmamk_f32 v144, v144, 0x3e38aa3b, v175
	v_fmamk_f32 v145, v145, 0x3e38aa3b, v175
	v_fmamk_f32 v146, v146, 0x3e38aa3b, v175
	v_fmamk_f32 v147, v147, 0x3e38aa3b, v175
	v_fmamk_f32 v148, v148, 0x3e38aa3b, v175
	v_fmamk_f32 v149, v149, 0x3e38aa3b, v175
	v_fmamk_f32 v150, v150, 0x3e38aa3b, v175
	v_fmamk_f32 v151, v151, 0x3e38aa3b, v175
	v_exp_f32_e32 v201, v128
	v_fmamk_f32 v128, v133, 0x3e38aa3b, v173
	v_exp_f32_e32 v203, v132
	v_fmamk_f32 v132, v135, 0x3e38aa3b, v173
	v_exp_f32_e32 v170, v144
	v_exp_f32_e32 v171, v145
	v_exp_f32_e32 v172, v146
	v_exp_f32_e32 v174, v147
	v_exp_f32_e32 v176, v148
	v_exp_f32_e32 v177, v149
	v_exp_f32_e32 v178, v150
	v_exp_f32_e32 v179, v151
	v_fmamk_f32 v144, v155, 0x3e38aa3b, v175
	v_exp_f32_e32 v202, v128
	v_exp_f32_e32 v204, v132
	v_exp_f32_e32 v197, v144
	v_fmamk_f32 v144, v156, 0x3e38aa3b, v175
	v_fmamk_f32 v152, v152, 0x3e38aa3b, v175
	v_exp_f32_e32 v198, v144
	v_fmamk_f32 v144, v157, 0x3e38aa3b, v175
	v_exp_f32_e32 v180, v152
	v_exp_f32_e32 v199, v144
	v_fmamk_f32 v144, v158, 0x3e38aa3b, v175
	v_add_u32_e32 v152, 0x6800, v164
	v_fmamk_f32 v136, v136, 0x3e38aa3b, v173
	v_exp_f32_e32 v200, v144
	v_cvt_pk_bf16_f32 v144, v170, v171
	v_cvt_pk_bf16_f32 v145, v172, v174
	v_cvt_pk_bf16_f32 v146, v176, v177
	v_cvt_pk_bf16_f32 v147, v178, v179
	ds_read2_b64 v[128:131], v152 offset1:2
	v_cvt_pk_bf16_f32 v132, v192, v193
	v_cvt_pk_bf16_f32 v133, v194, v195
	v_cvt_pk_bf16_f32 v134, v201, v202
	v_cvt_pk_bf16_f32 v135, v203, v204
	v_exp_f32_e32 v205, v136
	v_fmamk_f32 v136, v137, 0x3e38aa3b, v173
	v_exp_f32_e32 v206, v136
	v_fmamk_f32 v136, v138, 0x3e38aa3b, v173
	v_exp_f32_e32 v207, v136
	v_fmamk_f32 v136, v139, 0x3e38aa3b, v173
	v_fmamk_f32 v153, v153, 0x3e38aa3b, v175
	v_exp_f32_e32 v208, v136
	v_fmamk_f32 v136, v140, 0x3e38aa3b, v173
	v_exp_f32_e32 v181, v153
	v_add_u32_e32 v153, 0x7000, v164
	v_exp_f32_e32 v209, v136
	v_fmamk_f32 v136, v141, 0x3e38aa3b, v173
	v_fmamk_f32 v154, v154, 0x3e38aa3b, v175
	v_fmac_f32_e32 v175, 0x3e38aa3b, v159
	s_waitcnt lgkmcnt(0)
	v_mfma_f32_32x32x16_bf16 v[64:79], v[144:147], v[128:131], v[64:79]
	v_exp_f32_e32 v210, v136
	v_fmamk_f32 v136, v142, 0x3e38aa3b, v173
	v_fmac_f32_e32 v173, 0x3e38aa3b, v143
	v_exp_f32_e32 v196, v154
	v_exp_f32_e32 v175, v175
	v_exp_f32_e32 v212, v136
	v_exp_f32_e32 v173, v173
	v_mfma_f32_32x32x16_bf16 v[48:63], v[132:135], v[128:131], v[48:63]
	ds_read2_b64 v[128:131], v153 offset0:32 offset1:34
	v_cvt_pk_bf16_f32 v148, v180, v181
	v_cvt_pk_bf16_f32 v149, v196, v197
	v_cvt_pk_bf16_f32 v150, v198, v199
	v_cvt_pk_bf16_f32 v151, v200, v175
	v_cvt_pk_bf16_f32 v136, v205, v206
	v_cvt_pk_bf16_f32 v137, v207, v208
	s_waitcnt lgkmcnt(0)
	v_mfma_f32_32x32x16_bf16 v[80:95], v[144:147], v[128:131], v[80:95]
	v_cvt_pk_bf16_f32 v138, v209, v210
	v_cvt_pk_bf16_f32 v139, v212, v173
	v_add_u32_e32 v160, 0x8000, v164
	v_mfma_f32_32x32x16_bf16 v[32:47], v[132:135], v[128:131], v[32:47]
	ds_read2_b64 v[128:131], v152 offset0:4 offset1:6
	v_add_u32_e32 v152, 0x7800, v164
	ds_read2_b64 v[140:143], v152 offset0:64 offset1:66
	s_waitcnt lgkmcnt(1)
	v_mfma_f32_32x32x16_bf16 v[64:79], v[148:151], v[128:131], v[64:79]
	v_mfma_f32_32x32x16_bf16 v[48:63], v[136:139], v[128:131], v[48:63]
	ds_read2_b64 v[128:131], v153 offset0:36 offset1:38
	ds_read2_b64 v[152:155], v152 offset0:68 offset1:70
	ds_read2_b64 v[156:159], v160 offset0:96 offset1:98
	ds_read2_b64 v[160:163], v160 offset0:100 offset1:102
	s_waitcnt lgkmcnt(0)
	s_barrier
	global_load_dword v164, v165, s[18:19]
	v_mfma_f32_32x32x16_bf16 v[96:111], v[144:147], v[140:143], v[96:111]
	v_and_b32_e32 v213, 31, v167
	v_mfma_f32_32x32x16_bf16 v[16:31], v[132:135], v[140:143], v[16:31]
	v_add_f32_e32 v140, v169, v192
	v_add_f32_e32 v140, v193, v140
	v_add_f32_e32 v140, v194, v140
	v_add_f32_e32 v140, v195, v140
	v_add_f32_e32 v140, v201, v140
	v_add_f32_e32 v140, v202, v140
	v_add_f32_e32 v140, v203, v140
	v_add_f32_e32 v140, v204, v140
	v_add_f32_e32 v140, v205, v140
	v_add_f32_e32 v140, v206, v140
	v_mfma_f32_32x32x16_bf16 v[0:15], v[132:135], v[156:159], v[0:15]
	v_add_f32_e32 v132, v207, v140
	v_add_f32_e32 v132, v208, v132
	v_add_f32_e32 v132, v209, v132
	v_add_f32_e32 v132, v210, v132
	v_add_f32_e32 v132, v212, v132
	v_add_f32_e32 v132, v173, v132
	ds_bpermute_b32 v133, v191, v132
	v_mfma_f32_32x32x16_bf16 v[80:95], v[148:151], v[128:131], v[80:95]
	s_waitcnt lgkmcnt(0)
	v_add_f32_e32 v132, v132, v133
	s_waitcnt vmcnt(0)
	v_div_scale_f32 v133, s[0:1], v132, v132, v164
	v_mfma_f32_32x32x16_bf16 v[32:47], v[136:139], v[128:131], v[32:47]
	v_add_f32_e32 v131, v168, v170
	v_add_f32_e32 v131, v171, v131
	v_add_f32_e32 v131, v172, v131
	v_add_f32_e32 v131, v174, v131
	v_add_f32_e32 v131, v176, v131
	v_add_f32_e32 v131, v177, v131
	v_add_f32_e32 v131, v178, v131
	v_add_f32_e32 v131, v179, v131
	v_add_f32_e32 v131, v180, v131
	v_add_f32_e32 v131, v181, v131
	v_lshlrev_b32_e32 v128, 2, v213
	v_add_f32_e32 v131, v196, v131
	v_rcp_f32_e32 v134, v133
	global_load_dword v129, v128, s[54:55] offset:512
	global_load_dword v130, v128, s[54:55] offset:640
	global_load_dword v215, v128, s[54:55] offset:768
	v_add_f32_e32 v131, v197, v131
	v_add_f32_e32 v131, v198, v131
	v_add_f32_e32 v131, v199, v131
	v_add_f32_e32 v131, v200, v131
	v_fma_f32 v140, -v133, v134, 1.0
	v_add_f32_e32 v131, v175, v131
	v_fmac_f32_e32 v134, v140, v134
	v_div_scale_f32 v140, vcc, v164, v132, v164
	ds_bpermute_b32 v135, v191, v131
	v_mul_f32_e32 v141, v140, v134
	v_fma_f32 v142, -v133, v141, v140
	v_fmac_f32_e32 v141, v142, v134
	v_fma_f32 v133, -v133, v141, v140
	v_div_fmas_f32 v133, v133, v134, v141
	v_div_fixup_f32 v132, v133, v132, v164
	s_waitcnt lgkmcnt(0)
; DI u16 f2bf(float a) { return (u16)(pk2(a, 0.f) & 0xffffu); }
; DI int crow(int i, int h) { return (i & 3) + 8 * (i >> 2) + 4 * h; }
; __device__ __forceinline__ void attn_item_A(const Params& p, int layer, int head, int q0u, char* lds) {
;     ...
;   lA += __shfl_xor(lA, 32); lB += __shfl_xor(lB, 32);
;   const float lam = ((const float*)(p.ws + OFF_LAM))[layer];
;   const float iA = 1.f / lA, iB = lam / lB;
;   u16* Mx = (u16*)(p.ws + OFF_M);
;   const int orow0 = q0u + wid * 32;
;   const float lam_init = 0.8f - 0.6f * expf(-0.3f * (float)layer);
;   float sw[4];
; #pragma unroll
;   for (int d = 0; d < 4; ++d) sw[d] = p.subln[layer * 128 + d * 32 + r_e] * (1.f - lam_init);
; #pragma unroll
;   for (int e = 0; e < 16; ++e) {
;     const int qq = crow(e, h_e);
;     const float ia = __shfl(iA, qq), ib = __shfl(iB, qq);
;     float ov[4];
;     float ss = 0.f;
; #pragma unroll
;     for (int d = 0; d < 4; ++d) { ov[d] = o1[d][e] * ia - o2[d][e] * ib; ss += ov[d] * ov[d]; }
; #pragma unroll
;     for (int x = 16; x >= 1; x >>= 1) ss += __shfl_xor(ss, x);
;     const float rs = rsqrtf(ss * (1.f / 128.f) + LN_EPS);
;     const size_t rowoff = (size_t)(orow0 + qq) * LDX + ocol + r_e;
; #pragma unroll
;     for (int d = 0; d < 4; ++d) Mx[rowoff + d * 32] = f2bf(ov[d] * rs * sw[d]);
;   }
	v_add_f32_e32 v133, v131, v135
	v_div_scale_f32 v134, s[0:1], v133, v133, 1.0
	v_rcp_f32_e32 v135, v134
	v_mfma_f32_32x32x16_bf16 v[0:15], v[136:139], v[160:163], v[0:15]
	v_mov_b32_e32 v143, v32
	v_mov_b32_e32 v140, v64
	v_mov_b32_e32 v142, v48
	v_mov_b32_e32 v141, v80
	v_mov_b32_e32 v80, v65
	s_add_u32 s0, s34, s4
	s_addc_u32 s1, s35, s5
	v_mfma_f32_32x32x16_bf16 v[112:127], v[144:147], v[156:159], v[112:127]
	s_nop 3
	v_mov_b32_e32 v146, v0
	v_xor_b32_e32 v0, 16, v214
	v_lshlrev_b32_e32 v164, 1, v213
	global_load_dword v128, v128, s[54:55] offset:896
	s_waitcnt vmcnt(3)
	v_mul_f32_e32 v131, 0x3f24fd5c, v129
	v_mfma_f32_32x32x16_bf16 v[16:31], v[136:139], v[152:155], v[16:31]
	v_fma_f32 v136, -v134, v135, 1.0
	v_fmac_f32_e32 v135, v136, v135
	v_div_scale_f32 v136, vcc, 1.0, v133, 1.0
	v_mul_f32_e32 v137, v136, v135
	v_fma_f32 v138, -v134, v137, v136
	v_fmac_f32_e32 v137, v138, v135
	v_fma_f32 v134, -v134, v137, v136
	v_div_fmas_f32 v134, v134, v135, v137
	v_ashrrev_i32_e32 v135, 3, v167
	v_div_fixup_f32 v133, v134, v133, 1.0
	v_and_b32_e32 v134, -4, v135
	v_mfma_f32_32x32x16_bf16 v[96:111], v[148:151], v[152:155], v[96:111]
	v_cmp_lt_i32_e32 vcc, v0, v187
	v_and_or_b32 v136, v135, 60, v186
	v_mov_b32_e32 v147, v16
	v_cndmask_b32_e32 v16, v214, v0, vcc
	v_lshlrev_b32_e32 v137, 2, v136
	ds_bpermute_b32 v138, v137, v132
	ds_bpermute_b32 v136, v137, v133
	v_mfma_f32_32x32x16_bf16 v[112:127], v[148:151], v[160:163], v[112:127]
	v_or_b32_e32 v150, 1, v134
	v_and_or_b32 v0, v150, 61, v186
	v_lshlrev_b32_e32 v32, 2, v0
	ds_bpermute_b32 v0, v32, v132
	ds_bpermute_b32 v64, v32, v133
	v_mov_b32_e32 v32, v49
	s_waitcnt lgkmcnt(3)
	v_pk_mul_f32 v[142:143], v[142:143], v[138:139] op_sel_hi:[1,0]
	s_nop 3
	v_mov_b32_e32 v144, v112
	v_mov_b32_e32 v145, v96
	v_pk_mul_f32 v[138:139], v[146:147], v[138:139] op_sel_hi:[1,0]
	v_lshlrev_b32_e32 v48, 2, v16
	s_waitcnt lgkmcnt(1)
	v_pk_mul_f32 v[32:33], v[32:33], v[0:1] op_sel_hi:[1,0]
	v_mov_b32_e32 v16, v1
	v_pk_fma_f32 v[140:141], v[140:141], v[136:137], v[142:143] op_sel_hi:[1,0,1] neg_lo:[0,0,1] neg_hi:[0,0,1]
	v_pk_fma_f32 v[136:137], v[144:145], v[136:137], v[138:139] op_sel_hi:[1,0,1] neg_lo:[0,0,1] neg_hi:[0,0,1]
	s_waitcnt lgkmcnt(0)
	v_pk_fma_f32 v[144:145], v[80:81], v[64:65], v[32:33] op_sel_hi:[1,0,1] neg_lo:[0,0,1] neg_hi:[0,0,1]
	v_mov_b32_e32 v96, v113
	v_pk_mul_f32 v[0:1], v[16:17], v[0:1] op_sel_hi:[1,0]
	v_pk_mul_f32 v[142:143], v[140:141], v[140:141]
	v_pk_mul_f32 v[32:33], v[144:145], v[144:145]
	v_pk_fma_f32 v[96:97], v[96:97], v[64:65], v[0:1] op_sel_hi:[1,0,1] neg_lo:[0,0,1] neg_hi:[0,0,1]
	v_pk_mul_f32 v[138:139], v[136:137], v[136:137]
	v_pk_mul_f32 v[0:1], v[96:97], v[96:97]
	v_mov_b32_e32 v16, v32
	v_mov_b32_e32 v17, v142
	v_mov_b32_e32 v142, v33
	v_pk_add_f32 v[16:17], v[16:17], v[142:143]
	v_mov_b32_e32 v32, v1
	v_mov_b32_e32 v33, v139
	v_pk_add_f32 v[16:17], v[32:33], v[16:17]
	v_mov_b32_e32 v1, v138
	v_pk_add_f32 v[0:1], v[0:1], v[16:17]
	ds_bpermute_b32 v17, v48, v1
	ds_bpermute_b32 v16, v48, v0
	v_xor_b32_e32 v32, 8, v214
	v_cmp_lt_i32_e32 vcc, v32, v187
	s_waitcnt vmcnt(2)
	v_mul_f32_e32 v130, 0x3f24fd5c, v130
	s_waitcnt vmcnt(1)
	v_mul_f32_e32 v129, 0x3f24fd5c, v215
	v_cndmask_b32_e32 v32, v214, v32, vcc
	v_lshlrev_b32_e32 v49, 2, v32
	s_waitcnt lgkmcnt(0)
	v_pk_add_f32 v[0:1], v[0:1], v[16:17]
	ds_bpermute_b32 v17, v49, v1
	ds_bpermute_b32 v16, v49, v0
	v_xor_b32_e32 v32, 4, v214
	v_cmp_lt_i32_e32 vcc, v32, v187
	v_or_b32_e32 v152, 2, v134
	v_or_b32_e32 v135, 3, v135
	v_cndmask_b32_e32 v32, v214, v32, vcc
	v_lshlrev_b32_e32 v64, 2, v32
	s_waitcnt lgkmcnt(0)
	v_pk_add_f32 v[0:1], v[0:1], v[16:17]
	ds_bpermute_b32 v17, v64, v1
	ds_bpermute_b32 v16, v64, v0
	v_xor_b32_e32 v32, 2, v214
	v_cmp_lt_i32_e32 vcc, v32, v187
	v_mov_b32_e32 v148, v2
	v_and_or_b32 v2, v135, 63, v186
	v_cndmask_b32_e32 v32, v214, v32, vcc
	v_lshlrev_b32_e32 v65, 2, v32
	s_waitcnt lgkmcnt(0)
	v_pk_add_f32 v[0:1], v[0:1], v[16:17]
	ds_bpermute_b32 v17, v65, v1
	ds_bpermute_b32 v16, v65, v0
	v_xor_b32_e32 v32, 1, v214
	v_cmp_lt_i32_e32 vcc, v32, v187
	v_mov_b32_e32 v149, v18
	v_lshlrev_b32_e32 v18, 2, v2
	v_cndmask_b32_e32 v32, v214, v32, vcc
	v_lshlrev_b32_e32 v80, 2, v32
	s_waitcnt lgkmcnt(0)
	v_pk_add_f32 v[0:1], v[0:1], v[16:17]
	ds_bpermute_b32 v33, v80, v1
	ds_bpermute_b32 v32, v80, v0
	v_lshl_add_u64 v[16:17], s[0:1], 0, v[164:165]
	ds_bpermute_b32 v2, v18, v132
	v_mov_b32_e32 v142, v50
	ds_bpermute_b32 v50, v18, v133
	s_waitcnt lgkmcnt(2)
	v_pk_add_f32 v[0:1], v[0:1], v[32:33]
	v_mov_b64_e32 v[32:33], s[36:37]
	v_pk_fma_f32 v[112:113], v[0:1], s[30:31], v[32:33] op_sel_hi:[1,0,0]
	v_mov_b32_e32 v143, v34
	v_mul_f32_e32 v0, 0x4b800000, v113
	v_cmp_gt_f32_e32 vcc, s81, v113
	v_mov_b32_e32 v34, v51
	s_waitcnt lgkmcnt(1)
	v_pk_mul_f32 v[34:35], v[34:35], v[2:3] op_sel_hi:[1,0]
	v_cndmask_b32_e32 v0, v113, v0, vcc
	v_rsq_f32_e32 v81, v0
	v_add_u32_e32 v0, v134, v190
	v_mad_i64_i32 v[0:1], s[0:1], v0, s78, v[16:17]
	v_mul_f32_e32 v113, 0x45800000, v81
	v_cndmask_b32_e32 v81, v81, v113, vcc
	v_mul_f32_e32 v113, v140, v81
	v_mul_f32_e32 v113, v131, v113
	v_cvt_pk_bf16_f32 v113, v113, s0
	global_store_short v[0:1], v113, off
	v_mul_f32_e32 v113, v141, v81
	v_mul_f32_e32 v113, v130, v113
	v_cvt_pk_bf16_f32 v113, v113, s0
	global_store_short v[0:1], v113, off offset:64
	v_mul_f32_e32 v113, v137, v81
	v_mul_f32_e32 v113, v129, v113
	v_cvt_pk_bf16_f32 v137, v113, s0
	v_mul_f32_e32 v113, 0x4b800000, v112
	v_cmp_gt_f32_e32 vcc, s81, v112
	v_mov_b32_e32 v140, v66
	v_mov_b32_e32 v141, v82
	v_cndmask_b32_e32 v112, v112, v113, vcc
	v_rsq_f32_e32 v151, v112
	v_and_or_b32 v112, v152, 62, v186
	v_lshlrev_b32_e32 v113, 2, v112
	ds_bpermute_b32 v138, v113, v132
	ds_bpermute_b32 v112, v113, v133
	v_mov_b32_e32 v82, v67
	v_mov_b32_e32 v18, v3
	v_mov_b32_e32 v146, v114
	s_waitcnt lgkmcnt(1)
; DI u16 f2bf(float a) { return (u16)(pk2(a, 0.f) & 0xffffu); }
; DI int crow(int i, int h) { return (i & 3) + 8 * (i >> 2) + 4 * h; }
; __device__ __forceinline__ void attn_item_A(const Params& p, int layer, int head, int q0u, char* lds) {
;     ...
; #pragma unroll
;   for (int e = 0; e < 16; ++e) {
;     const int qq = crow(e, h_e);
;     const float ia = __shfl(iA, qq), ib = __shfl(iB, qq);
;     float ov[4];
;     float ss = 0.f;
; #pragma unroll
;     for (int d = 0; d < 4; ++d) { ov[d] = o1[d][e] * ia - o2[d][e] * ib; ss += ov[d] * ov[d]; }
; #pragma unroll
;     for (int x = 16; x >= 1; x >>= 1) ss += __shfl_xor(ss, x);
;     const float rs = rsqrtf(ss * (1.f / 128.f) + LN_EPS);
;     const size_t rowoff = (size_t)(orow0 + qq) * LDX + ocol + r_e;
; #pragma unroll
;     for (int d = 0; d < 4; ++d) Mx[rowoff + d * 32] = f2bf(ov[d] * rs * sw[d]);
;   }
	v_pk_mul_f32 v[142:143], v[142:143], v[138:139] op_sel_hi:[1,0]
	v_mov_b32_e32 v147, v98
	s_waitcnt lgkmcnt(0)
	v_pk_fma_f32 v[140:141], v[140:141], v[112:113], v[142:143] op_sel_hi:[1,0,1] neg_lo:[0,0,1] neg_hi:[0,0,1]
	v_pk_mul_f32 v[138:139], v[148:149], v[138:139] op_sel_hi:[1,0]
	v_pk_fma_f32 v[66:67], v[82:83], v[50:51], v[34:35] op_sel_hi:[1,0,1] neg_lo:[0,0,1] neg_hi:[0,0,1]
	v_mov_b32_e32 v98, v115
	v_pk_mul_f32 v[2:3], v[18:19], v[2:3] op_sel_hi:[1,0]
	v_pk_mul_f32 v[142:143], v[140:141], v[140:141]
	v_pk_fma_f32 v[112:113], v[146:147], v[112:113], v[138:139] op_sel_hi:[1,0,1] neg_lo:[0,0,1] neg_hi:[0,0,1]
	v_pk_mul_f32 v[34:35], v[66:67], v[66:67]
	v_pk_fma_f32 v[50:51], v[98:99], v[50:51], v[2:3] op_sel_hi:[1,0,1] neg_lo:[0,0,1] neg_hi:[0,0,1]
	v_pk_mul_f32 v[138:139], v[112:113], v[112:113]
	v_pk_mul_f32 v[2:3], v[50:51], v[50:51]
	v_mov_b32_e32 v18, v34
	v_mov_b32_e32 v19, v142
	v_mov_b32_e32 v142, v35
	v_pk_add_f32 v[18:19], v[18:19], v[142:143]
	v_mov_b32_e32 v34, v3
	v_mov_b32_e32 v35, v139
	v_pk_add_f32 v[18:19], v[34:35], v[18:19]
	v_mov_b32_e32 v3, v138
	v_pk_add_f32 v[2:3], v[2:3], v[18:19]
	ds_bpermute_b32 v19, v48, v3
	ds_bpermute_b32 v18, v48, v2
	v_mul_f32_e32 v35, 0x45800000, v151
	v_cndmask_b32_e32 v35, v151, v35, vcc
	v_mul_f32_e32 v34, v136, v81
	v_mul_f32_e32 v81, v144, v35
	s_waitcnt lgkmcnt(0)
	v_pk_add_f32 v[18:19], v[2:3], v[18:19]
	ds_bpermute_b32 v83, v49, v19
	ds_bpermute_b32 v82, v49, v18
	v_add_u32_e32 v2, v150, v190
	v_mad_i64_i32 v[2:3], s[0:1], v2, s78, v[16:17]
	v_mul_f32_e32 v81, v131, v81
	s_waitcnt lgkmcnt(0)
	v_pk_add_f32 v[18:19], v[18:19], v[82:83]
	ds_bpermute_b32 v83, v64, v19
	ds_bpermute_b32 v82, v64, v18
	v_cvt_pk_bf16_f32 v81, v81, s0
	global_store_short v[2:3], v81, off
	v_mul_f32_e32 v81, v145, v35
	v_mul_f32_e32 v81, v130, v81
	s_waitcnt lgkmcnt(0)
	v_pk_add_f32 v[18:19], v[18:19], v[82:83]
	ds_bpermute_b32 v83, v65, v19
	ds_bpermute_b32 v82, v65, v18
	v_cvt_pk_bf16_f32 v81, v81, s0
	global_store_short v[2:3], v81, off offset:64
	v_mul_f32_e32 v81, v97, v35
	v_mul_f32_e32 v81, v129, v81
	s_waitcnt lgkmcnt(0)
	v_pk_add_f32 v[18:19], v[18:19], v[82:83]
	ds_bpermute_b32 v83, v80, v19
	ds_bpermute_b32 v82, v80, v18
	v_cvt_pk_bf16_f32 v81, v81, s0
	global_store_short v[2:3], v81, off offset:128
	v_mov_b32_e32 v136, v116
	v_add_u32_e32 v116, 9, v134
	s_waitcnt lgkmcnt(0)
	v_pk_add_f32 v[18:19], v[18:19], v[82:83]
	v_mov_b32_e32 v138, v4
	v_pk_fma_f32 v[82:83], v[18:19], s[30:31], v[32:33] op_sel_hi:[1,0,0]
	v_and_or_b32 v4, v116, 61, v186
	v_mul_f32_e32 v18, 0x4b800000, v83
	v_cmp_gt_f32_e32 vcc, s81, v83
	v_mov_b32_e32 v139, v20
	v_lshlrev_b32_e32 v20, 2, v4
	v_cndmask_b32_e32 v18, v83, v18, vcc
	v_rsq_f32_e32 v81, v18
	v_add_u32_e32 v18, v152, v190
	v_mad_i64_i32 v[18:19], s[0:1], v18, s78, v[16:17]
	v_mul_f32_e32 v83, 0x45800000, v81
	v_cndmask_b32_e32 v81, v81, v83, vcc
	v_mul_f32_e32 v83, v140, v81
	v_mul_f32_e32 v83, v131, v83
	v_cvt_pk_bf16_f32 v83, v83, s0
	global_store_short v[18:19], v83, off
	v_mul_f32_e32 v83, v141, v81
	v_mul_f32_e32 v83, v130, v83
	v_cvt_pk_bf16_f32 v83, v83, s0
	global_store_short v[18:19], v83, off offset:64
	v_mul_f32_e32 v83, v113, v81
	v_mul_f32_e32 v83, v129, v83
	v_cvt_pk_bf16_f32 v113, v83, s0
	v_mul_f32_e32 v83, 0x4b800000, v82
	v_cmp_gt_f32_e32 vcc, s81, v82
	v_add_u32_e32 v141, 8, v134
	v_mul_f32_e32 v35, v96, v35
	v_cndmask_b32_e32 v82, v82, v83, vcc
	v_rsq_f32_e32 v140, v82
	v_and_or_b32 v82, v141, 60, v186
	v_lshlrev_b32_e32 v83, 2, v82
	ds_bpermute_b32 v96, v83, v132
	ds_bpermute_b32 v4, v20, v132
	ds_bpermute_b32 v82, v83, v133
	v_mov_b32_e32 v114, v52
	ds_bpermute_b32 v52, v20, v133
	v_mov_b32_e32 v115, v36
	v_mov_b32_e32 v36, v53
	v_mov_b32_e32 v98, v68
	v_mov_b32_e32 v99, v84
	s_waitcnt lgkmcnt(3)
	v_pk_mul_f32 v[114:115], v[114:115], v[96:97] op_sel_hi:[1,0]
	v_mov_b32_e32 v84, v69
	s_waitcnt lgkmcnt(2)
	v_pk_mul_f32 v[36:37], v[36:37], v[4:5] op_sel_hi:[1,0]
	v_mov_b32_e32 v20, v5
	global_store_short v[0:1], v137, off offset:128
	s_waitcnt lgkmcnt(1)
	v_pk_fma_f32 v[98:99], v[98:99], v[82:83], v[114:115] op_sel_hi:[1,0,1] neg_lo:[0,0,1] neg_hi:[0,0,1]
	v_mov_b32_e32 v137, v100
	v_pk_mul_f32 v[96:97], v[138:139], v[96:97] op_sel_hi:[1,0]
	s_waitcnt lgkmcnt(0)
	v_pk_fma_f32 v[68:69], v[84:85], v[52:53], v[36:37] op_sel_hi:[1,0,1] neg_lo:[0,0,1] neg_hi:[0,0,1]
	v_mov_b32_e32 v100, v117
	v_pk_mul_f32 v[4:5], v[20:21], v[4:5] op_sel_hi:[1,0]
	v_pk_mul_f32 v[114:115], v[98:99], v[98:99]
	v_pk_fma_f32 v[82:83], v[136:137], v[82:83], v[96:97] op_sel_hi:[1,0,1] neg_lo:[0,0,1] neg_hi:[0,0,1]
	v_pk_mul_f32 v[36:37], v[68:69], v[68:69]
	v_pk_fma_f32 v[52:53], v[100:101], v[52:53], v[4:5] op_sel_hi:[1,0,1] neg_lo:[0,0,1] neg_hi:[0,0,1]
	v_pk_mul_f32 v[96:97], v[82:83], v[82:83]
	v_pk_mul_f32 v[4:5], v[52:53], v[52:53]
	v_mov_b32_e32 v20, v36
	v_mov_b32_e32 v21, v114
	v_mov_b32_e32 v114, v37
	v_pk_add_f32 v[20:21], v[20:21], v[114:115]
	v_mov_b32_e32 v36, v5
	v_mov_b32_e32 v37, v97
	v_pk_add_f32 v[20:21], v[36:37], v[20:21]
	v_mov_b32_e32 v5, v96
	v_pk_add_f32 v[4:5], v[4:5], v[20:21]
	ds_bpermute_b32 v21, v48, v5
	ds_bpermute_b32 v20, v48, v4
	v_mul_f32_e32 v37, 0x45800000, v140
	v_cndmask_b32_e32 v37, v140, v37, vcc
	v_mul_f32_e32 v66, v66, v37
	v_mul_f32_e32 v66, v131, v66
	s_waitcnt lgkmcnt(0)
	v_pk_add_f32 v[20:21], v[4:5], v[20:21]
	ds_bpermute_b32 v85, v49, v21
	ds_bpermute_b32 v84, v49, v20
	v_add_u32_e32 v4, v135, v190
	v_mad_i64_i32 v[4:5], s[0:1], v4, s78, v[16:17]
	v_mul_f32_e32 v36, v112, v81
	s_waitcnt lgkmcnt(0)
; DI u16 f2bf(float a) { return (u16)(pk2(a, 0.f) & 0xffffu); }
; DI int crow(int i, int h) { return (i & 3) + 8 * (i >> 2) + 4 * h; }
; __device__ __forceinline__ void attn_item_A(const Params& p, int layer, int head, int q0u, char* lds) {
;     ...
; #pragma unroll
;   for (int e = 0; e < 16; ++e) {
;     const int qq = crow(e, h_e);
;     const float ia = __shfl(iA, qq), ib = __shfl(iB, qq);
;     float ov[4];
;     float ss = 0.f;
; #pragma unroll
;     for (int d = 0; d < 4; ++d) { ov[d] = o1[d][e] * ia - o2[d][e] * ib; ss += ov[d] * ov[d]; }
; #pragma unroll
;     for (int x = 16; x >= 1; x >>= 1) ss += __shfl_xor(ss, x);
;     const float rs = rsqrtf(ss * (1.f / 128.f) + LN_EPS);
;     const size_t rowoff = (size_t)(orow0 + qq) * LDX + ocol + r_e;
; #pragma unroll
;     for (int d = 0; d < 4; ++d) Mx[rowoff + d * 32] = f2bf(ov[d] * rs * sw[d]);
;   }
	v_pk_add_f32 v[20:21], v[20:21], v[84:85]
	ds_bpermute_b32 v85, v64, v21
	ds_bpermute_b32 v84, v64, v20
	v_cvt_pk_bf16_f32 v66, v66, s0
	global_store_short v[4:5], v66, off
	v_mul_f32_e32 v81, v67, v37
	v_mul_f32_e32 v51, v51, v37
	s_waitcnt lgkmcnt(0)
	v_pk_add_f32 v[20:21], v[20:21], v[84:85]
	ds_bpermute_b32 v67, v65, v21
	ds_bpermute_b32 v66, v65, v20
	v_mul_f32_e32 v51, v129, v51
	v_cvt_pk_bf16_f32 v51, v51, s0
	global_store_short v[4:5], v51, off offset:128
	v_mul_f32_e32 v37, v50, v37
	s_waitcnt lgkmcnt(0)
	v_pk_add_f32 v[20:21], v[20:21], v[66:67]
	ds_bpermute_b32 v67, v80, v21
	ds_bpermute_b32 v66, v80, v20
	v_mul_f32_e32 v81, v130, v81
	v_cvt_pk_bf16_f32 v81, v81, s0
	global_store_short v[4:5], v81, off offset:64
	global_store_short v[18:19], v113, off offset:128
	s_waitcnt lgkmcnt(0)
	v_pk_add_f32 v[20:21], v[20:21], v[66:67]
	v_add_u32_e32 v113, 10, v134
	v_pk_fma_f32 v[50:51], v[20:21], s[30:31], v[32:33] op_sel_hi:[1,0,0]
	v_mov_b32_e32 v96, v54
	v_mul_f32_e32 v20, 0x4b800000, v51
	v_cmp_gt_f32_e32 vcc, s81, v51
	v_mov_b32_e32 v97, v38
	v_mov_b32_e32 v100, v6
	v_cndmask_b32_e32 v20, v51, v20, vcc
	v_rsq_f32_e32 v51, v20
	v_add_u32_e32 v20, v141, v190
	v_mad_i64_i32 v[20:21], s[0:1], v20, s78, v[16:17]
	v_mul_f32_e32 v66, 0x45800000, v51
	v_cndmask_b32_e32 v81, v51, v66, vcc
	v_mul_f32_e32 v51, v98, v81
	v_mul_f32_e32 v51, v131, v51
	v_cvt_pk_bf16_f32 v51, v51, s0
	global_store_short v[20:21], v51, off
	v_mul_f32_e32 v51, v99, v81
	v_mul_f32_e32 v51, v130, v51
	v_cvt_pk_bf16_f32 v51, v51, s0
	global_store_short v[20:21], v51, off offset:64
	v_mul_f32_e32 v51, v83, v81
	v_mul_f32_e32 v51, v129, v51
	v_cvt_pk_bf16_f32 v83, v51, s0
	v_mul_f32_e32 v51, 0x4b800000, v50
	v_cmp_gt_f32_e32 vcc, s81, v50
	v_mov_b32_e32 v101, v22
	v_mov_b32_e32 v84, v70
	v_cndmask_b32_e32 v50, v50, v51, vcc
	v_rsq_f32_e32 v112, v50
	v_and_or_b32 v50, v113, 62, v186
	v_lshlrev_b32_e32 v51, 2, v50
	ds_bpermute_b32 v66, v51, v132
	ds_bpermute_b32 v50, v51, v133
	v_mov_b32_e32 v85, v86
	v_mov_b32_e32 v98, v118
	v_mov_b32_e32 v99, v102
	s_waitcnt lgkmcnt(1)
	v_pk_mul_f32 v[96:97], v[96:97], v[66:67] op_sel_hi:[1,0]
	v_pk_mul_f32 v[66:67], v[100:101], v[66:67] op_sel_hi:[1,0]
	s_waitcnt lgkmcnt(0)
	v_pk_fma_f32 v[84:85], v[84:85], v[50:51], v[96:97] op_sel_hi:[1,0,1] neg_lo:[0,0,1] neg_hi:[0,0,1]
	v_pk_fma_f32 v[50:51], v[98:99], v[50:51], v[66:67] op_sel_hi:[1,0,1] neg_lo:[0,0,1] neg_hi:[0,0,1]
	v_add_u32_e32 v98, 11, v134
	v_and_or_b32 v6, v98, 63, v186
	v_lshlrev_b32_e32 v22, 2, v6
	ds_bpermute_b32 v6, v22, v132
	ds_bpermute_b32 v54, v22, v133
	v_mov_b32_e32 v38, v55
	v_mov_b32_e32 v86, v71
	v_mov_b32_e32 v22, v7
	s_waitcnt lgkmcnt(1)
	v_pk_mul_f32 v[38:39], v[38:39], v[6:7] op_sel_hi:[1,0]
	v_mov_b32_e32 v102, v119
	s_waitcnt lgkmcnt(0)
	v_pk_fma_f32 v[70:71], v[86:87], v[54:55], v[38:39] op_sel_hi:[1,0,1] neg_lo:[0,0,1] neg_hi:[0,0,1]
	v_pk_mul_f32 v[6:7], v[22:23], v[6:7] op_sel_hi:[1,0]
	v_pk_mul_f32 v[96:97], v[84:85], v[84:85]
	v_pk_mul_f32 v[38:39], v[70:71], v[70:71]
	v_pk_fma_f32 v[54:55], v[102:103], v[54:55], v[6:7] op_sel_hi:[1,0,1] neg_lo:[0,0,1] neg_hi:[0,0,1]
	v_pk_mul_f32 v[66:67], v[50:51], v[50:51]
	v_pk_mul_f32 v[6:7], v[54:55], v[54:55]
	v_mov_b32_e32 v22, v38
	v_mov_b32_e32 v23, v96
	v_mov_b32_e32 v96, v39
	v_pk_add_f32 v[22:23], v[22:23], v[96:97]
	v_mov_b32_e32 v38, v7
	v_mov_b32_e32 v39, v67
	v_pk_add_f32 v[22:23], v[38:39], v[22:23]
	v_mov_b32_e32 v7, v66
	v_pk_add_f32 v[6:7], v[6:7], v[22:23]
	ds_bpermute_b32 v23, v48, v7
	ds_bpermute_b32 v22, v48, v6
	v_mul_f32_e32 v39, 0x45800000, v112
	v_cndmask_b32_e32 v39, v112, v39, vcc
	v_mul_f32_e32 v68, v68, v39
	v_mul_f32_e32 v53, v53, v39
	s_waitcnt lgkmcnt(0)
	v_pk_add_f32 v[22:23], v[6:7], v[22:23]
	ds_bpermute_b32 v67, v49, v23
	ds_bpermute_b32 v66, v49, v22
	v_add_u32_e32 v6, v116, v190
	v_mad_i64_i32 v[6:7], s[0:1], v6, s78, v[16:17]
	v_mul_f32_e32 v68, v131, v68
	s_waitcnt lgkmcnt(0)
	v_pk_add_f32 v[22:23], v[22:23], v[66:67]
	ds_bpermute_b32 v67, v64, v23
	ds_bpermute_b32 v66, v64, v22
	v_mul_f32_e32 v53, v129, v53
	v_cvt_pk_bf16_f32 v68, v68, s0
	v_cvt_pk_bf16_f32 v53, v53, s0
	global_store_short v[6:7], v68, off
	s_waitcnt lgkmcnt(0)
	v_pk_add_f32 v[22:23], v[22:23], v[66:67]
	ds_bpermute_b32 v67, v65, v23
	ds_bpermute_b32 v66, v65, v22
	v_mul_f32_e32 v68, v69, v39
	global_store_short v[6:7], v53, off offset:128
	v_mul_f32_e32 v39, v52, v39
	v_mul_f32_e32 v38, v82, v81
	s_waitcnt lgkmcnt(0)
	v_pk_add_f32 v[22:23], v[22:23], v[66:67]
	ds_bpermute_b32 v67, v80, v23
	ds_bpermute_b32 v66, v80, v22
	v_mul_f32_e32 v68, v130, v68
	v_cvt_pk_bf16_f32 v68, v68, s0
	v_add_u32_e32 v97, 16, v134
	global_store_short v[20:21], v83, off offset:128
	s_waitcnt lgkmcnt(0)
	v_pk_add_f32 v[22:23], v[22:23], v[66:67]
	v_mov_b32_e32 v82, v56
	v_pk_fma_f32 v[52:53], v[22:23], s[30:31], v[32:33] op_sel_hi:[1,0,0]
	v_mov_b32_e32 v83, v40
	v_mul_f32_e32 v22, 0x4b800000, v53
	v_cmp_gt_f32_e32 vcc, s81, v53
	v_mov_b32_e32 v86, v8
	v_mov_b32_e32 v87, v24
	v_cndmask_b32_e32 v22, v53, v22, vcc
	v_rsq_f32_e32 v53, v22
	v_add_u32_e32 v22, v113, v190
	v_mad_i64_i32 v[22:23], s[0:1], v22, s78, v[16:17]
	v_mul_f32_e32 v66, 0x45800000, v53
	v_cndmask_b32_e32 v81, v53, v66, vcc
	v_mul_f32_e32 v53, v84, v81
	v_mul_f32_e32 v53, v131, v53
	v_cvt_pk_bf16_f32 v53, v53, s0
	global_store_short v[22:23], v53, off
	v_mul_f32_e32 v53, v85, v81
	v_mul_f32_e32 v53, v130, v53
	v_cvt_pk_bf16_f32 v53, v53, s0
	global_store_short v[22:23], v53, off offset:64
	v_mul_f32_e32 v53, 0x4b800000, v52
	v_cmp_gt_f32_e32 vcc, s81, v52
	global_store_short v[6:7], v68, off offset:64
	v_mov_b32_e32 v68, v72
	v_cndmask_b32_e32 v52, v52, v53, vcc
	v_rsq_f32_e32 v96, v52
	v_and_or_b32 v52, v97, 60, v186
	v_lshlrev_b32_e32 v53, 2, v52
	ds_bpermute_b32 v66, v53, v132
	ds_bpermute_b32 v52, v53, v133
	v_mov_b32_e32 v69, v88
	v_mov_b32_e32 v84, v120
	v_mov_b32_e32 v85, v104
	s_waitcnt lgkmcnt(1)
; DI u16 f2bf(float a) { return (u16)(pk2(a, 0.f) & 0xffffu); }
; DI int crow(int i, int h) { return (i & 3) + 8 * (i >> 2) + 4 * h; }
; __device__ __forceinline__ void attn_item_A(const Params& p, int layer, int head, int q0u, char* lds) {
;     ...
; #pragma unroll
;   for (int e = 0; e < 16; ++e) {
;     const int qq = crow(e, h_e);
;     const float ia = __shfl(iA, qq), ib = __shfl(iB, qq);
;     float ov[4];
;     float ss = 0.f;
; #pragma unroll
;     for (int d = 0; d < 4; ++d) { ov[d] = o1[d][e] * ia - o2[d][e] * ib; ss += ov[d] * ov[d]; }
; #pragma unroll
;     for (int x = 16; x >= 1; x >>= 1) ss += __shfl_xor(ss, x);
;     const float rs = rsqrtf(ss * (1.f / 128.f) + LN_EPS);
;     const size_t rowoff = (size_t)(orow0 + qq) * LDX + ocol + r_e;
; #pragma unroll
;     for (int d = 0; d < 4; ++d) Mx[rowoff + d * 32] = f2bf(ov[d] * rs * sw[d]);
;   }
	v_pk_mul_f32 v[82:83], v[82:83], v[66:67] op_sel_hi:[1,0]
	v_pk_mul_f32 v[66:67], v[86:87], v[66:67] op_sel_hi:[1,0]
	s_waitcnt lgkmcnt(0)
	v_pk_fma_f32 v[68:69], v[68:69], v[52:53], v[82:83] op_sel_hi:[1,0,1] neg_lo:[0,0,1] neg_hi:[0,0,1]
	v_pk_fma_f32 v[52:53], v[84:85], v[52:53], v[66:67] op_sel_hi:[1,0,1] neg_lo:[0,0,1] neg_hi:[0,0,1]
	v_add_u32_e32 v84, 17, v134
	v_and_or_b32 v8, v84, 61, v186
	v_lshlrev_b32_e32 v24, 2, v8
	ds_bpermute_b32 v8, v24, v132
	ds_bpermute_b32 v56, v24, v133
	v_mov_b32_e32 v40, v57
	v_mov_b32_e32 v88, v73
	v_mov_b32_e32 v24, v9
	s_waitcnt lgkmcnt(1)
	v_pk_mul_f32 v[40:41], v[40:41], v[8:9] op_sel_hi:[1,0]
	v_mov_b32_e32 v104, v121
	s_waitcnt lgkmcnt(0)
	v_pk_fma_f32 v[72:73], v[88:89], v[56:57], v[40:41] op_sel_hi:[1,0,1] neg_lo:[0,0,1] neg_hi:[0,0,1]
	v_pk_mul_f32 v[8:9], v[24:25], v[8:9] op_sel_hi:[1,0]
	v_pk_mul_f32 v[82:83], v[68:69], v[68:69]
	v_pk_mul_f32 v[40:41], v[72:73], v[72:73]
	v_pk_fma_f32 v[56:57], v[104:105], v[56:57], v[8:9] op_sel_hi:[1,0,1] neg_lo:[0,0,1] neg_hi:[0,0,1]
	v_pk_mul_f32 v[66:67], v[52:53], v[52:53]
	v_pk_mul_f32 v[8:9], v[56:57], v[56:57]
	v_mov_b32_e32 v24, v40
	v_mov_b32_e32 v25, v82
	v_mov_b32_e32 v82, v41
	v_pk_add_f32 v[24:25], v[24:25], v[82:83]
	v_mov_b32_e32 v40, v9
	v_mov_b32_e32 v41, v67
	v_pk_add_f32 v[24:25], v[40:41], v[24:25]
	v_mov_b32_e32 v9, v66
	v_pk_add_f32 v[8:9], v[8:9], v[24:25]
	ds_bpermute_b32 v25, v48, v9
	ds_bpermute_b32 v24, v48, v8
	v_mul_f32_e32 v51, v51, v81
	v_mul_f32_e32 v51, v129, v51
	v_cvt_pk_bf16_f32 v51, v51, s0
	global_store_short v[22:23], v51, off offset:128
	s_waitcnt lgkmcnt(0)
	v_pk_add_f32 v[24:25], v[8:9], v[24:25]
	v_mul_f32_e32 v40, v50, v81
	ds_bpermute_b32 v51, v49, v25
	ds_bpermute_b32 v50, v49, v24
	v_mul_f32_e32 v41, 0x45800000, v96
	v_cndmask_b32_e32 v41, v96, v41, vcc
	v_add_u32_e32 v8, v98, v190
	v_mul_f32_e32 v66, v70, v41
	s_waitcnt lgkmcnt(0)
	v_pk_add_f32 v[24:25], v[24:25], v[50:51]
	ds_bpermute_b32 v51, v64, v25
	ds_bpermute_b32 v50, v64, v24
	v_mad_i64_i32 v[8:9], s[0:1], v8, s78, v[16:17]
	v_mul_f32_e32 v66, v131, v66
	s_nop 0
	v_cvt_pk_bf16_f32 v66, v66, s0
	s_waitcnt lgkmcnt(0)
	v_pk_add_f32 v[24:25], v[24:25], v[50:51]
	ds_bpermute_b32 v51, v65, v25
	ds_bpermute_b32 v50, v65, v24
	global_store_short v[8:9], v66, off
	v_mul_f32_e32 v66, v71, v41
	v_mul_f32_e32 v55, v55, v41
	v_mul_f32_e32 v41, v54, v41
	s_waitcnt lgkmcnt(0)
	v_pk_add_f32 v[24:25], v[24:25], v[50:51]
	ds_bpermute_b32 v51, v80, v25
	ds_bpermute_b32 v50, v80, v24
	v_mul_f32_e32 v66, v130, v66
	v_mul_f32_e32 v55, v129, v55
	v_cvt_pk_bf16_f32 v66, v66, s0
	v_cvt_pk_bf16_f32 v55, v55, s0
	s_waitcnt lgkmcnt(0)
	v_pk_add_f32 v[24:25], v[24:25], v[50:51]
	v_add_u32_e32 v86, 18, v134
	v_pk_fma_f32 v[50:51], v[24:25], s[30:31], v[32:33] op_sel_hi:[1,0,0]
	global_store_short v[8:9], v66, off offset:64
	v_mul_f32_e32 v24, 0x4b800000, v51
	v_cmp_gt_f32_e32 vcc, s81, v51
	v_mov_b32_e32 v66, v74
	v_add_u32_e32 v74, 19, v134
	v_cndmask_b32_e32 v24, v51, v24, vcc
	v_rsq_f32_e32 v51, v24
	v_add_u32_e32 v24, v97, v190
	v_mad_i64_i32 v[24:25], s[0:1], v24, s78, v[16:17]
	v_mul_f32_e32 v54, 0x45800000, v51
	v_cndmask_b32_e32 v81, v51, v54, vcc
	v_mul_f32_e32 v51, v68, v81
	v_mul_f32_e32 v51, v131, v51
	v_cvt_pk_bf16_f32 v51, v51, s0
	global_store_short v[24:25], v51, off
	v_mul_f32_e32 v51, v69, v81
	v_mul_f32_e32 v51, v130, v51
	v_cvt_pk_bf16_f32 v51, v51, s0
	global_store_short v[24:25], v51, off offset:64
	v_mul_f32_e32 v51, v53, v81
	v_mul_f32_e32 v51, v129, v51
	v_cvt_pk_bf16_f32 v53, v51, s0
	v_mul_f32_e32 v51, 0x4b800000, v50
	v_cmp_gt_f32_e32 vcc, s81, v50
	v_mov_b32_e32 v82, v10
	v_and_or_b32 v10, v74, 63, v186
	v_cndmask_b32_e32 v50, v50, v51, vcc
	v_rsq_f32_e32 v85, v50
	v_and_or_b32 v50, v86, 62, v186
	v_lshlrev_b32_e32 v51, 2, v50
	ds_bpermute_b32 v54, v51, v132
	ds_bpermute_b32 v50, v51, v133
	v_mov_b32_e32 v68, v58
	v_mov_b32_e32 v69, v42
	v_mov_b32_e32 v83, v26
	v_lshlrev_b32_e32 v26, 2, v10
	global_store_short v[8:9], v55, off offset:128
	v_mov_b32_e32 v67, v90
	s_waitcnt lgkmcnt(1)
	v_pk_mul_f32 v[68:69], v[68:69], v[54:55] op_sel_hi:[1,0]
	v_mov_b32_e32 v70, v122
	v_mov_b32_e32 v71, v106
	v_pk_mul_f32 v[54:55], v[82:83], v[54:55] op_sel_hi:[1,0]
	ds_bpermute_b32 v10, v26, v132
	s_waitcnt lgkmcnt(1)
	v_pk_fma_f32 v[66:67], v[66:67], v[50:51], v[68:69] op_sel_hi:[1,0,1] neg_lo:[0,0,1] neg_hi:[0,0,1]
	v_pk_fma_f32 v[50:51], v[70:71], v[50:51], v[54:55] op_sel_hi:[1,0,1] neg_lo:[0,0,1] neg_hi:[0,0,1]
	ds_bpermute_b32 v54, v26, v133
	v_mov_b32_e32 v42, v59
	v_mov_b32_e32 v90, v75
	s_waitcnt lgkmcnt(1)
	v_pk_mul_f32 v[42:43], v[42:43], v[10:11] op_sel_hi:[1,0]
	v_mov_b32_e32 v26, v11
	s_waitcnt lgkmcnt(0)
	v_pk_fma_f32 v[42:43], v[90:91], v[54:55], v[42:43] op_sel_hi:[1,0,1] neg_lo:[0,0,1] neg_hi:[0,0,1]
	v_mov_b32_e32 v106, v123
	v_pk_mul_f32 v[10:11], v[26:27], v[10:11] op_sel_hi:[1,0]
	v_pk_mul_f32 v[68:69], v[66:67], v[66:67]
	v_pk_mul_f32 v[58:59], v[42:43], v[42:43]
	v_pk_fma_f32 v[54:55], v[106:107], v[54:55], v[10:11] op_sel_hi:[1,0,1] neg_lo:[0,0,1] neg_hi:[0,0,1]
	v_pk_mul_f32 v[70:71], v[50:51], v[50:51]
	v_pk_mul_f32 v[10:11], v[54:55], v[54:55]
	v_mov_b32_e32 v26, v58
	v_mov_b32_e32 v27, v68
	v_mov_b32_e32 v68, v59
	v_pk_add_f32 v[26:27], v[26:27], v[68:69]
	v_mov_b32_e32 v58, v11
	v_mov_b32_e32 v59, v71
	v_pk_add_f32 v[26:27], v[58:59], v[26:27]
	v_mov_b32_e32 v11, v70
	v_pk_add_f32 v[10:11], v[10:11], v[26:27]
	ds_bpermute_b32 v27, v48, v11
	ds_bpermute_b32 v26, v48, v10
	v_mul_f32_e32 v75, v52, v81
	v_mul_f32_e32 v52, 0x45800000, v85
	global_store_short v[24:25], v53, off offset:128
	v_cndmask_b32_e32 v58, v85, v52, vcc
	s_waitcnt lgkmcnt(0)
; DI u16 f2bf(float a) { return (u16)(pk2(a, 0.f) & 0xffffu); }
; DI int crow(int i, int h) { return (i & 3) + 8 * (i >> 2) + 4 * h; }
; __device__ __forceinline__ void attn_item_A(const Params& p, int layer, int head, int q0u, char* lds) {
;     ...
; #pragma unroll
;   for (int e = 0; e < 16; ++e) {
;     const int qq = crow(e, h_e);
;     const float ia = __shfl(iA, qq), ib = __shfl(iB, qq);
;     float ov[4];
;     float ss = 0.f;
; #pragma unroll
;     for (int d = 0; d < 4; ++d) { ov[d] = o1[d][e] * ia - o2[d][e] * ib; ss += ov[d] * ov[d]; }
; #pragma unroll
;     for (int x = 16; x >= 1; x >>= 1) ss += __shfl_xor(ss, x);
;     const float rs = rsqrtf(ss * (1.f / 128.f) + LN_EPS);
;     const size_t rowoff = (size_t)(orow0 + qq) * LDX + ocol + r_e;
; #pragma unroll
;     for (int d = 0; d < 4; ++d) Mx[rowoff + d * 32] = f2bf(ov[d] * rs * sw[d]);
;   }
	v_pk_add_f32 v[26:27], v[10:11], v[26:27]
	ds_bpermute_b32 v53, v49, v27
	ds_bpermute_b32 v52, v49, v26
	v_add_u32_e32 v10, v84, v190
	v_mul_f32_e32 v59, v72, v58
	v_mad_i64_i32 v[10:11], s[0:1], v10, s78, v[16:17]
	s_waitcnt lgkmcnt(0)
	v_pk_add_f32 v[26:27], v[26:27], v[52:53]
	ds_bpermute_b32 v53, v64, v27
	ds_bpermute_b32 v52, v64, v26
	v_mul_f32_e32 v59, v131, v59
	v_cvt_pk_bf16_f32 v59, v59, s0
	v_mul_f32_e32 v72, v56, v58
	global_store_short v[10:11], v59, off
	s_waitcnt lgkmcnt(0)
	v_pk_add_f32 v[26:27], v[26:27], v[52:53]
	ds_bpermute_b32 v53, v65, v27
	ds_bpermute_b32 v52, v65, v26
	v_mul_f32_e32 v59, v73, v58
	v_mul_f32_e32 v57, v57, v58
	v_mul_f32_e32 v59, v130, v59
	v_mul_f32_e32 v57, v129, v57
	s_waitcnt lgkmcnt(0)
	v_pk_add_f32 v[26:27], v[26:27], v[52:53]
	ds_bpermute_b32 v53, v80, v27
	ds_bpermute_b32 v52, v80, v26
	v_cvt_pk_bf16_f32 v59, v59, s0
	v_cvt_pk_bf16_f32 v57, v57, s0
	v_add_u32_e32 v82, 24, v134
	v_mov_b32_e32 v70, v12
	s_waitcnt lgkmcnt(0)
	v_pk_add_f32 v[26:27], v[26:27], v[52:53]
	v_mov_b32_e32 v71, v28
	v_pk_fma_f32 v[52:53], v[26:27], s[30:31], v[32:33] op_sel_hi:[1,0,0]
	global_store_short v[10:11], v57, off offset:128
	v_mul_f32_e32 v26, 0x4b800000, v53
	v_cmp_gt_f32_e32 vcc, s81, v53
	global_store_short v[10:11], v59, off offset:64
	v_mov_b32_e32 v58, v76
	v_cndmask_b32_e32 v26, v53, v26, vcc
	v_rsq_f32_e32 v53, v26
	v_add_u32_e32 v26, v86, v190
	v_mad_i64_i32 v[26:27], s[0:1], v26, s78, v[16:17]
	v_mul_f32_e32 v56, 0x45800000, v53
	v_cndmask_b32_e32 v73, v53, v56, vcc
	v_mul_f32_e32 v53, v66, v73
	v_mul_f32_e32 v53, v131, v53
	v_cvt_pk_bf16_f32 v53, v53, s0
	global_store_short v[26:27], v53, off
	v_mul_f32_e32 v53, v67, v73
	v_mul_f32_e32 v53, v130, v53
	v_cvt_pk_bf16_f32 v53, v53, s0
	global_store_short v[26:27], v53, off offset:64
	v_mul_f32_e32 v53, 0x4b800000, v52
	v_cmp_gt_f32_e32 vcc, s81, v52
	v_mov_b32_e32 v66, v60
	v_mov_b32_e32 v67, v44
	v_cndmask_b32_e32 v52, v52, v53, vcc
	v_rsq_f32_e32 v81, v52
	v_and_or_b32 v52, v82, 60, v186
	v_lshlrev_b32_e32 v53, 2, v52
	ds_bpermute_b32 v56, v53, v132
	ds_bpermute_b32 v52, v53, v133
	v_mov_b32_e32 v59, v92
	v_mov_b32_e32 v68, v124
	v_mov_b32_e32 v69, v108
	s_waitcnt lgkmcnt(1)
	v_pk_mul_f32 v[66:67], v[66:67], v[56:57] op_sel_hi:[1,0]
	v_pk_mul_f32 v[56:57], v[70:71], v[56:57] op_sel_hi:[1,0]
	v_add_u32_e32 v70, 25, v134
	v_and_or_b32 v12, v70, 61, v186
	v_lshlrev_b32_e32 v28, 2, v12
	ds_bpermute_b32 v12, v28, v132
	s_waitcnt lgkmcnt(1)
	v_pk_fma_f32 v[58:59], v[58:59], v[52:53], v[66:67] op_sel_hi:[1,0,1] neg_lo:[0,0,1] neg_hi:[0,0,1]
	v_pk_fma_f32 v[52:53], v[68:69], v[52:53], v[56:57] op_sel_hi:[1,0,1] neg_lo:[0,0,1] neg_hi:[0,0,1]
	ds_bpermute_b32 v56, v28, v133
	v_mov_b32_e32 v44, v61
	v_mov_b32_e32 v92, v77
	s_waitcnt lgkmcnt(1)
	v_pk_mul_f32 v[44:45], v[44:45], v[12:13] op_sel_hi:[1,0]
	v_mov_b32_e32 v28, v13
	s_waitcnt lgkmcnt(0)
	v_pk_fma_f32 v[44:45], v[92:93], v[56:57], v[44:45] op_sel_hi:[1,0,1] neg_lo:[0,0,1] neg_hi:[0,0,1]
	v_mov_b32_e32 v108, v125
	v_pk_mul_f32 v[12:13], v[28:29], v[12:13] op_sel_hi:[1,0]
	v_pk_mul_f32 v[66:67], v[58:59], v[58:59]
	v_pk_mul_f32 v[60:61], v[44:45], v[44:45]
	v_pk_fma_f32 v[28:29], v[108:109], v[56:57], v[12:13] op_sel_hi:[1,0,1] neg_lo:[0,0,1] neg_hi:[0,0,1]
	v_pk_mul_f32 v[68:69], v[52:53], v[52:53]
	v_pk_mul_f32 v[12:13], v[28:29], v[28:29]
	v_mov_b32_e32 v56, v60
	v_mov_b32_e32 v57, v66
	v_mov_b32_e32 v66, v61
	v_pk_add_f32 v[56:57], v[56:57], v[66:67]
	v_mov_b32_e32 v60, v13
	v_mov_b32_e32 v61, v69
	v_pk_add_f32 v[56:57], v[60:61], v[56:57]
	v_mov_b32_e32 v13, v68
	v_pk_add_f32 v[12:13], v[12:13], v[56:57]
	ds_bpermute_b32 v57, v48, v13
	ds_bpermute_b32 v56, v48, v12
	v_mul_f32_e32 v51, v51, v73
	v_mul_f32_e32 v51, v129, v51
	v_cvt_pk_bf16_f32 v51, v51, s0
	v_mul_f32_e32 v68, v50, v73
	v_mul_f32_e32 v50, 0x45800000, v81
	global_store_short v[26:27], v51, off offset:128
	v_cndmask_b32_e32 v60, v81, v50, vcc
	s_waitcnt lgkmcnt(0)
	v_pk_add_f32 v[50:51], v[12:13], v[56:57]
	ds_bpermute_b32 v57, v49, v51
	ds_bpermute_b32 v56, v49, v50
	v_add_u32_e32 v12, v74, v190
	v_mul_f32_e32 v42, v42, v60
	v_mad_i64_i32 v[12:13], s[0:1], v12, s78, v[16:17]
	s_waitcnt lgkmcnt(0)
	v_pk_add_f32 v[50:51], v[50:51], v[56:57]
	ds_bpermute_b32 v57, v64, v51
	ds_bpermute_b32 v56, v64, v50
	v_mul_f32_e32 v42, v131, v42
	v_cvt_pk_bf16_f32 v42, v42, s0
	global_store_short v[12:13], v42, off
	v_mul_f32_e32 v61, v43, v60
	s_waitcnt lgkmcnt(0)
	v_pk_add_f32 v[42:43], v[50:51], v[56:57]
	ds_bpermute_b32 v51, v65, v43
	ds_bpermute_b32 v50, v65, v42
	v_mul_f32_e32 v69, v54, v60
	v_mul_f32_e32 v55, v55, v60
	v_mul_f32_e32 v56, v130, v61
	v_mul_f32_e32 v55, v129, v55
	s_waitcnt lgkmcnt(0)
	v_pk_add_f32 v[42:43], v[42:43], v[50:51]
	ds_bpermute_b32 v51, v80, v43
	ds_bpermute_b32 v50, v80, v42
	v_cvt_pk_bf16_f32 v56, v56, s0
	v_cvt_pk_bf16_f32 v55, v55, s0
	v_add_u32_e32 v74, 26, v134
	v_add_u32_e32 v76, 27, v134
	s_waitcnt lgkmcnt(0)
	v_pk_add_f32 v[42:43], v[42:43], v[50:51]
	v_mov_b32_e32 v66, v14
	v_pk_fma_f32 v[42:43], v[42:43], s[30:31], v[32:33] op_sel_hi:[1,0,0]
	v_mov_b32_e32 v67, v30
	v_mul_f32_e32 v50, 0x4b800000, v43
	v_cmp_gt_f32_e32 vcc, s81, v43
	v_and_or_b32 v14, v76, 63, v186
	global_store_short v[12:13], v56, off offset:64
	v_cndmask_b32_e32 v43, v43, v50, vcc
	v_rsq_f32_e32 v43, v43
	v_add_u32_e32 v50, v82, v190
	v_mad_i64_i32 v[50:51], s[0:1], v50, s78, v[16:17]
	v_mul_f32_e32 v54, 0x45800000, v43
	v_cndmask_b32_e32 v71, v43, v54, vcc
	v_mul_f32_e32 v43, v58, v71
	v_mul_f32_e32 v43, v131, v43
	v_cvt_pk_bf16_f32 v43, v43, s0
	global_store_short v[50:51], v43, off
	v_mul_f32_e32 v43, v59, v71
	v_mul_f32_e32 v43, v130, v43
	v_cvt_pk_bf16_f32 v43, v43, s0
	global_store_short v[50:51], v43, off offset:64
	v_mul_f32_e32 v43, v53, v71
	v_mul_f32_e32 v43, v129, v43
	v_cvt_pk_bf16_f32 v53, v43, s0
	v_mul_f32_e32 v43, 0x4b800000, v42
	v_cmp_gt_f32_e32 vcc, s81, v42
	v_mov_b32_e32 v58, v62
	v_mov_b32_e32 v59, v46
	v_cndmask_b32_e32 v42, v42, v43, vcc
	v_rsq_f32_e32 v73, v42
	v_and_or_b32 v42, v74, 62, v186
	v_lshlrev_b32_e32 v43, 2, v42
	ds_bpermute_b32 v54, v43, v132
	ds_bpermute_b32 v42, v43, v133
	global_store_short v[12:13], v55, off offset:128
	v_mov_b32_e32 v56, v78
	v_mov_b32_e32 v57, v94
	s_waitcnt lgkmcnt(1)
; DI u16 f2bf(float a) { return (u16)(pk2(a, 0.f) & 0xffffu); }
; DI int crow(int i, int h) { return (i & 3) + 8 * (i >> 2) + 4 * h; }
; __device__ __forceinline__ void attn_item_A(const Params& p, int layer, int head, int q0u, char* lds) {
;     ...
; #pragma unroll
;   for (int e = 0; e < 16; ++e) {
;     const int qq = crow(e, h_e);
;     const float ia = __shfl(iA, qq), ib = __shfl(iB, qq);
;     float ov[4];
;     float ss = 0.f;
; #pragma unroll
;     for (int d = 0; d < 4; ++d) { ov[d] = o1[d][e] * ia - o2[d][e] * ib; ss += ov[d] * ov[d]; }
; #pragma unroll
;     for (int x = 16; x >= 1; x >>= 1) ss += __shfl_xor(ss, x);
;     const float rs = rsqrtf(ss * (1.f / 128.f) + LN_EPS);
;     const size_t rowoff = (size_t)(orow0 + qq) * LDX + ocol + r_e;
; #pragma unroll
;     for (int d = 0; d < 4; ++d) Mx[rowoff + d * 32] = f2bf(ov[d] * rs * sw[d]);
;   }
	v_pk_mul_f32 v[58:59], v[58:59], v[54:55] op_sel_hi:[1,0]
	v_mov_b32_e32 v60, v126
	v_mov_b32_e32 v61, v110
	v_pk_mul_f32 v[54:55], v[66:67], v[54:55] op_sel_hi:[1,0]
	v_lshlrev_b32_e32 v14, 2, v14
	s_waitcnt lgkmcnt(0)
	v_pk_fma_f32 v[56:57], v[56:57], v[42:43], v[58:59] op_sel_hi:[1,0,1] neg_lo:[0,0,1] neg_hi:[0,0,1]
	v_pk_fma_f32 v[42:43], v[60:61], v[42:43], v[54:55] op_sel_hi:[1,0,1] neg_lo:[0,0,1] neg_hi:[0,0,1]
	ds_bpermute_b32 v55, v14, v132
	ds_bpermute_b32 v54, v14, v133
	v_mov_b32_e32 v46, v63
	v_mov_b32_e32 v94, v79
	v_pk_mul_f32 v[58:59], v[56:57], v[56:57]
	s_waitcnt lgkmcnt(1)
	v_mov_b32_e32 v14, v55
	v_pk_mul_f32 v[46:47], v[46:47], v[14:15] op_sel_hi:[1,0]
	v_mov_b32_e32 v14, v127
	s_waitcnt lgkmcnt(0)
	v_pk_mul_f32 v[14:15], v[14:15], v[54:55]
	v_pk_fma_f32 v[46:47], v[94:95], v[54:55], v[46:47] op_sel_hi:[1,0,1] neg_lo:[0,0,1] neg_hi:[0,0,1]
	v_mul_f32_e32 v67, v111, v54
	v_mul_f32_e32 v31, v31, v55
	v_mov_b32_e32 v66, v14
	v_mov_b32_e32 v30, v15
	v_pk_mul_f32 v[62:63], v[46:47], v[46:47]
	v_pk_add_f32 v[14:15], v[66:67], v[30:31] neg_lo:[0,1] neg_hi:[0,1]
	v_pk_mul_f32 v[60:61], v[42:43], v[42:43]
	v_pk_mul_f32 v[30:31], v[14:15], v[14:15]
	v_mov_b32_e32 v54, v62
	v_mov_b32_e32 v55, v58
	v_mov_b32_e32 v58, v63
	v_pk_add_f32 v[54:55], v[54:55], v[58:59]
	v_mov_b32_e32 v58, v31
	v_mov_b32_e32 v59, v61
	v_pk_add_f32 v[54:55], v[58:59], v[54:55]
	v_mov_b32_e32 v31, v60
	v_pk_add_f32 v[30:31], v[30:31], v[54:55]
	ds_bpermute_b32 v55, v48, v31
	ds_bpermute_b32 v54, v48, v30
	global_store_short v[50:51], v53, off offset:128
	v_mul_f32_e32 v58, v52, v71
	v_mul_f32_e32 v48, 0x45800000, v73
	v_cndmask_b32_e32 v59, v73, v48, vcc
	s_waitcnt lgkmcnt(0)
	v_pk_add_f32 v[30:31], v[30:31], v[54:55]
	ds_bpermute_b32 v53, v49, v31
	ds_bpermute_b32 v52, v49, v30
	v_add_u32_e32 v48, v70, v190
	v_mul_f32_e32 v44, v44, v59
	v_mad_i64_i32 v[48:49], s[0:1], v48, s78, v[16:17]
	s_waitcnt lgkmcnt(0)
	v_pk_add_f32 v[30:31], v[30:31], v[52:53]
	ds_bpermute_b32 v53, v64, v31
	ds_bpermute_b32 v52, v64, v30
	v_mul_f32_e32 v44, v131, v44
	v_cvt_pk_bf16_f32 v44, v44, s0
	global_store_short v[48:49], v44, off
	v_mul_f32_e32 v54, v45, v59
	s_waitcnt lgkmcnt(0)
	v_pk_add_f32 v[30:31], v[30:31], v[52:53]
	ds_bpermute_b32 v45, v65, v31
	ds_bpermute_b32 v44, v65, v30
	v_mul_f32_e32 v29, v29, v59
	v_mul_f32_e32 v52, v130, v54
	v_mul_f32_e32 v29, v129, v29
	v_cvt_pk_bf16_f32 v52, v52, s0
	s_waitcnt lgkmcnt(0)
	v_pk_add_f32 v[30:31], v[30:31], v[44:45]
	ds_bpermute_b32 v45, v80, v31
	ds_bpermute_b32 v44, v80, v30
	v_cvt_pk_bf16_f32 v29, v29, s0
	global_store_short v[48:49], v52, off offset:64
	global_store_short v[48:49], v29, off offset:128
	v_mul_f32_e32 v52, v28, v59
	s_waitcnt lgkmcnt(0)
	v_pk_add_f32 v[28:29], v[30:31], v[44:45]
	s_nop 0
	v_pk_fma_f32 v[28:29], v[28:29], s[30:31], v[32:33] op_sel_hi:[1,0,0]
	s_nop 0
	v_mul_f32_e32 v30, 0x4b800000, v29
	v_cmp_gt_f32_e32 vcc, s81, v29
	v_mul_f32_e32 v33, 0x4b800000, v28
	s_nop 0
	v_cndmask_b32_e32 v29, v29, v30, vcc
	v_rsq_f32_e32 v29, v29
	v_add_u32_e32 v30, v74, v190
	v_mad_i64_i32 v[30:31], s[0:1], v30, s78, v[16:17]
	v_mul_f32_e32 v32, 0x45800000, v29
	v_cndmask_b32_e32 v29, v29, v32, vcc
	v_mul_f32_e32 v32, v56, v29
	v_mul_f32_e32 v32, v131, v32
	v_cvt_pk_bf16_f32 v32, v32, s0
	global_store_short v[30:31], v32, off
	v_mul_f32_e32 v32, v57, v29
	v_cmp_gt_f32_e32 vcc, s81, v28
	v_mul_f32_e32 v32, v130, v32
	v_cvt_pk_bf16_f32 v32, v32, s0
	v_cndmask_b32_e32 v28, v28, v33, vcc
	v_rsq_f32_e32 v28, v28
	global_store_short v[30:31], v32, off offset:64
	v_mul_f32_e32 v32, v43, v29
	v_mul_f32_e32 v32, v129, v32
	v_cvt_pk_bf16_f32 v32, v32, s0
	global_store_short v[30:31], v32, off offset:128
	v_mul_f32_e32 v32, 0x45800000, v28
	v_cndmask_b32_e32 v167, v28, v32, vcc
	v_add_u32_e32 v28, v76, v190
	v_mad_i64_i32 v[16:17], s[0:1], v28, s78, v[16:17]
	v_mul_f32_e32 v28, v46, v167
	v_mul_f32_e32 v28, v131, v28
	v_cvt_pk_bf16_f32 v28, v28, s0
	v_mul_f32_e32 v15, v15, v167
	global_store_short v[16:17], v28, off
	v_mul_f32_e32 v28, v47, v167
	v_mul_f32_e32 v15, v129, v15
	v_mul_f32_e32 v28, v130, v28
	v_cvt_pk_bf16_f32 v15, v15, s0
	v_mov_b32_e32 v129, v14
	v_cvt_pk_bf16_f32 v28, v28, s0
	global_store_short v[16:17], v15, off offset:128
	s_waitcnt vmcnt(47)
	v_pk_mul_f32 v[14:15], v[128:129], v[166:167]
	global_store_short v[16:17], v28, off offset:64
	v_mul_f32_e32 v28, v14, v34
	v_cvt_pk_bf16_f32 v28, v28, s0
	global_store_short v[0:1], v28, off offset:192
	v_mul_f32_e32 v0, v14, v35
	v_cvt_pk_bf16_f32 v0, v0, s0
	global_store_short v[2:3], v0, off offset:192
	v_mul_f32_e32 v0, v14, v36
	v_cvt_pk_bf16_f32 v0, v0, s0
	global_store_short v[18:19], v0, off offset:192
	v_mul_f32_e32 v0, v14, v37
	v_cvt_pk_bf16_f32 v0, v0, s0
	global_store_short v[4:5], v0, off offset:192
	v_mul_f32_e32 v0, v14, v38
	v_cvt_pk_bf16_f32 v0, v0, s0
	global_store_short v[20:21], v0, off offset:192
	v_mul_f32_e32 v0, v14, v39
	v_cvt_pk_bf16_f32 v0, v0, s0
	global_store_short v[6:7], v0, off offset:192
	v_mul_f32_e32 v0, v14, v40
	v_cvt_pk_bf16_f32 v0, v0, s0
	global_store_short v[22:23], v0, off offset:192
	v_mul_f32_e32 v0, v14, v41
	v_cvt_pk_bf16_f32 v0, v0, s0
	global_store_short v[8:9], v0, off offset:192
	v_mul_f32_e32 v0, v14, v75
	v_cvt_pk_bf16_f32 v0, v0, s0
	global_store_short v[24:25], v0, off offset:192
	v_mul_f32_e32 v0, v14, v72
	v_cvt_pk_bf16_f32 v0, v0, s0
	global_store_short v[10:11], v0, off offset:192
	v_mul_f32_e32 v0, v14, v68
	v_cvt_pk_bf16_f32 v0, v0, s0
	global_store_short v[26:27], v0, off offset:192
	v_mul_f32_e32 v0, v14, v69
	v_cvt_pk_bf16_f32 v0, v0, s0
	global_store_short v[12:13], v0, off offset:192
	v_mul_f32_e32 v0, v14, v58
	v_cvt_pk_bf16_f32 v0, v0, s0
	global_store_short v[50:51], v0, off offset:192
	v_mul_f32_e32 v0, v14, v52
	v_mul_f32_e32 v29, v42, v29
	v_cvt_pk_bf16_f32 v0, v0, s0
	global_store_short v[48:49], v0, off offset:192
	v_mul_f32_e32 v0, v14, v29
	v_cvt_pk_bf16_f32 v0, v0, s0
	global_store_short v[30:31], v0, off offset:192
	v_mul_f32_e32 v0, v14, v15
	s_branch .LBB0_2240
